# scan inner two-step loop re-scheduled with register renaming (same arithmetic order); DMA issues spread across the K-loop; residual epilogues load 16-deep
# speedup vs baseline: 1.0125x; 1.0125x over previous
; #define MFMA16(a, b, c) __builtin_amdgcn_mfma_f32_16x16x32_bf16((a), (b), (c), 0, 0, 0)
; DI void glds16(const void* g, unsigned char* l) { __builtin_amdgcn_global_load_lds((const unsigned*)g, (lds_u32*)l, 16, 0, 0); }
; template <int N> DI void wait_vm() { asm volatile("s_waitcnt vmcnt(%0)" :: "n"(N) : "memory"); }
;     ...
;   for (int kt = 0; kt < nk; ++kt) {
;     wait_vm<0>();
;     __builtin_amdgcn_s_barrier();
;     if (kt + 1 < nk) {
;       unsigned char* sn = smem + ((kt + 1) & 1) * STG;
;       const int ko = (kt + 1) * 64;
; #pragma unroll
;       for (int i = 0; i < NA; ++i) glds16(Ab + ((size_t)i * 128 * lda + ko * 2) + voA, sn + (i * 512 + tid) * 16);
; #pragma unroll
;       for (int i = 0; i < NB; ++i) glds16(Bb + ((size_t)i * 128 * ldb + ko * 2) + voB, sn + AB + (i * 512 + tid) * 16);
;     } else if (nA) {
;       const unsigned nvoA = (unsigned)(srow * nlda + kch * 8) * 2u, nvoB = (unsigned)(srow * nldb + kch * 8) * 2u;
; #pragma unroll
;       for (int i = 0; i < NA; ++i) glds16((const char*)nA + (size_t)i * 128 * nlda + nvoA, smem + (i * 512 + tid) * 16);
; #pragma unroll
;       for (int i = 0; i < NB; ++i) glds16((const char*)nB + (size_t)i * 128 * nldb + nvoB, smem + AB + (i * 512 + tid) * 16);
;     }
;     const unsigned stb = lds_base + (kt & 1) * STG;
; #pragma unroll
;     for (int ks = 0; ks < 2; ++ks) {
;       const unsigned co = ((ks * 4 + fq) ^ sw) * 16;
;       const unsigned sa = stb + a_row + co, sb = stb + b_row + co;
;       bf16x8 af[4], bfr[NT];
; #pragma unroll
;       for (int n = 0; n < NT; ++n) asm volatile("ds_read_b128 %0, %1 offset:%2" : "=v"(bfr[n]) : "v"(sb), "n"(n * 2048) : "memory");
; #pragma unroll
;       for (int mg = 0; mg < MT / 4; ++mg) {
; #pragma unroll
;         for (int m = 0; m < 4; ++m) asm volatile("ds_read_b128 %0, %1 offset:%2" : "=v"(af[m]) : "v"(sa), "n"((mg * 4 + m) * 2048) : "memory");
;         if (mg == 0) {
; #pragma unroll
;           for (int n = 0; n < NT; ++n) asm volatile("s_waitcnt lgkmcnt(%1)" : "+v"(bfr[n]) : "n"(4 + NT - 1 - n) : "memory");
;         }
; #pragma unroll
;         for (int m = 0; m < 4; ++m) {
;           asm volatile("s_waitcnt lgkmcnt(%1)" : "+v"(af[m]) : "n"(3 - m) : "memory");
; #pragma unroll
;           for (int n = 0; n < NT; ++n) acc[mg * 4 + m][n] = MFMA16(bfr[n], af[m], acc[mg * 4 + m][n]);
;         }
;       }
;     }
.LBB0_134:
	s_add_i32 s2, s13, 0x10000
	s_and_b32 s14, s2, 0x10000
	v_add_u32_e32 v143, s14, v139
	v_lshl_add_u64 v[144:145], v[134:135], 0, s[46:47]
	v_readfirstlane_b32 s14, v143
	v_add_u32_e32 v148, 0x2000, v143
	v_lshl_add_u64 v[146:147], v[144:145], 0, s[58:59]
	s_mov_b32 m0, s14
	v_readfirstlane_b32 s14, v148
	v_add_u32_e32 v148, 0x4000, v143
	s_waitcnt vmcnt(0)
	s_waitcnt lgkmcnt(0)
	s_barrier
	s_and_b32 s13, s13, 0x10000
	v_add_u32_e32 v240, s13, v142
	v_add_u32_e32 v236, v240, v140
	v_add_u32_e32 v237, v240, v138
	v_add_u32_e32 v240, s13, v141
	v_add_u32_e32 v238, v240, v140
	v_add_u32_e32 v239, v240, v138
	v_mfma_f32_16x16x32_bf16 v[60:63], v[188:191], v[204:207], v[60:63]
	ds_read_b128 v[152:155], v236 offset:0
	ds_read_b128 v[156:159], v236 offset:2048
	v_mfma_f32_16x16x32_bf16 v[56:59], v[192:195], v[204:207], v[56:59]
	ds_read_b128 v[160:163], v236 offset:4096
	ds_read_b128 v[164:167], v236 offset:6144
	global_load_lds_dwordx4 v[146:147], off
	v_mfma_f32_16x16x32_bf16 v[52:55], v[196:199], v[204:207], v[52:55]
	ds_read_b128 v[168:171], v238 offset:0
	ds_read_b128 v[172:175], v238 offset:2048
	v_mfma_f32_16x16x32_bf16 v[48:51], v[200:203], v[204:207], v[48:51]
	ds_read_b128 v[180:183], v238 offset:4096
	ds_read_b128 v[184:187], v238 offset:6144
	v_mfma_f32_16x16x32_bf16 v[44:47], v[188:191], v[208:211], v[44:47]
	v_mfma_f32_16x16x32_bf16 v[40:43], v[192:195], v[208:211], v[40:43]
	v_mfma_f32_16x16x32_bf16 v[36:39], v[196:199], v[208:211], v[36:39]
	v_lshl_add_u64 v[146:147], v[144:145], 0, s[60:61]
	s_mov_b32 m0, s14
	v_readfirstlane_b32 s14, v148
	global_load_lds_dwordx4 v[146:147], off
	v_mfma_f32_16x16x32_bf16 v[32:35], v[200:203], v[208:211], v[32:35]
	v_mfma_f32_16x16x32_bf16 v[28:31], v[188:191], v[228:231], v[28:31]
	v_mfma_f32_16x16x32_bf16 v[24:27], v[192:195], v[228:231], v[24:27]
	v_mfma_f32_16x16x32_bf16 v[20:23], v[196:199], v[228:231], v[20:23]
	v_mfma_f32_16x16x32_bf16 v[16:19], v[200:203], v[228:231], v[16:19]
	v_lshl_add_u64 v[146:147], v[144:145], 0, s[62:63]
	s_mov_b32 m0, s14
	v_lshl_add_u64 v[144:145], v[144:145], 0, s[64:65]
	global_load_lds_dwordx4 v[146:147], off
	v_mfma_f32_16x16x32_bf16 v[12:15], v[188:191], v[232:235], v[12:15]
	v_mfma_f32_16x16x32_bf16 v[8:11], v[192:195], v[232:235], v[8:11]
	v_mfma_f32_16x16x32_bf16 v[4:7], v[196:199], v[232:235], v[4:7]
	v_mfma_f32_16x16x32_bf16 v[0:3], v[200:203], v[232:235], v[0:3]
	s_waitcnt lgkmcnt(3)
	v_mfma_f32_16x16x32_bf16 v[124:127], v[152:155], v[168:171], v[124:127]
	v_add_u32_e32 v146, 0x6000, v143
	v_add_u32_e32 v148, 0x8000, v143
	v_readfirstlane_b32 s14, v146
	s_mov_b32 m0, s14
	v_readfirstlane_b32 s14, v148
	global_load_lds_dwordx4 v[144:145], off
	v_mfma_f32_16x16x32_bf16 v[120:123], v[156:159], v[168:171], v[120:123]
	ds_read_b128 v[204:207], v238 offset:8192
	v_mfma_f32_16x16x32_bf16 v[116:119], v[160:163], v[168:171], v[116:119]
	v_mfma_f32_16x16x32_bf16 v[112:115], v[164:167], v[168:171], v[112:115]
	ds_read_b128 v[208:211], v238 offset:10240
	s_waitcnt lgkmcnt(4)
	v_mfma_f32_16x16x32_bf16 v[108:111], v[152:155], v[172:175], v[108:111]
	v_mfma_f32_16x16x32_bf16 v[104:107], v[156:159], v[172:175], v[104:107]
	ds_read_b128 v[228:231], v238 offset:12288
	v_lshl_add_u64 v[144:145], v[136:137], 0, s[46:47]
	v_lshl_add_u64 v[146:147], v[144:145], 0, s[16:17]
	s_mov_b32 m0, s14
	s_mov_b64 s[14:15], 0x28080
	v_add_u32_e32 v148, 0xa000, v143
	global_load_lds_dwordx4 v[146:147], off
	v_mfma_f32_16x16x32_bf16 v[100:103], v[160:163], v[172:175], v[100:103]
	v_mfma_f32_16x16x32_bf16 v[96:99], v[164:167], v[172:175], v[96:99]
	ds_read_b128 v[232:235], v238 offset:14336
	s_waitcnt lgkmcnt(5)
	v_mfma_f32_16x16x32_bf16 v[92:95], v[152:155], v[180:183], v[92:95]
	v_mfma_f32_16x16x32_bf16 v[88:91], v[156:159], v[180:183], v[88:91]
	ds_read_b128 v[188:191], v237 offset:0
	v_mfma_f32_16x16x32_bf16 v[84:87], v[160:163], v[180:183], v[84:87]
	v_lshl_add_u64 v[146:147], v[144:145], 0, s[14:15]
	v_readfirstlane_b32 s14, v148
	s_mov_b32 m0, s14
	s_mov_b64 s[14:15], 0x48080
	v_add_u32_e32 v148, 0xc000, v143
	global_load_lds_dwordx4 v[146:147], off
	v_mfma_f32_16x16x32_bf16 v[80:83], v[164:167], v[180:183], v[80:83]
	ds_read_b128 v[192:195], v237 offset:2048
	s_waitcnt lgkmcnt(6)
	v_mfma_f32_16x16x32_bf16 v[76:79], v[152:155], v[184:187], v[76:79]
	v_mfma_f32_16x16x32_bf16 v[72:75], v[156:159], v[184:187], v[72:75]
	ds_read_b128 v[196:199], v237 offset:4096
	v_mfma_f32_16x16x32_bf16 v[68:71], v[160:163], v[184:187], v[68:71]
	v_mfma_f32_16x16x32_bf16 v[64:67], v[164:167], v[184:187], v[64:67]
	ds_read_b128 v[200:203], v237 offset:6144
	v_lshl_add_u64 v[146:147], v[144:145], 0, s[14:15]
	v_readfirstlane_b32 s14, v148
	s_mov_b32 m0, s14
	s_mov_b64 s[14:15], 0x68080
	v_add_u32_e32 v143, 0xe000, v143
	v_lshl_add_u64 v[144:145], v[144:145], 0, s[14:15]
	v_readfirstlane_b32 s14, v143
	global_load_lds_dwordx4 v[146:147], off
	s_waitcnt lgkmcnt(7)
	v_mfma_f32_16x16x32_bf16 v[60:63], v[152:155], v[204:207], v[60:63]
	v_mfma_f32_16x16x32_bf16 v[56:59], v[156:159], v[204:207], v[56:59]
	ds_read_b128 v[168:171], v239 offset:0
	v_mfma_f32_16x16x32_bf16 v[52:55], v[160:163], v[204:207], v[52:55]
	v_mfma_f32_16x16x32_bf16 v[48:51], v[164:167], v[204:207], v[48:51]
	ds_read_b128 v[172:175], v239 offset:2048
	s_waitcnt lgkmcnt(8)
; #define MFMA16(a, b, c) __builtin_amdgcn_mfma_f32_16x16x32_bf16((a), (b), (c), 0, 0, 0)
; DI void glds16(const void* g, unsigned char* l) { __builtin_amdgcn_global_load_lds((const unsigned*)g, (lds_u32*)l, 16, 0, 0); }
; template <int N> DI void wait_vm() { asm volatile("s_waitcnt vmcnt(%0)" :: "n"(N) : "memory"); }
;     ...
;   for (int kt = 0; kt < nk; ++kt) {
;     wait_vm<0>();
;     __builtin_amdgcn_s_barrier();
;     if (kt + 1 < nk) {
;       unsigned char* sn = smem + ((kt + 1) & 1) * STG;
;       const int ko = (kt + 1) * 64;
; #pragma unroll
;       for (int i = 0; i < NA; ++i) glds16(Ab + ((size_t)i * 128 * lda + ko * 2) + voA, sn + (i * 512 + tid) * 16);
; #pragma unroll
;       for (int i = 0; i < NB; ++i) glds16(Bb + ((size_t)i * 128 * ldb + ko * 2) + voB, sn + AB + (i * 512 + tid) * 16);
;     } else if (nA) {
;       const unsigned nvoA = (unsigned)(srow * nlda + kch * 8) * 2u, nvoB = (unsigned)(srow * nldb + kch * 8) * 2u;
; #pragma unroll
;       for (int i = 0; i < NA; ++i) glds16((const char*)nA + (size_t)i * 128 * nlda + nvoA, smem + (i * 512 + tid) * 16);
; #pragma unroll
;       for (int i = 0; i < NB; ++i) glds16((const char*)nB + (size_t)i * 128 * nldb + nvoB, smem + AB + (i * 512 + tid) * 16);
;     }
;     const unsigned stb = lds_base + (kt & 1) * STG;
; #pragma unroll
;     for (int ks = 0; ks < 2; ++ks) {
;       const unsigned co = ((ks * 4 + fq) ^ sw) * 16;
;       const unsigned sa = stb + a_row + co, sb = stb + b_row + co;
;       bf16x8 af[4], bfr[NT];
; #pragma unroll
;       for (int n = 0; n < NT; ++n) asm volatile("ds_read_b128 %0, %1 offset:%2" : "=v"(bfr[n]) : "v"(sb), "n"(n * 2048) : "memory");
; #pragma unroll
;       for (int mg = 0; mg < MT / 4; ++mg) {
; #pragma unroll
;         for (int m = 0; m < 4; ++m) asm volatile("ds_read_b128 %0, %1 offset:%2" : "=v"(af[m]) : "v"(sa), "n"((mg * 4 + m) * 2048) : "memory");
;         if (mg == 0) {
; #pragma unroll
;           for (int n = 0; n < NT; ++n) asm volatile("s_waitcnt lgkmcnt(%1)" : "+v"(bfr[n]) : "n"(4 + NT - 1 - n) : "memory");
;         }
; #pragma unroll
;         for (int m = 0; m < 4; ++m) {
;           asm volatile("s_waitcnt lgkmcnt(%1)" : "+v"(af[m]) : "n"(3 - m) : "memory");
; #pragma unroll
;           for (int n = 0; n < NT; ++n) acc[mg * 4 + m][n] = MFMA16(bfr[n], af[m], acc[mg * 4 + m][n]);
;         }
;       }
;     }
	v_mfma_f32_16x16x32_bf16 v[44:47], v[152:155], v[208:211], v[44:47]
	s_mov_b32 m0, s14
	s_nop 0
	global_load_lds_dwordx4 v[144:145], off
	v_mfma_f32_16x16x32_bf16 v[40:43], v[156:159], v[208:211], v[40:43]
	ds_read_b128 v[180:183], v239 offset:4096
	v_mfma_f32_16x16x32_bf16 v[36:39], v[160:163], v[208:211], v[36:39]
	v_mfma_f32_16x16x32_bf16 v[32:35], v[164:167], v[208:211], v[32:35]
	ds_read_b128 v[184:187], v239 offset:6144
	s_waitcnt lgkmcnt(9)
	v_mfma_f32_16x16x32_bf16 v[28:31], v[152:155], v[228:231], v[28:31]
	v_mfma_f32_16x16x32_bf16 v[24:27], v[156:159], v[228:231], v[24:27]
	v_mfma_f32_16x16x32_bf16 v[20:23], v[160:163], v[228:231], v[20:23]
	v_mfma_f32_16x16x32_bf16 v[16:19], v[164:167], v[228:231], v[16:19]
	s_waitcnt lgkmcnt(8)
	v_mfma_f32_16x16x32_bf16 v[12:15], v[152:155], v[232:235], v[12:15]
	v_mfma_f32_16x16x32_bf16 v[8:11], v[156:159], v[232:235], v[8:11]
	v_mfma_f32_16x16x32_bf16 v[4:7], v[160:163], v[232:235], v[4:7]
	v_mfma_f32_16x16x32_bf16 v[0:3], v[164:167], v[232:235], v[0:3]
	s_waitcnt lgkmcnt(3)
	v_mfma_f32_16x16x32_bf16 v[124:127], v[188:191], v[168:171], v[124:127]
	v_mfma_f32_16x16x32_bf16 v[120:123], v[192:195], v[168:171], v[120:123]
	ds_read_b128 v[204:207], v239 offset:8192
	v_mfma_f32_16x16x32_bf16 v[116:119], v[196:199], v[168:171], v[116:119]
	v_mfma_f32_16x16x32_bf16 v[112:115], v[200:203], v[168:171], v[112:115]
	ds_read_b128 v[208:211], v239 offset:10240
	s_waitcnt lgkmcnt(4)
	v_mfma_f32_16x16x32_bf16 v[108:111], v[188:191], v[172:175], v[108:111]
	v_mfma_f32_16x16x32_bf16 v[104:107], v[192:195], v[172:175], v[104:107]
	ds_read_b128 v[228:231], v239 offset:12288
	v_mfma_f32_16x16x32_bf16 v[100:103], v[196:199], v[172:175], v[100:103]
	v_mfma_f32_16x16x32_bf16 v[96:99], v[200:203], v[172:175], v[96:99]
	ds_read_b128 v[232:235], v239 offset:14336
	s_waitcnt lgkmcnt(5)
	v_mfma_f32_16x16x32_bf16 v[92:95], v[188:191], v[180:183], v[92:95]
	v_mfma_f32_16x16x32_bf16 v[88:91], v[192:195], v[180:183], v[88:91]
	v_mfma_f32_16x16x32_bf16 v[84:87], v[196:199], v[180:183], v[84:87]
	v_mfma_f32_16x16x32_bf16 v[80:83], v[200:203], v[180:183], v[80:83]
	s_waitcnt lgkmcnt(4)
	v_mfma_f32_16x16x32_bf16 v[76:79], v[188:191], v[184:187], v[76:79]
	v_mfma_f32_16x16x32_bf16 v[72:75], v[192:195], v[184:187], v[72:75]
	v_mfma_f32_16x16x32_bf16 v[68:71], v[196:199], v[184:187], v[68:71]
	v_mfma_f32_16x16x32_bf16 v[64:67], v[200:203], v[184:187], v[64:67]
	s_add_u32 s46, s46, 0x80
	s_addc_u32 s47, s47, 0
	s_cmpk_eq_i32 s46, 0x780
	s_mov_b32 s13, s2
	s_cbranch_scc0 .LBB0_134
	s_waitcnt lgkmcnt(0)
	v_mfma_f32_16x16x32_bf16 v[60:63], v[188:191], v[204:207], v[60:63]
	v_mfma_f32_16x16x32_bf16 v[56:59], v[192:195], v[204:207], v[56:59]
	v_mfma_f32_16x16x32_bf16 v[52:55], v[196:199], v[204:207], v[52:55]
	v_mfma_f32_16x16x32_bf16 v[48:51], v[200:203], v[204:207], v[48:51]
	v_mfma_f32_16x16x32_bf16 v[44:47], v[188:191], v[208:211], v[44:47]
	v_mfma_f32_16x16x32_bf16 v[40:43], v[192:195], v[208:211], v[40:43]
	v_mfma_f32_16x16x32_bf16 v[36:39], v[196:199], v[208:211], v[36:39]
	v_mfma_f32_16x16x32_bf16 v[32:35], v[200:203], v[208:211], v[32:35]
	v_mfma_f32_16x16x32_bf16 v[28:31], v[188:191], v[228:231], v[28:31]
	v_mfma_f32_16x16x32_bf16 v[24:27], v[192:195], v[228:231], v[24:27]
	v_mfma_f32_16x16x32_bf16 v[20:23], v[196:199], v[228:231], v[20:23]
	v_mfma_f32_16x16x32_bf16 v[16:19], v[200:203], v[228:231], v[16:19]
	v_mfma_f32_16x16x32_bf16 v[12:15], v[188:191], v[232:235], v[12:15]
	v_mfma_f32_16x16x32_bf16 v[8:11], v[192:195], v[232:235], v[8:11]
	v_mfma_f32_16x16x32_bf16 v[4:7], v[196:199], v[232:235], v[4:7]
	v_mfma_f32_16x16x32_bf16 v[0:3], v[200:203], v[232:235], v[0:3]
	s_waitcnt vmcnt(0)
	s_andn2_b64 vcc, exec, s[10:11]
	s_mov_b64 s[48:49], s[26:27]
	s_mov_b64 s[50:51], 0xe3f8080
	s_barrier
	s_cbranch_vccnz .LBB0_137
	s_add_u32 s2, s54, s42
	s_addc_u32 s13, s55, s43
	s_and_b64 s[10:11], exec, s[38:39]
	s_cselect_b32 s11, 0, s13
	s_cselect_b32 s10, 0, s2
	v_readfirstlane_b32 s2, v139
	v_lshl_add_u64 v[134:135], s[10:11], 0, v[128:129]
	s_mov_b32 m0, s2
	v_lshl_add_u64 v[144:145], v[134:135], 0, s[80:81]
	v_lshl_add_u64 v[152:153], v[134:135], 0, s[82:83]
	v_lshl_add_u64 v[154:155], v[134:135], 0, s[70:71]
	global_load_lds_dwordx4 v[134:135], off
	v_add_u32_e32 v134, 0x2000, v139
	v_add_u32_e32 v143, 0x4000, v139
	v_readfirstlane_b32 s2, v134
	s_mov_b32 m0, s2
	v_readfirstlane_b32 s2, v143
	v_add_u32_e32 v134, 0x6000, v139
	s_add_u32 s14, s33, s44
	global_load_lds_dwordx4 v[154:155], off
	s_mov_b32 m0, s2
	v_readfirstlane_b32 s2, v134
	v_add_u32_e32 v134, 0x8000, v139
	s_addc_u32 s15, s34, s45
	global_load_lds_dwordx4 v[144:145], off
	s_mov_b32 m0, s2
	v_readfirstlane_b32 s2, v134
	v_add_u32_e32 v134, 0xa000, v139
	v_lshl_add_u64 v[136:137], s[14:15], 0, v[128:129]
	v_add_u32_e32 v128, 0xc000, v139
	global_load_lds_dwordx4 v[152:153], off
	s_mov_b32 m0, s2
	v_readfirstlane_b32 s2, v134
	v_lshl_add_u64 v[150:151], v[136:137], 0, s[70:71]
	global_load_lds_dwordx4 v[136:137], off
	s_mov_b32 m0, s2
	v_readfirstlane_b32 s2, v128
	v_add_u32_e32 v128, 0xe000, v139
	v_lshl_add_u64 v[146:147], v[136:137], 0, s[80:81]
	global_load_lds_dwordx4 v[150:151], off
	s_mov_b32 m0, s2
	v_readfirstlane_b32 s2, v128
	v_lshl_add_u64 v[148:149], v[136:137], 0, s[82:83]
	global_load_lds_dwordx4 v[146:147], off
	s_mov_b32 m0, s2
	s_nop 0
	global_load_lds_dwordx4 v[148:149], off

; DI void phase_gemm_resid(const bf16_t* __restrict__ A, int K, const bf16_t* __restrict__ Bt, const float* __restrict__ xin, float* __restrict__ xout, float alpha, unsigned char* smem) {
;     ...
; #pragma unroll
;     for (int m = 0; m < 8; ++m) {
;       const size_t row = (size_t)pm * 256 + wr * 128 + m * 16 + fr;
; #pragma unroll
;       for (int n = 0; n < 4; ++n) {
;         const size_t o = row * D + pn * 256 + wc * 64 + n * 16 + fq * 4;
;         const f32x4 x = *(const f32x4*)(xin + o);
;         *(f32x4*)(xout + o) = x + alpha * acc[m][n];
;       }
;     }
.LBB0_194:
	s_lshl_b32 s2, s2, 8
	s_ashr_i32 s10, s2, 31
	s_lshl_b64 s[6:7], s[6:7], 18
	v_mov_b32_e32 v137, s10
	v_or_b32_e32 v136, s2, v132
	v_lshl_add_u64 v[138:139], s[6:7], 0, v[134:135]
	v_lshl_add_u64 v[136:137], v[138:139], 0, v[136:137]
	v_lshlrev_b64 v[136:137], 2, v[136:137]
	v_lshl_add_u64 v[142:143], s[4:5], 0, v[136:137]
	v_readlane_b32 s10, v254, 42
	v_readlane_b32 s11, v254, 43
	global_load_dwordx4 v[168:171], v[142:143], off
	global_load_dwordx4 v[172:175], v[142:143], off offset:64
	global_load_dwordx4 v[176:179], v[142:143], off offset:128
	global_load_dwordx4 v[180:183], v[142:143], off offset:192
	s_mov_b64 s[6:7], 0x10000
	v_lshl_add_u64 v[248:249], v[142:143], 0, s[6:7]
	global_load_dwordx4 v[184:187], v[248:249], off
	global_load_dwordx4 v[188:191], v[248:249], off offset:64
	global_load_dwordx4 v[192:195], v[248:249], off offset:128
	global_load_dwordx4 v[196:199], v[248:249], off offset:192
	s_mov_b64 s[6:7], 0x20000
	v_lshl_add_u64 v[248:249], v[142:143], 0, s[6:7]
	global_load_dwordx4 v[200:203], v[248:249], off
	global_load_dwordx4 v[204:207], v[248:249], off offset:64
	global_load_dwordx4 v[208:211], v[248:249], off offset:128
	global_load_dwordx4 v[228:231], v[248:249], off offset:192
	s_mov_b64 s[6:7], 0x30000
	v_lshl_add_u64 v[248:249], v[142:143], 0, s[6:7]
	global_load_dwordx4 v[232:235], v[248:249], off
	global_load_dwordx4 v[236:239], v[248:249], off offset:64
	global_load_dwordx4 v[240:243], v[248:249], off offset:128
	global_load_dwordx4 v[244:247], v[248:249], off offset:192
	v_lshl_add_u64 v[138:139], s[10:11], 0, v[136:137]
	s_waitcnt vmcnt(15)
	v_pk_fma_f32 v[126:127], v[126:127], 0.5, v[170:171] op_sel_hi:[1,0,1]
	v_pk_fma_f32 v[124:125], v[124:125], 0.5, v[168:169] op_sel_hi:[1,0,1]
	global_store_dwordx4 v[138:139], v[124:127], off
	s_mov_b64 s[6:7], 0x40000
	v_lshl_add_u64 v[248:249], v[142:143], 0, s[6:7]
	global_load_dwordx4 v[168:171], v[248:249], off
	s_waitcnt vmcnt(16)
	v_pk_fma_f32 v[122:123], v[122:123], 0.5, v[174:175] op_sel_hi:[1,0,1]
	v_pk_fma_f32 v[120:121], v[120:121], 0.5, v[172:173] op_sel_hi:[1,0,1]
	global_store_dwordx4 v[138:139], v[120:123], off offset:64
	global_load_dwordx4 v[172:175], v[248:249], off offset:64
	s_waitcnt vmcnt(17)
	v_pk_fma_f32 v[118:119], v[118:119], 0.5, v[178:179] op_sel_hi:[1,0,1]
	v_pk_fma_f32 v[116:117], v[116:117], 0.5, v[176:177] op_sel_hi:[1,0,1]
	global_store_dwordx4 v[138:139], v[116:119], off offset:128
	global_load_dwordx4 v[176:179], v[248:249], off offset:128
	s_waitcnt vmcnt(18)
	v_pk_fma_f32 v[114:115], v[114:115], 0.5, v[182:183] op_sel_hi:[1,0,1]
	v_pk_fma_f32 v[112:113], v[112:113], 0.5, v[180:181] op_sel_hi:[1,0,1]
	global_store_dwordx4 v[138:139], v[112:115], off offset:192
	global_load_dwordx4 v[180:183], v[248:249], off offset:192
	s_waitcnt vmcnt(19)
	v_pk_fma_f32 v[110:111], v[110:111], 0.5, v[186:187] op_sel_hi:[1,0,1]
	v_pk_fma_f32 v[108:109], v[108:109], 0.5, v[184:185] op_sel_hi:[1,0,1]
	s_mov_b64 s[6:7], 0x10000
	v_lshl_add_u64 v[250:251], v[138:139], 0, s[6:7]
	global_store_dwordx4 v[250:251], v[108:111], off
	s_mov_b64 s[6:7], 0x50000
	v_lshl_add_u64 v[248:249], v[142:143], 0, s[6:7]
	global_load_dwordx4 v[184:187], v[248:249], off
	s_waitcnt vmcnt(20)
	v_pk_fma_f32 v[106:107], v[106:107], 0.5, v[190:191] op_sel_hi:[1,0,1]
	v_pk_fma_f32 v[104:105], v[104:105], 0.5, v[188:189] op_sel_hi:[1,0,1]
	global_store_dwordx4 v[250:251], v[104:107], off offset:64
	global_load_dwordx4 v[188:191], v[248:249], off offset:64
	s_waitcnt vmcnt(21)
	v_pk_fma_f32 v[102:103], v[102:103], 0.5, v[194:195] op_sel_hi:[1,0,1]
	v_pk_fma_f32 v[100:101], v[100:101], 0.5, v[192:193] op_sel_hi:[1,0,1]
	global_store_dwordx4 v[250:251], v[100:103], off offset:128
	global_load_dwordx4 v[192:195], v[248:249], off offset:128
	s_waitcnt vmcnt(22)
	v_pk_fma_f32 v[98:99], v[98:99], 0.5, v[198:199] op_sel_hi:[1,0,1]
	v_pk_fma_f32 v[96:97], v[96:97], 0.5, v[196:197] op_sel_hi:[1,0,1]
	global_store_dwordx4 v[250:251], v[96:99], off offset:192
	global_load_dwordx4 v[196:199], v[248:249], off offset:192
	s_waitcnt vmcnt(23)
	v_pk_fma_f32 v[94:95], v[94:95], 0.5, v[202:203] op_sel_hi:[1,0,1]
	v_pk_fma_f32 v[92:93], v[92:93], 0.5, v[200:201] op_sel_hi:[1,0,1]
	s_mov_b64 s[6:7], 0x20000
	v_lshl_add_u64 v[250:251], v[138:139], 0, s[6:7]
	global_store_dwordx4 v[250:251], v[92:95], off
	s_mov_b64 s[6:7], 0x60000
	v_lshl_add_u64 v[248:249], v[142:143], 0, s[6:7]
	global_load_dwordx4 v[200:203], v[248:249], off
	s_waitcnt vmcnt(24)
	v_pk_fma_f32 v[90:91], v[90:91], 0.5, v[206:207] op_sel_hi:[1,0,1]
	v_pk_fma_f32 v[88:89], v[88:89], 0.5, v[204:205] op_sel_hi:[1,0,1]
	global_store_dwordx4 v[250:251], v[88:91], off offset:64
	global_load_dwordx4 v[204:207], v[248:249], off offset:64
	s_waitcnt vmcnt(25)
	v_pk_fma_f32 v[86:87], v[86:87], 0.5, v[210:211] op_sel_hi:[1,0,1]
	v_pk_fma_f32 v[84:85], v[84:85], 0.5, v[208:209] op_sel_hi:[1,0,1]
	global_store_dwordx4 v[250:251], v[84:87], off offset:128
	global_load_dwordx4 v[208:211], v[248:249], off offset:128
	s_waitcnt vmcnt(26)
; DI void phase_gemm_resid(const bf16_t* __restrict__ A, int K, const bf16_t* __restrict__ Bt, const float* __restrict__ xin, float* __restrict__ xout, float alpha, unsigned char* smem) {
;     ...
; #pragma unroll
;     for (int m = 0; m < 8; ++m) {
;       const size_t row = (size_t)pm * 256 + wr * 128 + m * 16 + fr;
; #pragma unroll
;       for (int n = 0; n < 4; ++n) {
;         const size_t o = row * D + pn * 256 + wc * 64 + n * 16 + fq * 4;
;         const f32x4 x = *(const f32x4*)(xin + o);
;         *(f32x4*)(xout + o) = x + alpha * acc[m][n];
;       }
;     }
	v_pk_fma_f32 v[82:83], v[82:83], 0.5, v[230:231] op_sel_hi:[1,0,1]
	v_pk_fma_f32 v[80:81], v[80:81], 0.5, v[228:229] op_sel_hi:[1,0,1]
	global_store_dwordx4 v[250:251], v[80:83], off offset:192
	global_load_dwordx4 v[228:231], v[248:249], off offset:192
	s_waitcnt vmcnt(27)
	v_pk_fma_f32 v[78:79], v[78:79], 0.5, v[234:235] op_sel_hi:[1,0,1]
	v_pk_fma_f32 v[76:77], v[76:77], 0.5, v[232:233] op_sel_hi:[1,0,1]
	s_mov_b64 s[6:7], 0x30000
	v_lshl_add_u64 v[250:251], v[138:139], 0, s[6:7]
	global_store_dwordx4 v[250:251], v[76:79], off
	s_mov_b64 s[6:7], 0x70000
	v_lshl_add_u64 v[248:249], v[142:143], 0, s[6:7]
	global_load_dwordx4 v[232:235], v[248:249], off
	s_waitcnt vmcnt(28)
	v_pk_fma_f32 v[74:75], v[74:75], 0.5, v[238:239] op_sel_hi:[1,0,1]
	v_pk_fma_f32 v[72:73], v[72:73], 0.5, v[236:237] op_sel_hi:[1,0,1]
	global_store_dwordx4 v[250:251], v[72:75], off offset:64
	global_load_dwordx4 v[236:239], v[248:249], off offset:64
	s_waitcnt vmcnt(29)
	v_pk_fma_f32 v[70:71], v[70:71], 0.5, v[242:243] op_sel_hi:[1,0,1]
	v_pk_fma_f32 v[68:69], v[68:69], 0.5, v[240:241] op_sel_hi:[1,0,1]
	global_store_dwordx4 v[250:251], v[68:71], off offset:128
	global_load_dwordx4 v[240:243], v[248:249], off offset:128
	s_waitcnt vmcnt(30)
	v_pk_fma_f32 v[66:67], v[66:67], 0.5, v[246:247] op_sel_hi:[1,0,1]
	v_pk_fma_f32 v[64:65], v[64:65], 0.5, v[244:245] op_sel_hi:[1,0,1]
	global_store_dwordx4 v[250:251], v[64:67], off offset:192
	global_load_dwordx4 v[244:247], v[248:249], off offset:192
	s_waitcnt vmcnt(30)
	v_pk_fma_f32 v[62:63], v[62:63], 0.5, v[170:171] op_sel_hi:[1,0,1]
	v_pk_fma_f32 v[60:61], v[60:61], 0.5, v[168:169] op_sel_hi:[1,0,1]
	s_mov_b64 s[6:7], 0x40000
	v_lshl_add_u64 v[250:251], v[138:139], 0, s[6:7]
	global_store_dwordx4 v[250:251], v[60:63], off
	s_waitcnt vmcnt(29)
	v_pk_fma_f32 v[58:59], v[58:59], 0.5, v[174:175] op_sel_hi:[1,0,1]
	v_pk_fma_f32 v[56:57], v[56:57], 0.5, v[172:173] op_sel_hi:[1,0,1]
	global_store_dwordx4 v[250:251], v[56:59], off offset:64
	s_waitcnt vmcnt(28)
	v_pk_fma_f32 v[54:55], v[54:55], 0.5, v[178:179] op_sel_hi:[1,0,1]
	v_pk_fma_f32 v[52:53], v[52:53], 0.5, v[176:177] op_sel_hi:[1,0,1]
	global_store_dwordx4 v[250:251], v[52:55], off offset:128
	s_waitcnt vmcnt(27)
	v_pk_fma_f32 v[50:51], v[50:51], 0.5, v[182:183] op_sel_hi:[1,0,1]
	v_pk_fma_f32 v[48:49], v[48:49], 0.5, v[180:181] op_sel_hi:[1,0,1]
	global_store_dwordx4 v[250:251], v[48:51], off offset:192
	s_waitcnt vmcnt(26)
	v_pk_fma_f32 v[46:47], v[46:47], 0.5, v[186:187] op_sel_hi:[1,0,1]
	v_pk_fma_f32 v[44:45], v[44:45], 0.5, v[184:185] op_sel_hi:[1,0,1]
	s_mov_b64 s[6:7], 0x50000
	v_lshl_add_u64 v[250:251], v[138:139], 0, s[6:7]
	global_store_dwordx4 v[250:251], v[44:47], off
	s_waitcnt vmcnt(25)
	v_pk_fma_f32 v[42:43], v[42:43], 0.5, v[190:191] op_sel_hi:[1,0,1]
	v_pk_fma_f32 v[40:41], v[40:41], 0.5, v[188:189] op_sel_hi:[1,0,1]
	global_store_dwordx4 v[250:251], v[40:43], off offset:64
	s_waitcnt vmcnt(24)
	v_pk_fma_f32 v[38:39], v[38:39], 0.5, v[194:195] op_sel_hi:[1,0,1]
	v_pk_fma_f32 v[36:37], v[36:37], 0.5, v[192:193] op_sel_hi:[1,0,1]
	global_store_dwordx4 v[250:251], v[36:39], off offset:128
	s_waitcnt vmcnt(23)
	v_pk_fma_f32 v[34:35], v[34:35], 0.5, v[198:199] op_sel_hi:[1,0,1]
	v_pk_fma_f32 v[32:33], v[32:33], 0.5, v[196:197] op_sel_hi:[1,0,1]
	global_store_dwordx4 v[250:251], v[32:35], off offset:192
	s_waitcnt vmcnt(22)
	v_pk_fma_f32 v[30:31], v[30:31], 0.5, v[202:203] op_sel_hi:[1,0,1]
	v_pk_fma_f32 v[28:29], v[28:29], 0.5, v[200:201] op_sel_hi:[1,0,1]
	s_mov_b64 s[6:7], 0x60000
	v_lshl_add_u64 v[250:251], v[138:139], 0, s[6:7]
	global_store_dwordx4 v[250:251], v[28:31], off
	s_waitcnt vmcnt(21)
	v_pk_fma_f32 v[26:27], v[26:27], 0.5, v[206:207] op_sel_hi:[1,0,1]
	v_pk_fma_f32 v[24:25], v[24:25], 0.5, v[204:205] op_sel_hi:[1,0,1]
	global_store_dwordx4 v[250:251], v[24:27], off offset:64
	s_waitcnt vmcnt(20)
	v_pk_fma_f32 v[22:23], v[22:23], 0.5, v[210:211] op_sel_hi:[1,0,1]
	v_pk_fma_f32 v[20:21], v[20:21], 0.5, v[208:209] op_sel_hi:[1,0,1]
	global_store_dwordx4 v[250:251], v[20:23], off offset:128
	s_waitcnt vmcnt(19)
	v_pk_fma_f32 v[18:19], v[18:19], 0.5, v[230:231] op_sel_hi:[1,0,1]
	v_pk_fma_f32 v[16:17], v[16:17], 0.5, v[228:229] op_sel_hi:[1,0,1]
	global_store_dwordx4 v[250:251], v[16:19], off offset:192
	s_waitcnt vmcnt(18)
	v_pk_fma_f32 v[14:15], v[14:15], 0.5, v[234:235] op_sel_hi:[1,0,1]
	v_pk_fma_f32 v[12:13], v[12:13], 0.5, v[232:233] op_sel_hi:[1,0,1]
	s_mov_b64 s[6:7], 0x70000
	v_lshl_add_u64 v[250:251], v[138:139], 0, s[6:7]
	global_store_dwordx4 v[250:251], v[12:15], off
	s_waitcnt vmcnt(17)
	v_pk_fma_f32 v[10:11], v[10:11], 0.5, v[238:239] op_sel_hi:[1,0,1]
	v_pk_fma_f32 v[8:9], v[8:9], 0.5, v[236:237] op_sel_hi:[1,0,1]
	global_store_dwordx4 v[250:251], v[8:11], off offset:64
	s_waitcnt vmcnt(16)
	v_pk_fma_f32 v[6:7], v[6:7], 0.5, v[242:243] op_sel_hi:[1,0,1]
	v_pk_fma_f32 v[4:5], v[4:5], 0.5, v[240:241] op_sel_hi:[1,0,1]
	global_store_dwordx4 v[250:251], v[4:7], off offset:128
	s_waitcnt vmcnt(15)
	v_pk_fma_f32 v[2:3], v[2:3], 0.5, v[246:247] op_sel_hi:[1,0,1]
	v_pk_fma_f32 v[0:1], v[0:1], 0.5, v[244:245] op_sel_hi:[1,0,1]
	global_store_dwordx4 v[250:251], v[0:3], off offset:192
	s_mov_b64 s[6:7], 0x700c0
	s_andn2_b64 vcc, exec, s[38:39]
	s_mov_b32 s2, s22
	s_cbranch_vccz .LBB0_207

; #define MFMA16(a, b, c) __builtin_amdgcn_mfma_f32_16x16x32_bf16((a), (b), (c), 0, 0, 0)
; DI void glds16(const void* g, unsigned char* l) { __builtin_amdgcn_global_load_lds((const unsigned*)g, (lds_u32*)l, 16, 0, 0); }
; template <int N> DI void wait_vm() { asm volatile("s_waitcnt vmcnt(%0)" :: "n"(N) : "memory"); }
;     ...
;   for (int kt = 0; kt < nk; ++kt) {
;     wait_vm<0>();
;     __builtin_amdgcn_s_barrier();
;     if (kt + 1 < nk) {
;       unsigned char* sn = smem + ((kt + 1) & 1) * STG;
;       const int ko = (kt + 1) * 64;
; #pragma unroll
;       for (int i = 0; i < NA; ++i) glds16(Ab + ((size_t)i * 128 * lda + ko * 2) + voA, sn + (i * 512 + tid) * 16);
; #pragma unroll
;       for (int i = 0; i < NB; ++i) glds16(Bb + ((size_t)i * 128 * ldb + ko * 2) + voB, sn + AB + (i * 512 + tid) * 16);
;     } else if (nA) {
;       const unsigned nvoA = (unsigned)(srow * nlda + kch * 8) * 2u, nvoB = (unsigned)(srow * nldb + kch * 8) * 2u;
; #pragma unroll
;       for (int i = 0; i < NA; ++i) glds16((const char*)nA + (size_t)i * 128 * nlda + nvoA, smem + (i * 512 + tid) * 16);
; #pragma unroll
;       for (int i = 0; i < NB; ++i) glds16((const char*)nB + (size_t)i * 128 * nldb + nvoB, smem + AB + (i * 512 + tid) * 16);
;     }
;     const unsigned stb = lds_base + (kt & 1) * STG;
; #pragma unroll
;     for (int ks = 0; ks < 2; ++ks) {
;       const unsigned co = ((ks * 4 + fq) ^ sw) * 16;
;       const unsigned sa = stb + a_row + co, sb = stb + b_row + co;
;       bf16x8 af[4], bfr[NT];
; #pragma unroll
;       for (int n = 0; n < NT; ++n) asm volatile("ds_read_b128 %0, %1 offset:%2" : "=v"(bfr[n]) : "v"(sb), "n"(n * 2048) : "memory");
; #pragma unroll
;       for (int mg = 0; mg < MT / 4; ++mg) {
; #pragma unroll
;         for (int m = 0; m < 4; ++m) asm volatile("ds_read_b128 %0, %1 offset:%2" : "=v"(af[m]) : "v"(sa), "n"((mg * 4 + m) * 2048) : "memory");
;         if (mg == 0) {
; #pragma unroll
;           for (int n = 0; n < NT; ++n) asm volatile("s_waitcnt lgkmcnt(%1)" : "+v"(bfr[n]) : "n"(4 + NT - 1 - n) : "memory");
;         }
; #pragma unroll
;         for (int m = 0; m < 4; ++m) {
;           asm volatile("s_waitcnt lgkmcnt(%1)" : "+v"(af[m]) : "n"(3 - m) : "memory");
; #pragma unroll
;           for (int n = 0; n < NT; ++n) acc[mg * 4 + m][n] = MFMA16(bfr[n], af[m], acc[mg * 4 + m][n]);
;         }
;       }
;     }
.LBB0_202:
	s_add_i32 s14, s15, 0x10000
	s_and_b32 s16, s14, 0x10000
	v_add_u32_e32 v143, s16, v133
	v_lshl_add_u64 v[144:145], v[136:137], 0, s[44:45]
	v_readfirstlane_b32 s16, v143
	v_add_u32_e32 v148, 0x2000, v143
	v_lshl_add_u64 v[146:147], v[144:145], 0, s[96:97]
	s_mov_b32 m0, s16
	v_readfirstlane_b32 s16, v148
	v_add_u32_e32 v148, 0x4000, v143
	s_waitcnt vmcnt(0)
	s_waitcnt lgkmcnt(0)
	s_barrier
	s_and_b32 s15, s15, 0x10000
	v_add_u32_e32 v240, s15, v142
	v_add_u32_e32 v236, v240, v140
	v_add_u32_e32 v237, v240, v131
	v_add_u32_e32 v240, s15, v141
	v_add_u32_e32 v238, v240, v140
	v_add_u32_e32 v239, v240, v131
	v_mfma_f32_16x16x32_bf16 v[60:63], v[188:191], v[204:207], v[60:63]
	ds_read_b128 v[152:155], v236 offset:0
	ds_read_b128 v[156:159], v236 offset:2048
	v_mfma_f32_16x16x32_bf16 v[56:59], v[192:195], v[204:207], v[56:59]
	ds_read_b128 v[160:163], v236 offset:4096
	ds_read_b128 v[164:167], v236 offset:6144
	global_load_lds_dwordx4 v[146:147], off
	v_mfma_f32_16x16x32_bf16 v[52:55], v[196:199], v[204:207], v[52:55]
	ds_read_b128 v[168:171], v238 offset:0
	ds_read_b128 v[172:175], v238 offset:2048
	v_mfma_f32_16x16x32_bf16 v[48:51], v[200:203], v[204:207], v[48:51]
	ds_read_b128 v[180:183], v238 offset:4096
	ds_read_b128 v[184:187], v238 offset:6144
	v_mfma_f32_16x16x32_bf16 v[44:47], v[188:191], v[208:211], v[44:47]
	v_mfma_f32_16x16x32_bf16 v[40:43], v[192:195], v[208:211], v[40:43]
	v_mfma_f32_16x16x32_bf16 v[36:39], v[196:199], v[208:211], v[36:39]
	v_lshl_add_u64 v[146:147], v[144:145], 0, s[78:79]
	s_mov_b32 m0, s16
	v_readfirstlane_b32 s16, v148
	global_load_lds_dwordx4 v[146:147], off
	v_mfma_f32_16x16x32_bf16 v[32:35], v[200:203], v[208:211], v[32:35]
	v_mfma_f32_16x16x32_bf16 v[28:31], v[188:191], v[228:231], v[28:31]
	v_mfma_f32_16x16x32_bf16 v[24:27], v[192:195], v[228:231], v[24:27]
	v_mfma_f32_16x16x32_bf16 v[20:23], v[196:199], v[228:231], v[20:23]
	v_mfma_f32_16x16x32_bf16 v[16:19], v[200:203], v[228:231], v[16:19]
	v_lshl_add_u64 v[146:147], v[144:145], 0, s[50:51]
	s_mov_b32 m0, s16
	v_lshl_add_u64 v[144:145], v[144:145], 0, s[26:27]
	global_load_lds_dwordx4 v[146:147], off
	v_mfma_f32_16x16x32_bf16 v[12:15], v[188:191], v[232:235], v[12:15]
	v_mfma_f32_16x16x32_bf16 v[8:11], v[192:195], v[232:235], v[8:11]
	v_mfma_f32_16x16x32_bf16 v[4:7], v[196:199], v[232:235], v[4:7]
	v_mfma_f32_16x16x32_bf16 v[0:3], v[200:203], v[232:235], v[0:3]
	s_waitcnt lgkmcnt(3)
	v_mfma_f32_16x16x32_bf16 v[124:127], v[152:155], v[168:171], v[124:127]
	v_add_u32_e32 v146, 0x6000, v143
	v_add_u32_e32 v148, 0x8000, v143
	v_readfirstlane_b32 s16, v146
	s_mov_b32 m0, s16
	s_mov_b64 s[16:17], 0xb08080
	global_load_lds_dwordx4 v[144:145], off
	v_mfma_f32_16x16x32_bf16 v[120:123], v[156:159], v[168:171], v[120:123]
	ds_read_b128 v[204:207], v238 offset:8192
	v_mfma_f32_16x16x32_bf16 v[116:119], v[160:163], v[168:171], v[116:119]
	v_mfma_f32_16x16x32_bf16 v[112:115], v[164:167], v[168:171], v[112:115]
	ds_read_b128 v[208:211], v238 offset:10240
	s_waitcnt lgkmcnt(4)
	v_mfma_f32_16x16x32_bf16 v[108:111], v[152:155], v[172:175], v[108:111]
	v_mfma_f32_16x16x32_bf16 v[104:107], v[156:159], v[172:175], v[104:107]
	ds_read_b128 v[228:231], v238 offset:12288
	v_lshl_add_u64 v[144:145], v[138:139], 0, s[44:45]
	v_lshl_add_u64 v[146:147], v[144:145], 0, s[16:17]
	v_readfirstlane_b32 s16, v148
	s_mov_b32 m0, s16
	s_mov_b64 s[16:17], 0xb60080
	v_add_u32_e32 v148, 0xa000, v143
	global_load_lds_dwordx4 v[146:147], off
	v_mfma_f32_16x16x32_bf16 v[100:103], v[160:163], v[172:175], v[100:103]
	v_mfma_f32_16x16x32_bf16 v[96:99], v[164:167], v[172:175], v[96:99]
	ds_read_b128 v[232:235], v238 offset:14336
	s_waitcnt lgkmcnt(5)
	v_mfma_f32_16x16x32_bf16 v[92:95], v[152:155], v[180:183], v[92:95]
	v_mfma_f32_16x16x32_bf16 v[88:91], v[156:159], v[180:183], v[88:91]
	ds_read_b128 v[188:191], v237 offset:0
	v_mfma_f32_16x16x32_bf16 v[84:87], v[160:163], v[180:183], v[84:87]
	v_lshl_add_u64 v[146:147], v[144:145], 0, s[16:17]
	v_readfirstlane_b32 s16, v148
	s_mov_b32 m0, s16
	s_mov_b64 s[16:17], 0xbb8080
	v_add_u32_e32 v148, 0xc000, v143
	global_load_lds_dwordx4 v[146:147], off
	v_mfma_f32_16x16x32_bf16 v[80:83], v[164:167], v[180:183], v[80:83]
	ds_read_b128 v[192:195], v237 offset:2048
	s_waitcnt lgkmcnt(6)
	v_mfma_f32_16x16x32_bf16 v[76:79], v[152:155], v[184:187], v[76:79]
	v_mfma_f32_16x16x32_bf16 v[72:75], v[156:159], v[184:187], v[72:75]
	ds_read_b128 v[196:199], v237 offset:4096
	v_mfma_f32_16x16x32_bf16 v[68:71], v[160:163], v[184:187], v[68:71]
	v_mfma_f32_16x16x32_bf16 v[64:67], v[164:167], v[184:187], v[64:67]
	ds_read_b128 v[200:203], v237 offset:6144
	v_lshl_add_u64 v[146:147], v[144:145], 0, s[16:17]
	v_readfirstlane_b32 s16, v148
	s_mov_b32 m0, s16
	s_mov_b64 s[16:17], 0xc10080
	v_add_u32_e32 v143, 0xe000, v143
	v_lshl_add_u64 v[144:145], v[144:145], 0, s[16:17]
	v_readfirstlane_b32 s16, v143
	global_load_lds_dwordx4 v[146:147], off
	s_waitcnt lgkmcnt(7)
	v_mfma_f32_16x16x32_bf16 v[60:63], v[152:155], v[204:207], v[60:63]
	v_mfma_f32_16x16x32_bf16 v[56:59], v[156:159], v[204:207], v[56:59]
	ds_read_b128 v[168:171], v239 offset:0
	v_mfma_f32_16x16x32_bf16 v[52:55], v[160:163], v[204:207], v[52:55]
	v_mfma_f32_16x16x32_bf16 v[48:51], v[164:167], v[204:207], v[48:51]
	ds_read_b128 v[172:175], v239 offset:2048
	s_waitcnt lgkmcnt(8)
; #define MFMA16(a, b, c) __builtin_amdgcn_mfma_f32_16x16x32_bf16((a), (b), (c), 0, 0, 0)
; DI void glds16(const void* g, unsigned char* l) { __builtin_amdgcn_global_load_lds((const unsigned*)g, (lds_u32*)l, 16, 0, 0); }
; template <int N> DI void wait_vm() { asm volatile("s_waitcnt vmcnt(%0)" :: "n"(N) : "memory"); }
;     ...
;   for (int kt = 0; kt < nk; ++kt) {
;     wait_vm<0>();
;     __builtin_amdgcn_s_barrier();
;     if (kt + 1 < nk) {
;       unsigned char* sn = smem + ((kt + 1) & 1) * STG;
;       const int ko = (kt + 1) * 64;
; #pragma unroll
;       for (int i = 0; i < NA; ++i) glds16(Ab + ((size_t)i * 128 * lda + ko * 2) + voA, sn + (i * 512 + tid) * 16);
; #pragma unroll
;       for (int i = 0; i < NB; ++i) glds16(Bb + ((size_t)i * 128 * ldb + ko * 2) + voB, sn + AB + (i * 512 + tid) * 16);
;     } else if (nA) {
;       const unsigned nvoA = (unsigned)(srow * nlda + kch * 8) * 2u, nvoB = (unsigned)(srow * nldb + kch * 8) * 2u;
; #pragma unroll
;       for (int i = 0; i < NA; ++i) glds16((const char*)nA + (size_t)i * 128 * nlda + nvoA, smem + (i * 512 + tid) * 16);
; #pragma unroll
;       for (int i = 0; i < NB; ++i) glds16((const char*)nB + (size_t)i * 128 * nldb + nvoB, smem + AB + (i * 512 + tid) * 16);
;     }
;     const unsigned stb = lds_base + (kt & 1) * STG;
; #pragma unroll
;     for (int ks = 0; ks < 2; ++ks) {
;       const unsigned co = ((ks * 4 + fq) ^ sw) * 16;
;       const unsigned sa = stb + a_row + co, sb = stb + b_row + co;
;       bf16x8 af[4], bfr[NT];
; #pragma unroll
;       for (int n = 0; n < NT; ++n) asm volatile("ds_read_b128 %0, %1 offset:%2" : "=v"(bfr[n]) : "v"(sb), "n"(n * 2048) : "memory");
; #pragma unroll
;       for (int mg = 0; mg < MT / 4; ++mg) {
; #pragma unroll
;         for (int m = 0; m < 4; ++m) asm volatile("ds_read_b128 %0, %1 offset:%2" : "=v"(af[m]) : "v"(sa), "n"((mg * 4 + m) * 2048) : "memory");
;         if (mg == 0) {
; #pragma unroll
;           for (int n = 0; n < NT; ++n) asm volatile("s_waitcnt lgkmcnt(%1)" : "+v"(bfr[n]) : "n"(4 + NT - 1 - n) : "memory");
;         }
; #pragma unroll
;         for (int m = 0; m < 4; ++m) {
;           asm volatile("s_waitcnt lgkmcnt(%1)" : "+v"(af[m]) : "n"(3 - m) : "memory");
; #pragma unroll
;           for (int n = 0; n < NT; ++n) acc[mg * 4 + m][n] = MFMA16(bfr[n], af[m], acc[mg * 4 + m][n]);
;         }
;       }
;     }
	v_mfma_f32_16x16x32_bf16 v[44:47], v[152:155], v[208:211], v[44:47]
	s_mov_b32 m0, s16
	s_nop 0
	global_load_lds_dwordx4 v[144:145], off
	v_mfma_f32_16x16x32_bf16 v[40:43], v[156:159], v[208:211], v[40:43]
	ds_read_b128 v[180:183], v239 offset:4096
	v_mfma_f32_16x16x32_bf16 v[36:39], v[160:163], v[208:211], v[36:39]
	v_mfma_f32_16x16x32_bf16 v[32:35], v[164:167], v[208:211], v[32:35]
	ds_read_b128 v[184:187], v239 offset:6144
	s_waitcnt lgkmcnt(9)
	v_mfma_f32_16x16x32_bf16 v[28:31], v[152:155], v[228:231], v[28:31]
	v_mfma_f32_16x16x32_bf16 v[24:27], v[156:159], v[228:231], v[24:27]
	v_mfma_f32_16x16x32_bf16 v[20:23], v[160:163], v[228:231], v[20:23]
	v_mfma_f32_16x16x32_bf16 v[16:19], v[164:167], v[228:231], v[16:19]
	s_waitcnt lgkmcnt(8)
	v_mfma_f32_16x16x32_bf16 v[12:15], v[152:155], v[232:235], v[12:15]
	v_mfma_f32_16x16x32_bf16 v[8:11], v[156:159], v[232:235], v[8:11]
	v_mfma_f32_16x16x32_bf16 v[4:7], v[160:163], v[232:235], v[4:7]
	v_mfma_f32_16x16x32_bf16 v[0:3], v[164:167], v[232:235], v[0:3]
	s_waitcnt lgkmcnt(3)
	v_mfma_f32_16x16x32_bf16 v[124:127], v[188:191], v[168:171], v[124:127]
	v_mfma_f32_16x16x32_bf16 v[120:123], v[192:195], v[168:171], v[120:123]
	ds_read_b128 v[204:207], v239 offset:8192
	v_mfma_f32_16x16x32_bf16 v[116:119], v[196:199], v[168:171], v[116:119]
	v_mfma_f32_16x16x32_bf16 v[112:115], v[200:203], v[168:171], v[112:115]
	ds_read_b128 v[208:211], v239 offset:10240
	s_waitcnt lgkmcnt(4)
	v_mfma_f32_16x16x32_bf16 v[108:111], v[188:191], v[172:175], v[108:111]
	v_mfma_f32_16x16x32_bf16 v[104:107], v[192:195], v[172:175], v[104:107]
	ds_read_b128 v[228:231], v239 offset:12288
	v_mfma_f32_16x16x32_bf16 v[100:103], v[196:199], v[172:175], v[100:103]
	v_mfma_f32_16x16x32_bf16 v[96:99], v[200:203], v[172:175], v[96:99]
	ds_read_b128 v[232:235], v239 offset:14336
	s_waitcnt lgkmcnt(5)
	v_mfma_f32_16x16x32_bf16 v[92:95], v[188:191], v[180:183], v[92:95]
	v_mfma_f32_16x16x32_bf16 v[88:91], v[192:195], v[180:183], v[88:91]
	v_mfma_f32_16x16x32_bf16 v[84:87], v[196:199], v[180:183], v[84:87]
	v_mfma_f32_16x16x32_bf16 v[80:83], v[200:203], v[180:183], v[80:83]
	s_waitcnt lgkmcnt(4)
	v_mfma_f32_16x16x32_bf16 v[76:79], v[188:191], v[184:187], v[76:79]
	v_mfma_f32_16x16x32_bf16 v[72:75], v[192:195], v[184:187], v[72:75]
	v_mfma_f32_16x16x32_bf16 v[68:71], v[196:199], v[184:187], v[68:71]
	v_mfma_f32_16x16x32_bf16 v[64:67], v[200:203], v[184:187], v[64:67]
	s_add_u32 s44, s44, 0x80
	s_addc_u32 s45, s45, 0
	s_cmpk_eq_i32 s44, 0x1580
	s_mov_b32 s15, s14
	s_cbranch_scc0 .LBB0_202
	s_waitcnt lgkmcnt(0)
	v_mfma_f32_16x16x32_bf16 v[60:63], v[188:191], v[204:207], v[60:63]
	v_mfma_f32_16x16x32_bf16 v[56:59], v[192:195], v[204:207], v[56:59]
	v_mfma_f32_16x16x32_bf16 v[52:55], v[196:199], v[204:207], v[52:55]
	v_mfma_f32_16x16x32_bf16 v[48:51], v[200:203], v[204:207], v[48:51]
	v_mfma_f32_16x16x32_bf16 v[44:47], v[188:191], v[208:211], v[44:47]
	v_mfma_f32_16x16x32_bf16 v[40:43], v[192:195], v[208:211], v[40:43]
	v_mfma_f32_16x16x32_bf16 v[36:39], v[196:199], v[208:211], v[36:39]
	v_mfma_f32_16x16x32_bf16 v[32:35], v[200:203], v[208:211], v[32:35]
	v_mfma_f32_16x16x32_bf16 v[28:31], v[188:191], v[228:231], v[28:31]
	v_mfma_f32_16x16x32_bf16 v[24:27], v[192:195], v[228:231], v[24:27]
	v_mfma_f32_16x16x32_bf16 v[20:23], v[196:199], v[228:231], v[20:23]
	v_mfma_f32_16x16x32_bf16 v[16:19], v[200:203], v[228:231], v[16:19]
	v_mfma_f32_16x16x32_bf16 v[12:15], v[188:191], v[232:235], v[12:15]
	v_mfma_f32_16x16x32_bf16 v[8:11], v[192:195], v[232:235], v[8:11]
	v_mfma_f32_16x16x32_bf16 v[4:7], v[196:199], v[232:235], v[4:7]
	v_mfma_f32_16x16x32_bf16 v[0:3], v[200:203], v[232:235], v[0:3]
	s_waitcnt vmcnt(0)
	s_andn2_b64 vcc, exec, s[12:13]
	s_mov_b32 s23, 0x10000
	s_barrier
	s_cbranch_vccnz .LBB0_205
	s_lshl_b64 s[10:11], s[10:11], 1
	s_add_u32 s12, s52, s10
	s_addc_u32 s13, s53, s11
	s_and_b64 s[10:11], exec, s[38:39]
	s_cselect_b32 s11, 0, s13
	s_cselect_b32 s10, 0, s12
	s_lshl_b64 s[12:13], s[42:43], 1
	s_add_u32 s12, s18, s12
	s_addc_u32 s13, s19, s13
	v_lshl_add_u64 v[136:137], s[10:11], 0, v[128:129]
	v_lshl_add_u64 v[138:139], s[12:13], 0, v[128:129]
	s_mov_b64 s[10:11], 0xb0000
	v_lshl_add_u64 v[144:145], v[136:137], 0, s[10:11]
	v_lshl_add_u64 v[146:147], v[138:139], 0, s[10:11]
	s_mov_b64 s[10:11], 0x58000
	v_lshl_add_u64 v[150:151], v[138:139], 0, s[10:11]
	v_lshl_add_u64 v[154:155], v[136:137], 0, s[10:11]
	v_readfirstlane_b32 s10, v133
	s_mov_b64 s[12:13], 0x108000
	s_mov_b32 m0, s10
	v_lshl_add_u64 v[152:153], v[136:137], 0, s[12:13]
	global_load_lds_dwordx4 v[136:137], off
	v_add_u32_e32 v136, 0x2000, v133
	v_add_u32_e32 v143, 0x4000, v133
	v_readfirstlane_b32 s10, v136
	s_mov_b32 m0, s10
	v_readfirstlane_b32 s10, v143
	v_add_u32_e32 v136, 0x6000, v133
	global_load_lds_dwordx4 v[154:155], off
	s_mov_b32 m0, s10
	v_readfirstlane_b32 s10, v136
	v_add_u32_e32 v136, 0x8000, v133
	global_load_lds_dwordx4 v[144:145], off
	s_mov_b32 m0, s10
	v_readfirstlane_b32 s10, v136
	v_add_u32_e32 v136, 0xa000, v133
	v_add_u32_e32 v128, 0xc000, v133
	global_load_lds_dwordx4 v[152:153], off
	s_mov_b32 m0, s10
	v_readfirstlane_b32 s10, v136
	global_load_lds_dwordx4 v[138:139], off
	s_mov_b32 m0, s10
	v_readfirstlane_b32 s10, v128
	v_add_u32_e32 v128, 0xe000, v133
	global_load_lds_dwordx4 v[150:151], off
	s_mov_b32 m0, s10
	v_readfirstlane_b32 s10, v128
	v_lshl_add_u64 v[148:149], v[138:139], 0, s[12:13]
	global_load_lds_dwordx4 v[146:147], off
	s_mov_b32 m0, s10
	s_nop 0
	global_load_lds_dwordx4 v[148:149], off

; #define MFMA16(a, b, c) __builtin_amdgcn_mfma_f32_16x16x32_bf16((a), (b), (c), 0, 0, 0)
; DI void glds16(const void* g, unsigned char* l) { __builtin_amdgcn_global_load_lds((const unsigned*)g, (lds_u32*)l, 16, 0, 0); }
; template <int N> DI void wait_vm() { asm volatile("s_waitcnt vmcnt(%0)" :: "n"(N) : "memory"); }
;     ...
;   for (int kt = 0; kt < nk; ++kt) {
;     wait_vm<0>();
;     __builtin_amdgcn_s_barrier();
;     if (kt + 1 < nk) {
;       unsigned char* sn = smem + ((kt + 1) & 1) * STG;
;       const int ko = (kt + 1) * 64;
; #pragma unroll
;       for (int i = 0; i < NA; ++i) glds16(Ab + ((size_t)i * 128 * lda + ko * 2) + voA, sn + (i * 512 + tid) * 16);
; #pragma unroll
;       for (int i = 0; i < NB; ++i) glds16(Bb + ((size_t)i * 128 * ldb + ko * 2) + voB, sn + AB + (i * 512 + tid) * 16);
;     } else if (nA) {
;       const unsigned nvoA = (unsigned)(srow * nlda + kch * 8) * 2u, nvoB = (unsigned)(srow * nldb + kch * 8) * 2u;
; #pragma unroll
;       for (int i = 0; i < NA; ++i) glds16((const char*)nA + (size_t)i * 128 * nlda + nvoA, smem + (i * 512 + tid) * 16);
; #pragma unroll
;       for (int i = 0; i < NB; ++i) glds16((const char*)nB + (size_t)i * 128 * nldb + nvoB, smem + AB + (i * 512 + tid) * 16);
;     }
;     const unsigned stb = lds_base + (kt & 1) * STG;
; #pragma unroll
;     for (int ks = 0; ks < 2; ++ks) {
;       const unsigned co = ((ks * 4 + fq) ^ sw) * 16;
;       const unsigned sa = stb + a_row + co, sb = stb + b_row + co;
;       bf16x8 af[4], bfr[NT];
; #pragma unroll
;       for (int n = 0; n < NT; ++n) asm volatile("ds_read_b128 %0, %1 offset:%2" : "=v"(bfr[n]) : "v"(sb), "n"(n * 2048) : "memory");
; #pragma unroll
;       for (int mg = 0; mg < MT / 4; ++mg) {
; #pragma unroll
;         for (int m = 0; m < 4; ++m) asm volatile("ds_read_b128 %0, %1 offset:%2" : "=v"(af[m]) : "v"(sa), "n"((mg * 4 + m) * 2048) : "memory");
;         if (mg == 0) {
; #pragma unroll
;           for (int n = 0; n < NT; ++n) asm volatile("s_waitcnt lgkmcnt(%1)" : "+v"(bfr[n]) : "n"(4 + NT - 1 - n) : "memory");
;         }
; #pragma unroll
;         for (int m = 0; m < 4; ++m) {
;           asm volatile("s_waitcnt lgkmcnt(%1)" : "+v"(af[m]) : "n"(3 - m) : "memory");
; #pragma unroll
;           for (int n = 0; n < NT; ++n) acc[mg * 4 + m][n] = MFMA16(bfr[n], af[m], acc[mg * 4 + m][n]);
;         }
;       }
;     }
.LBB0_335:
	s_add_i32 s5, s14, 0x10000
	s_and_b32 s15, s5, 0x10000
	v_add_u32_e32 v148, s15, v140
	v_lshl_add_u64 v[144:145], v[136:137], 0, s[42:43]
	v_readfirstlane_b32 s15, v148
	v_add_u32_e32 v149, 0x2000, v148
	v_lshl_add_u64 v[146:147], v[144:145], 0, s[58:59]
	s_mov_b32 m0, s15
	v_readfirstlane_b32 s15, v149
	v_add_u32_e32 v149, 0x4000, v148
	s_waitcnt vmcnt(0)
	s_waitcnt lgkmcnt(0)
	s_barrier
	s_and_b32 s14, s14, 0x10000
	v_add_u32_e32 v240, s14, v143
	v_add_u32_e32 v236, v240, v141
	v_add_u32_e32 v237, v240, v131
	v_add_u32_e32 v240, s14, v142
	v_add_u32_e32 v238, v240, v141
	v_add_u32_e32 v239, v240, v131
	v_mfma_f32_16x16x32_bf16 v[60:63], v[188:191], v[204:207], v[60:63]
	ds_read_b128 v[152:155], v236 offset:0
	ds_read_b128 v[156:159], v236 offset:2048
	v_mfma_f32_16x16x32_bf16 v[56:59], v[192:195], v[204:207], v[56:59]
	ds_read_b128 v[160:163], v236 offset:4096
	ds_read_b128 v[164:167], v236 offset:6144
	global_load_lds_dwordx4 v[146:147], off
	v_mfma_f32_16x16x32_bf16 v[52:55], v[196:199], v[204:207], v[52:55]
	ds_read_b128 v[168:171], v238 offset:0
	ds_read_b128 v[172:175], v238 offset:2048
	v_mfma_f32_16x16x32_bf16 v[48:51], v[200:203], v[204:207], v[48:51]
	ds_read_b128 v[180:183], v238 offset:4096
	ds_read_b128 v[184:187], v238 offset:6144
	v_mfma_f32_16x16x32_bf16 v[44:47], v[188:191], v[208:211], v[44:47]
	v_mfma_f32_16x16x32_bf16 v[40:43], v[192:195], v[208:211], v[40:43]
	v_mfma_f32_16x16x32_bf16 v[36:39], v[196:199], v[208:211], v[36:39]
	v_lshl_add_u64 v[146:147], v[144:145], 0, s[60:61]
	s_mov_b32 m0, s15
	v_readfirstlane_b32 s15, v149
	global_load_lds_dwordx4 v[146:147], off
	v_mfma_f32_16x16x32_bf16 v[32:35], v[200:203], v[208:211], v[32:35]
	v_mfma_f32_16x16x32_bf16 v[28:31], v[188:191], v[228:231], v[28:31]
	v_mfma_f32_16x16x32_bf16 v[24:27], v[192:195], v[228:231], v[24:27]
	v_mfma_f32_16x16x32_bf16 v[20:23], v[196:199], v[228:231], v[20:23]
	v_mfma_f32_16x16x32_bf16 v[16:19], v[200:203], v[228:231], v[16:19]
	v_lshl_add_u64 v[146:147], v[144:145], 0, s[62:63]
	s_mov_b32 m0, s15
	v_lshl_add_u64 v[144:145], v[144:145], 0, s[64:65]
	global_load_lds_dwordx4 v[146:147], off
	v_mfma_f32_16x16x32_bf16 v[12:15], v[188:191], v[232:235], v[12:15]
	v_mfma_f32_16x16x32_bf16 v[8:11], v[192:195], v[232:235], v[8:11]
	v_mfma_f32_16x16x32_bf16 v[4:7], v[196:199], v[232:235], v[4:7]
	v_mfma_f32_16x16x32_bf16 v[0:3], v[200:203], v[232:235], v[0:3]
	s_waitcnt lgkmcnt(3)
	v_mfma_f32_16x16x32_bf16 v[124:127], v[152:155], v[168:171], v[124:127]
	v_add_u32_e32 v146, 0x6000, v148
	v_add_u32_e32 v149, 0x8000, v148
	v_readfirstlane_b32 s15, v146
	s_mov_b32 m0, s15
	v_readfirstlane_b32 s15, v149
	global_load_lds_dwordx4 v[144:145], off
	v_mfma_f32_16x16x32_bf16 v[120:123], v[156:159], v[168:171], v[120:123]
	ds_read_b128 v[204:207], v238 offset:8192
	v_mfma_f32_16x16x32_bf16 v[116:119], v[160:163], v[168:171], v[116:119]
	v_mfma_f32_16x16x32_bf16 v[112:115], v[164:167], v[168:171], v[112:115]
	ds_read_b128 v[208:211], v238 offset:10240
	s_waitcnt lgkmcnt(4)
	v_mfma_f32_16x16x32_bf16 v[108:111], v[152:155], v[172:175], v[108:111]
	v_mfma_f32_16x16x32_bf16 v[104:107], v[156:159], v[172:175], v[104:107]
	ds_read_b128 v[228:231], v238 offset:12288
	v_lshl_add_u64 v[144:145], v[138:139], 0, s[42:43]
	v_add_u32_e32 v149, 0xa000, v148
	v_lshl_add_u64 v[146:147], v[144:145], 0, s[72:73]
	s_mov_b32 m0, s15
	v_readfirstlane_b32 s15, v149
	v_add_u32_e32 v149, 0xc000, v148
	global_load_lds_dwordx4 v[146:147], off
	v_mfma_f32_16x16x32_bf16 v[100:103], v[160:163], v[172:175], v[100:103]
	v_mfma_f32_16x16x32_bf16 v[96:99], v[164:167], v[172:175], v[96:99]
	ds_read_b128 v[232:235], v238 offset:14336
	s_waitcnt lgkmcnt(5)
	v_mfma_f32_16x16x32_bf16 v[92:95], v[152:155], v[180:183], v[92:95]
	v_mfma_f32_16x16x32_bf16 v[88:91], v[156:159], v[180:183], v[88:91]
	ds_read_b128 v[188:191], v237 offset:0
	v_mfma_f32_16x16x32_bf16 v[84:87], v[160:163], v[180:183], v[84:87]
	v_lshl_add_u64 v[146:147], v[144:145], 0, s[74:75]
	s_mov_b32 m0, s15
	s_mov_b64 s[16:17], 0x2148080
	v_readfirstlane_b32 s15, v149
	global_load_lds_dwordx4 v[146:147], off
	v_mfma_f32_16x16x32_bf16 v[80:83], v[164:167], v[180:183], v[80:83]
	ds_read_b128 v[192:195], v237 offset:2048
	s_waitcnt lgkmcnt(6)
	v_mfma_f32_16x16x32_bf16 v[76:79], v[152:155], v[184:187], v[76:79]
	v_mfma_f32_16x16x32_bf16 v[72:75], v[156:159], v[184:187], v[72:75]
	ds_read_b128 v[196:199], v237 offset:4096
	v_mfma_f32_16x16x32_bf16 v[68:71], v[160:163], v[184:187], v[68:71]
	v_mfma_f32_16x16x32_bf16 v[64:67], v[164:167], v[184:187], v[64:67]
	ds_read_b128 v[200:203], v237 offset:6144
	v_lshl_add_u64 v[146:147], v[144:145], 0, s[16:17]
	s_mov_b32 m0, s15
	s_mov_b64 s[16:17], 0x2168080
	global_load_lds_dwordx4 v[146:147], off
	s_waitcnt lgkmcnt(7)
	v_mfma_f32_16x16x32_bf16 v[60:63], v[152:155], v[204:207], v[60:63]
	v_mfma_f32_16x16x32_bf16 v[56:59], v[156:159], v[204:207], v[56:59]
	ds_read_b128 v[168:171], v239 offset:0
	v_mfma_f32_16x16x32_bf16 v[52:55], v[160:163], v[204:207], v[52:55]
	v_mfma_f32_16x16x32_bf16 v[48:51], v[164:167], v[204:207], v[48:51]
	ds_read_b128 v[172:175], v239 offset:2048
	s_waitcnt lgkmcnt(8)
; #define MFMA16(a, b, c) __builtin_amdgcn_mfma_f32_16x16x32_bf16((a), (b), (c), 0, 0, 0)
; DI void glds16(const void* g, unsigned char* l) { __builtin_amdgcn_global_load_lds((const unsigned*)g, (lds_u32*)l, 16, 0, 0); }
; template <int N> DI void wait_vm() { asm volatile("s_waitcnt vmcnt(%0)" :: "n"(N) : "memory"); }
;     ...
;   for (int kt = 0; kt < nk; ++kt) {
;     wait_vm<0>();
;     __builtin_amdgcn_s_barrier();
;     if (kt + 1 < nk) {
;       unsigned char* sn = smem + ((kt + 1) & 1) * STG;
;       const int ko = (kt + 1) * 64;
; #pragma unroll
;       for (int i = 0; i < NA; ++i) glds16(Ab + ((size_t)i * 128 * lda + ko * 2) + voA, sn + (i * 512 + tid) * 16);
; #pragma unroll
;       for (int i = 0; i < NB; ++i) glds16(Bb + ((size_t)i * 128 * ldb + ko * 2) + voB, sn + AB + (i * 512 + tid) * 16);
;     } else if (nA) {
;       const unsigned nvoA = (unsigned)(srow * nlda + kch * 8) * 2u, nvoB = (unsigned)(srow * nldb + kch * 8) * 2u;
; #pragma unroll
;       for (int i = 0; i < NA; ++i) glds16((const char*)nA + (size_t)i * 128 * nlda + nvoA, smem + (i * 512 + tid) * 16);
; #pragma unroll
;       for (int i = 0; i < NB; ++i) glds16((const char*)nB + (size_t)i * 128 * nldb + nvoB, smem + AB + (i * 512 + tid) * 16);
;     }
;     const unsigned stb = lds_base + (kt & 1) * STG;
; #pragma unroll
;     for (int ks = 0; ks < 2; ++ks) {
;       const unsigned co = ((ks * 4 + fq) ^ sw) * 16;
;       const unsigned sa = stb + a_row + co, sb = stb + b_row + co;
;       bf16x8 af[4], bfr[NT];
; #pragma unroll
;       for (int n = 0; n < NT; ++n) asm volatile("ds_read_b128 %0, %1 offset:%2" : "=v"(bfr[n]) : "v"(sb), "n"(n * 2048) : "memory");
; #pragma unroll
;       for (int mg = 0; mg < MT / 4; ++mg) {
; #pragma unroll
;         for (int m = 0; m < 4; ++m) asm volatile("ds_read_b128 %0, %1 offset:%2" : "=v"(af[m]) : "v"(sa), "n"((mg * 4 + m) * 2048) : "memory");
;         if (mg == 0) {
; #pragma unroll
;           for (int n = 0; n < NT; ++n) asm volatile("s_waitcnt lgkmcnt(%1)" : "+v"(bfr[n]) : "n"(4 + NT - 1 - n) : "memory");
;         }
; #pragma unroll
;         for (int m = 0; m < 4; ++m) {
;           asm volatile("s_waitcnt lgkmcnt(%1)" : "+v"(af[m]) : "n"(3 - m) : "memory");
; #pragma unroll
;           for (int n = 0; n < NT; ++n) acc[mg * 4 + m][n] = MFMA16(bfr[n], af[m], acc[mg * 4 + m][n]);
;         }
;       }
;     }
	v_mfma_f32_16x16x32_bf16 v[44:47], v[152:155], v[208:211], v[44:47]
	v_add_u32_e32 v146, 0xe000, v148
	v_lshl_add_u64 v[144:145], v[144:145], 0, s[16:17]
	v_readfirstlane_b32 s15, v146
	s_mov_b32 m0, s15
	s_nop 0
	global_load_lds_dwordx4 v[144:145], off
	v_mfma_f32_16x16x32_bf16 v[40:43], v[156:159], v[208:211], v[40:43]
	ds_read_b128 v[180:183], v239 offset:4096
	v_mfma_f32_16x16x32_bf16 v[36:39], v[160:163], v[208:211], v[36:39]
	v_mfma_f32_16x16x32_bf16 v[32:35], v[164:167], v[208:211], v[32:35]
	ds_read_b128 v[184:187], v239 offset:6144
	s_waitcnt lgkmcnt(9)
	v_mfma_f32_16x16x32_bf16 v[28:31], v[152:155], v[228:231], v[28:31]
	v_mfma_f32_16x16x32_bf16 v[24:27], v[156:159], v[228:231], v[24:27]
	v_mfma_f32_16x16x32_bf16 v[20:23], v[160:163], v[228:231], v[20:23]
	v_mfma_f32_16x16x32_bf16 v[16:19], v[164:167], v[228:231], v[16:19]
	s_waitcnt lgkmcnt(8)
	v_mfma_f32_16x16x32_bf16 v[12:15], v[152:155], v[232:235], v[12:15]
	v_mfma_f32_16x16x32_bf16 v[8:11], v[156:159], v[232:235], v[8:11]
	v_mfma_f32_16x16x32_bf16 v[4:7], v[160:163], v[232:235], v[4:7]
	v_mfma_f32_16x16x32_bf16 v[0:3], v[164:167], v[232:235], v[0:3]
	s_waitcnt lgkmcnt(3)
	v_mfma_f32_16x16x32_bf16 v[124:127], v[188:191], v[168:171], v[124:127]
	v_mfma_f32_16x16x32_bf16 v[120:123], v[192:195], v[168:171], v[120:123]
	ds_read_b128 v[204:207], v239 offset:8192
	v_mfma_f32_16x16x32_bf16 v[116:119], v[196:199], v[168:171], v[116:119]
	v_mfma_f32_16x16x32_bf16 v[112:115], v[200:203], v[168:171], v[112:115]
	ds_read_b128 v[208:211], v239 offset:10240
	s_waitcnt lgkmcnt(4)
	v_mfma_f32_16x16x32_bf16 v[108:111], v[188:191], v[172:175], v[108:111]
	v_mfma_f32_16x16x32_bf16 v[104:107], v[192:195], v[172:175], v[104:107]
	ds_read_b128 v[228:231], v239 offset:12288
	v_mfma_f32_16x16x32_bf16 v[100:103], v[196:199], v[172:175], v[100:103]
	v_mfma_f32_16x16x32_bf16 v[96:99], v[200:203], v[172:175], v[96:99]
	ds_read_b128 v[232:235], v239 offset:14336
	s_waitcnt lgkmcnt(5)
	v_mfma_f32_16x16x32_bf16 v[92:95], v[188:191], v[180:183], v[92:95]
	v_mfma_f32_16x16x32_bf16 v[88:91], v[192:195], v[180:183], v[88:91]
	v_mfma_f32_16x16x32_bf16 v[84:87], v[196:199], v[180:183], v[84:87]
	v_mfma_f32_16x16x32_bf16 v[80:83], v[200:203], v[180:183], v[80:83]
	s_waitcnt lgkmcnt(4)
	v_mfma_f32_16x16x32_bf16 v[76:79], v[188:191], v[184:187], v[76:79]
	v_mfma_f32_16x16x32_bf16 v[72:75], v[192:195], v[184:187], v[72:75]
	v_mfma_f32_16x16x32_bf16 v[68:71], v[196:199], v[184:187], v[68:71]
	v_mfma_f32_16x16x32_bf16 v[64:67], v[200:203], v[184:187], v[64:67]
	s_add_u32 s42, s42, 0x80
	s_addc_u32 s43, s43, 0
	s_cmpk_eq_i32 s42, 0x780
	s_mov_b32 s14, s5
	s_cbranch_scc0 .LBB0_335
	s_waitcnt lgkmcnt(0)
	v_mfma_f32_16x16x32_bf16 v[60:63], v[188:191], v[204:207], v[60:63]
	v_mfma_f32_16x16x32_bf16 v[56:59], v[192:195], v[204:207], v[56:59]
	v_mfma_f32_16x16x32_bf16 v[52:55], v[196:199], v[204:207], v[52:55]
	v_mfma_f32_16x16x32_bf16 v[48:51], v[200:203], v[204:207], v[48:51]
	v_mfma_f32_16x16x32_bf16 v[44:47], v[188:191], v[208:211], v[44:47]
	v_mfma_f32_16x16x32_bf16 v[40:43], v[192:195], v[208:211], v[40:43]
	v_mfma_f32_16x16x32_bf16 v[36:39], v[196:199], v[208:211], v[36:39]
	v_mfma_f32_16x16x32_bf16 v[32:35], v[200:203], v[208:211], v[32:35]
	v_mfma_f32_16x16x32_bf16 v[28:31], v[188:191], v[228:231], v[28:31]
	v_mfma_f32_16x16x32_bf16 v[24:27], v[192:195], v[228:231], v[24:27]
	v_mfma_f32_16x16x32_bf16 v[20:23], v[196:199], v[228:231], v[20:23]
	v_mfma_f32_16x16x32_bf16 v[16:19], v[200:203], v[228:231], v[16:19]
	v_mfma_f32_16x16x32_bf16 v[12:15], v[188:191], v[232:235], v[12:15]
	v_mfma_f32_16x16x32_bf16 v[8:11], v[192:195], v[232:235], v[8:11]
	v_mfma_f32_16x16x32_bf16 v[4:7], v[196:199], v[232:235], v[4:7]
	v_mfma_f32_16x16x32_bf16 v[0:3], v[200:203], v[232:235], v[0:3]
	s_waitcnt vmcnt(0)
	s_andn2_b64 vcc, exec, s[12:13]
	s_barrier
	s_cbranch_vccnz .LBB0_338
	s_add_u32 s5, s54, s10
	s_addc_u32 s12, s55, s11
	s_and_b64 s[10:11], exec, s[0:1]
	s_cselect_b32 s11, 0, s12
	s_cselect_b32 s10, 0, s5
	v_readfirstlane_b32 s5, v140
	v_lshl_add_u64 v[136:137], s[10:11], 0, v[128:129]
	s_mov_b32 m0, s5
	v_lshl_add_u64 v[144:145], v[136:137], 0, s[80:81]
	v_lshl_add_u64 v[152:153], v[136:137], 0, s[82:83]
	v_lshl_add_u64 v[154:155], v[136:137], 0, s[70:71]
	global_load_lds_dwordx4 v[136:137], off
	v_add_u32_e32 v136, 0x2000, v140
	v_add_u32_e32 v156, 0x4000, v140
	v_readfirstlane_b32 s5, v136
	s_mov_b32 m0, s5
	v_readfirstlane_b32 s5, v156
	v_add_u32_e32 v136, 0x6000, v140
	s_add_u32 s12, s35, s38
	global_load_lds_dwordx4 v[154:155], off
	s_mov_b32 m0, s5
	v_readfirstlane_b32 s5, v136
	v_add_u32_e32 v136, 0x8000, v140
	s_addc_u32 s13, s27, s39
	global_load_lds_dwordx4 v[144:145], off
	s_mov_b32 m0, s5
	v_readfirstlane_b32 s5, v136
	v_add_u32_e32 v136, 0xa000, v140
	v_lshl_add_u64 v[138:139], s[12:13], 0, v[128:129]
	v_add_u32_e32 v128, 0xc000, v140
	global_load_lds_dwordx4 v[152:153], off
	s_mov_b32 m0, s5
	v_readfirstlane_b32 s5, v136
	v_lshl_add_u64 v[150:151], v[138:139], 0, s[70:71]
	global_load_lds_dwordx4 v[138:139], off
	s_mov_b32 m0, s5
	v_readfirstlane_b32 s5, v128
	v_add_u32_e32 v128, 0xe000, v140
	v_lshl_add_u64 v[146:147], v[138:139], 0, s[80:81]
	global_load_lds_dwordx4 v[150:151], off
	s_mov_b32 m0, s5
	v_readfirstlane_b32 s5, v128
	v_lshl_add_u64 v[148:149], v[138:139], 0, s[82:83]
	global_load_lds_dwordx4 v[146:147], off
	s_mov_b32 m0, s5
	s_nop 0
	global_load_lds_dwordx4 v[148:149], off

; DI float lo2f(unsigned u) { return __uint_as_float(u << 16); }
; DI float hi2f(unsigned u) { return __uint_as_float(u & 0xffff0000u); }
; DI void item_scan(const Params& p, int l, int L, int b, int h, int dir, const bf16_t* __restrict__ z, bf16_t* __restrict__ yout, float* __restrict__ bon, unsigned char* smem) {
;     ...
;     {
;       const int tt = tid >> 4, j = tid & 15, c = 4 * j;
;       u32x2 zu[5][3];
;       f32x4 mm[5][2];
; #pragma unroll
;       for (int s5 = 0; s5 < 5; ++s5) {
; #pragma unroll
;         for (int d3 = 0; d3 < 3; ++d3) zu[s5][d3] = *(const u32x2*)(ZR + (tt + d3) * 160 + s5 * 32 + 2 * j);
;         mm[s5][0] = *(const f32x4*)(MU + (s5 * 2) * 64 + c);
;         mm[s5][1] = *(const f32x4*)(MU + (s5 * 2 + 1) * 64 + c);
;       }
;       float zs[5][4];
; #pragma unroll
;       for (int s5 = 0; s5 < 5; ++s5)
; #pragma unroll
;         for (int e = 0; e < 4; ++e) {
;           const unsigned up = zu[s5][0][e >> 1], uc = zu[s5][1][e >> 1], un = zu[s5][2][e >> 1];
;           const float pv = (e & 1) ? hi2f(up) : lo2f(up), cv = (e & 1) ? hi2f(uc) : lo2f(uc), nv = (e & 1) ? hi2f(un) : lo2f(un);
;           zs[s5][e] = cv + mm[s5][0][e] * (pv - cv) + mm[s5][1][e] * (nv - cv);
;         }
;       *(f32x4*)(VR + tt * 64 + c) = (f32x4){zs[0][0], zs[0][1], zs[0][2], zs[0][3]};
;       *(f32x4*)(VK + tt * 64 + c) = (f32x4){zs[1][0], zs[1][1], zs[1][2], zs[1][3]};
;       *(f32x4*)(VV + tt * 64 + c) = (f32x4){zs[2][0], zs[2][1], zs[2][2], zs[2][3]};
.LBB0_513:
	ds_read2_b64 v[16:19], v141 offset1:16
	ds_read2_b64 v[20:23], v141 offset0:64 offset1:80
	ds_read2_b64 v[24:27], v141 offset0:160 offset1:176
	ds_read2_b64 v[28:31], v141 offset0:96 offset1:112
	ds_read_b128 v[32:35], v150 offset:45120
	ds_read_b128 v[36:39], v150 offset:45376
	ds_read2_b64 v[46:49], v141 offset0:32 offset1:48
	ds_read2_b64 v[60:63], v141 offset0:192 offset1:208
	ds_read_b128 v[90:93], v150 offset:45632
	ds_read_b128 v[94:97], v150 offset:45888
	ds_read2_b64 v[98:101], v141 offset0:128 offset1:144
	ds_read_b128 v[102:105], v150 offset:46144
	ds_read_b128 v[156:159], v150 offset:46400
	ds_read_b128 v[160:163], v150 offset:44864
	ds_read_b64 v[50:51], v141 offset:1792
	ds_read_b128 v[164:167], v150 offset:46656
	ds_read_b128 v[168:171], v150 offset:46912
	ds_read_b128 v[172:175], v150 offset:47168
	s_waitcnt lgkmcnt(14)
	v_lshlrev_b32_e32 v106, 16, v16
	v_and_b32_e32 v107, 0xffff0000, v16
	v_lshlrev_b32_e32 v176, 16, v22
	v_and_b32_e32 v177, 0xffff0000, v22
	v_lshlrev_b32_e32 v16, 16, v17
	v_and_b32_e32 v17, 0xffff0000, v17
	v_lshlrev_b32_e32 v22, 16, v23
	v_and_b32_e32 v23, 0xffff0000, v23
	v_lshlrev_b32_e32 v178, 16, v24
	v_and_b32_e32 v179, 0xffff0000, v24
	v_lshlrev_b32_e32 v24, 16, v25
	v_and_b32_e32 v25, 0xffff0000, v25
	v_pk_add_f32 v[16:17], v[16:17], v[22:23] neg_lo:[0,1] neg_hi:[0,1]
	v_pk_add_f32 v[106:107], v[106:107], v[176:177] neg_lo:[0,1] neg_hi:[0,1]
	s_waitcnt lgkmcnt(4)
	v_pk_fma_f32 v[16:17], v[162:163], v[16:17], v[22:23]
	v_pk_add_f32 v[22:23], v[24:25], v[22:23] neg_lo:[0,1] neg_hi:[0,1]
	v_lshlrev_b32_e32 v24, 16, v26
	v_pk_fma_f32 v[34:35], v[34:35], v[22:23], v[16:17]
	v_lshlrev_b32_e32 v16, 16, v18
	v_and_b32_e32 v17, 0xffff0000, v18
	v_lshlrev_b32_e32 v22, 16, v28
	v_and_b32_e32 v23, 0xffff0000, v28
	v_and_b32_e32 v25, 0xffff0000, v26
	v_pk_add_f32 v[16:17], v[16:17], v[22:23] neg_lo:[0,1] neg_hi:[0,1]
	v_lshlrev_b32_e32 v18, 16, v19
	v_pk_fma_f32 v[16:17], v[36:37], v[16:17], v[22:23]
	v_pk_add_f32 v[22:23], v[24:25], v[22:23] neg_lo:[0,1] neg_hi:[0,1]
	v_and_b32_e32 v19, 0xffff0000, v19
	v_pk_fma_f32 v[16:17], v[90:91], v[22:23], v[16:17]
	v_lshlrev_b32_e32 v22, 16, v29
	v_and_b32_e32 v23, 0xffff0000, v29
	v_lshlrev_b32_e32 v24, 16, v27
	v_and_b32_e32 v25, 0xffff0000, v27
	v_pk_add_f32 v[18:19], v[18:19], v[22:23] neg_lo:[0,1] neg_hi:[0,1]
	v_lshlrev_b32_e32 v26, 16, v60
	v_pk_fma_f32 v[18:19], v[38:39], v[18:19], v[22:23]
	v_pk_add_f32 v[22:23], v[24:25], v[22:23] neg_lo:[0,1] neg_hi:[0,1]
	v_lshlrev_b32_e32 v24, 16, v30
	v_pk_fma_f32 v[18:19], v[92:93], v[22:23], v[18:19]
	v_lshlrev_b32_e32 v22, 16, v46
	v_and_b32_e32 v23, 0xffff0000, v46
	v_and_b32_e32 v25, 0xffff0000, v30
	v_and_b32_e32 v27, 0xffff0000, v60
	v_pk_add_f32 v[22:23], v[22:23], v[24:25] neg_lo:[0,1] neg_hi:[0,1]
	v_lshlrev_b32_e32 v28, 16, v61
	v_pk_fma_f32 v[22:23], v[94:95], v[22:23], v[24:25]
	v_pk_add_f32 v[24:25], v[26:27], v[24:25] neg_lo:[0,1] neg_hi:[0,1]
	v_lshlrev_b32_e32 v26, 16, v31
	v_pk_fma_f32 v[22:23], v[102:103], v[24:25], v[22:23]
	v_lshlrev_b32_e32 v24, 16, v47
	v_and_b32_e32 v25, 0xffff0000, v47
	v_and_b32_e32 v27, 0xffff0000, v31
	v_and_b32_e32 v29, 0xffff0000, v61
	v_pk_add_f32 v[24:25], v[24:25], v[26:27] neg_lo:[0,1] neg_hi:[0,1]
	v_mov_b32_e32 v30, v156
	v_pk_fma_f32 v[24:25], v[96:97], v[24:25], v[26:27]
	v_pk_add_f32 v[26:27], v[28:29], v[26:27] neg_lo:[0,1] neg_hi:[0,1]
	v_lshlrev_b32_e32 v29, 16, v62
	v_pk_fma_f32 v[24:25], v[104:105], v[26:27], v[24:25]
	v_lshlrev_b32_e32 v26, 16, v98
	v_lshlrev_b32_e32 v28, 16, v48
	v_pk_add_f32 v[28:29], v[28:29], v[26:27] op_sel_hi:[1,0] neg_lo:[0,1] neg_hi:[0,1]
	s_waitcnt lgkmcnt(2)
	v_mov_b32_e32 v31, v164
	v_pk_mul_f32 v[28:29], v[30:31], v[28:29]
	v_mov_b32_e32 v164, v157
	v_add_f32_e32 v26, v28, v26
	v_add_f32_e32 v46, v26, v29
	v_and_b32_e32 v26, 0xffff0000, v98
	v_and_b32_e32 v29, 0xffff0000, v62
	v_and_b32_e32 v28, 0xffff0000, v48
	v_pk_add_f32 v[28:29], v[28:29], v[26:27] op_sel_hi:[1,0] neg_lo:[0,1] neg_hi:[0,1]
	v_mov_b32_e32 v30, v158
	v_pk_mul_f32 v[28:29], v[164:165], v[28:29]
	v_mov_b32_e32 v31, v166
	v_add_f32_e32 v26, v28, v26
	v_add_f32_e32 v47, v26, v29
	v_lshlrev_b32_e32 v26, 16, v99
	v_lshlrev_b32_e32 v29, 16, v63
	v_lshlrev_b32_e32 v28, 16, v49
	v_pk_add_f32 v[28:29], v[28:29], v[26:27] op_sel_hi:[1,0] neg_lo:[0,1] neg_hi:[0,1]
	v_mov_b32_e32 v166, v159
	v_pk_mul_f32 v[28:29], v[30:31], v[28:29]
	v_lshlrev_b32_e32 v30, 16, v50
	v_add_f32_e32 v26, v28, v26
	v_add_f32_e32 v48, v26, v29
	v_and_b32_e32 v26, 0xffff0000, v99
	v_and_b32_e32 v29, 0xffff0000, v63
	v_and_b32_e32 v28, 0xffff0000, v49
	v_pk_add_f32 v[28:29], v[28:29], v[26:27] op_sel_hi:[1,0] neg_lo:[0,1] neg_hi:[0,1]
	v_and_b32_e32 v27, 0xffff0000, v20
	v_pk_mul_f32 v[28:29], v[166:167], v[28:29]
	v_and_b32_e32 v31, 0xffff0000, v50
	v_add_f32_e32 v26, v28, v26
	v_add_f32_e32 v49, v26, v29
	v_lshlrev_b32_e32 v26, 16, v20
	v_lshlrev_b32_e32 v28, 16, v100
	v_and_b32_e32 v29, 0xffff0000, v100
	v_pk_add_f32 v[26:27], v[26:27], v[28:29] neg_lo:[0,1] neg_hi:[0,1]
	v_add_u32_e32 v20, v133, v132
	s_waitcnt lgkmcnt(1)
	v_pk_fma_f32 v[36:37], v[168:169], v[26:27], v[28:29]
	v_pk_add_f32 v[30:31], v[30:31], v[28:29] neg_lo:[0,1] neg_hi:[0,1]
	ds_read_b128 v[26:29], v20 offset:47424
	v_pk_fma_f32 v[106:107], v[160:161], v[106:107], v[176:177]
	v_pk_add_f32 v[160:161], v[178:179], v[176:177] neg_lo:[0,1] neg_hi:[0,1]
	s_waitcnt lgkmcnt(1)
; #define MFMA16(a, b, c) __builtin_amdgcn_mfma_f32_16x16x32_bf16((a), (b), (c), 0, 0, 0)
; DI unsigned pack2(float lo, float hi) { const f32x2 v = {lo, hi}; const bf16x2_t b = __builtin_convertvector(v, bf16x2_t); return __builtin_bit_cast(unsigned, b); }
; DI float rcp_(float x) { return __builtin_amdgcn_rcpf(x); }
; DI float sigmoidf_(float x) { return rcp_(1.0f + __expf(-x)); }
; DI void item_scan(const Params& p, int l, int L, int b, int h, int dir, const bf16_t* __restrict__ z, bf16_t* __restrict__ yout, float* __restrict__ bon, unsigned char* smem) {
;     ...
;       const f32x4 kc = *(const f32x4*)(KKC + c);
;       float kq4[4], th[4];
;       float ksum = 0.f;
; #pragma unroll
;       for (int e = 0; e < 4; ++e) {
;         kq4[e] = zs[1][e] * kc[e];
;         ksum += kq4[e] * kq4[e];
;         th[e] = 1.0f - 2.0f * rcp_(__expf(2.0f * zs[3][e]) + 1.0f);
;       }
;       *(u32x2*)(WT + tt * RS + c * 2) = (u32x2){pack2(th[0], th[1]), pack2(th[2], th[3])};
;       *(u32x2*)(AL + tt * RS + c * 2) = (u32x2){pack2(zs[4][0], zs[4][1]), pack2(zs[4][2], zs[4][3])};
;       ksum = row_sum16(ksum);
;       const float inv = rcp_(fmaxf(sqrtf(ksum), 1e-12f));
;       *(f32x4*)(VA + tt * 64 + c) = (f32x4){kq4[0] * inv, kq4[1] * inv, kq4[2] * inv, kq4[3] * inv};
;     }
;     __syncthreads();
;     {
;       f32x4 aw = {0.f, 0.f, 0.f, 0.f}, aa = {0.f, 0.f, 0.f, 0.f};
; #pragma unroll
;       for (int ks = 0; ks < 2; ++ks) {
;         const bf16x8 fw = *(const bf16x8*)(WT + fr * RS + ks * 64 + fq * 16);
;         const bf16x8 fa = *(const bf16x8*)(AL + fr * RS + ks * 64 + fq * 16);
;         aw = MFMA16(fw, bw[ks], aw);
;         aa = MFMA16(fa, ba[ks], aa);
;       }
; #pragma unroll
;       for (int j = 0; j < 4; ++j) {
;         const int tt = fq * 4 + j;
;         const float x = w0c + aw[j];
;         const float e = 0.60653065971263342f * sigmoidf_(x);
;         const float dcy = __expf(-e);
;         const float a = sigmoidf_(a0c + aa[j]);
;         const float k = VK[tt * 64 + cB], kk = VA[tt * 64 + cB];
;         VD[tt * 64 + cB] = dcy;
;         VK[tt * 64 + cB] = k * (1.0f + (a - 1.0f) * kac);
;         VA[tt * 64 + cB] = -kk;
;         VB[tt * 64 + cB] = kk * a;
;       }
;     }
;     __syncthreads();
	v_pk_fma_f32 v[30:31], v[172:173], v[30:31], v[36:37]
	v_pk_fma_f32 v[32:33], v[32:33], v[160:161], v[106:107]
	v_lshlrev_b32_e32 v20, 16, v21
	v_and_b32_e32 v21, 0xffff0000, v21
	v_lshlrev_b32_e32 v36, 16, v101
	v_and_b32_e32 v37, 0xffff0000, v101
	v_lshlrev_b32_e32 v38, 16, v51
	v_and_b32_e32 v39, 0xffff0000, v51
	v_pk_add_f32 v[20:21], v[20:21], v[36:37] neg_lo:[0,1] neg_hi:[0,1]
	ds_write_b128 v134, v[32:35] offset:11520
	ds_write_b128 v134, v[16:19] offset:19712
	ds_write_b128 v134, v[22:25] offset:23808
	s_waitcnt lgkmcnt(3)
	v_pk_mul_f32 v[16:17], v[16:17], v[26:27]
	v_pk_fma_f32 v[20:21], v[170:171], v[20:21], v[36:37]
	v_pk_add_f32 v[36:37], v[38:39], v[36:37] neg_lo:[0,1] neg_hi:[0,1]
	v_pk_mul_f32 v[26:27], v[16:17], v[16:17]
	v_pk_mul_f32 v[18:19], v[18:19], v[28:29]
	v_pk_fma_f32 v[20:21], v[174:175], v[36:37], v[20:21]
	v_add_f32_e32 v36, v46, v46
	v_add_f32_e32 v37, v47, v47
	v_add_f32_e32 v34, v48, v48
	v_add_f32_e32 v35, v49, v49
	v_pk_mul_f32 v[28:29], v[18:19], v[18:19]
	v_add_f32_e32 v26, v26, v27
	v_mul_f32_e32 v36, 0x3fb8aa3b, v36
	v_mul_f32_e32 v37, 0x3fb8aa3b, v37
	v_mul_f32_e32 v34, 0x3fb8aa3b, v34
	v_mul_f32_e32 v35, 0x3fb8aa3b, v35
	v_add_f32_e32 v26, v28, v26
	v_exp_f32_e32 v36, v36
	v_exp_f32_e32 v37, v37
	v_exp_f32_e32 v34, v34
	v_exp_f32_e32 v35, v35
	v_add_f32_e32 v26, v29, v26
	v_add_f32_e32 v32, 1.0, v36
	v_add_f32_e32 v33, 1.0, v37
	v_add_f32_dpp v26, v26, v26 quad_perm:[1,0,3,2] row_mask:0xf bank_mask:0xf bound_ctrl:1
	v_add_f32_e32 v34, 1.0, v34
	v_add_f32_e32 v35, 1.0, v35
	v_add_f32_dpp v26, v26, v26 quad_perm:[2,3,0,1] row_mask:0xf bank_mask:0xf bound_ctrl:1
	s_mov_b32 s12, 0xf800000
	v_rcp_f32_e32 v32, v32
	v_add_f32_dpp v26, v26, v26 row_half_mirror row_mask:0xf bank_mask:0xf bound_ctrl:1
	v_rcp_f32_e32 v33, v33
	v_rcp_f32_e32 v34, v34
	v_add_f32_dpp v26, v26, v26 row_mirror row_mask:0xf bank_mask:0xf bound_ctrl:1
	v_rcp_f32_e32 v35, v35
	v_mul_f32_e32 v27, 0x4f800000, v26
	v_cmp_gt_f32_e64 s[50:51], s12, v26
	v_pk_fma_f32 v[22:23], v[32:33], 2.0, 1.0 op_sel_hi:[1,0,0] neg_lo:[1,0,0] neg_hi:[1,0,0]
	v_pk_fma_f32 v[24:25], v[34:35], 2.0, 1.0 op_sel_hi:[1,0,0] neg_lo:[1,0,0] neg_hi:[1,0,0]
	v_cndmask_b32_e64 v26, v26, v27, s[50:51]
	v_sqrt_f32_e32 v27, v26
	v_cvt_pk_bf16_f32 v22, v22, v23
	v_cvt_pk_bf16_f32 v23, v24, v25
	ds_write_b64 v151, v[22:23] offset:40256
	v_add_u32_e32 v22, -1, v27
	v_fma_f32 v23, -v22, v27, v26
	v_cmp_ge_f32_e64 s[52:53], 0, v23
	v_add_u32_e32 v23, 1, v27
	v_fma_f32 v24, -v23, v27, v26
	v_cndmask_b32_e64 v22, v27, v22, s[52:53]
	v_cmp_lt_f32_e64 s[52:53], 0, v24
	v_cvt_pk_bf16_f32 v24, v30, v31
	v_cvt_pk_bf16_f32 v25, v20, v21
	v_cndmask_b32_e64 v22, v22, v23, s[52:53]
	v_mul_f32_e32 v23, 0x37800000, v22
	v_cndmask_b32_e64 v22, v22, v23, s[50:51]
	v_mov_b32_e32 v23, 0x260
	v_cmp_class_f32_e64 s[50:51], v26, v23
	ds_write_b64 v151, v[24:25] offset:42560
	s_nop 0
	v_cndmask_b32_e64 v22, v22, v26, s[50:51]
	v_max_f32_e32 v22, 0x2b8cbccc, v22
	v_rcp_f32_e32 v22, v22
	s_nop 0
	v_pk_mul_f32 v[18:19], v[18:19], v[22:23] op_sel_hi:[1,0]
	v_pk_mul_f32 v[16:17], v[16:17], v[22:23] op_sel_hi:[1,0]
	ds_write_b128 v134, v[16:19] offset:27904
	s_waitcnt lgkmcnt(0)
	s_barrier
	ds_read_b128 v[16:19], v152 offset:40256
	ds_read_b128 v[20:23], v152 offset:40320
	ds_read_b128 v[24:27], v152 offset:42560
	ds_read_b128 v[28:31], v152 offset:42624
	s_waitcnt lgkmcnt(3)
	v_mfma_f32_16x16x32_bf16 v[16:19], v[16:19], v[0:3], 0
	s_waitcnt lgkmcnt(1)
	v_mfma_f32_16x16x32_bf16 v[24:27], v[24:27], v[4:7], 0
	v_mfma_f32_16x16x32_bf16 v[16:19], v[20:23], v[8:11], v[16:19]
	s_waitcnt lgkmcnt(0)
	v_mfma_f32_16x16x32_bf16 v[20:23], v[28:31], v[12:15], v[24:27]
	s_nop 4
	ds_read2st64_b32 v[24:25], v142 offset0:77 offset1:78
	v_add_f32_e32 v16, v109, v16
	v_mul_f32_e32 v16, 0xbfb8aa3b, v16
	v_exp_f32_e32 v16, v16
	v_add_f32_e32 v20, v110, v20
	v_mul_f32_e32 v20, 0xbfb8aa3b, v20
	v_exp_f32_e32 v20, v20
	v_add_f32_e32 v16, 1.0, v16
	v_rcp_f32_e32 v16, v16
	v_add_f32_e32 v21, v110, v21
	v_add_f32_e32 v20, 1.0, v20
	v_rcp_f32_e32 v20, v20
	v_mul_f32_e32 v21, 0xbfb8aa3b, v21
	v_mul_f32_e32 v16, 0xbf1b4598, v16
	v_exp_f32_e32 v21, v21
	v_mul_f32_e32 v16, 0x3fb8aa3b, v16
	v_exp_f32_e32 v30, v16
	v_add_f32_e32 v16, -1.0, v20
	v_fma_f32 v31, v111, v16, 1.0
	v_add_f32_e32 v16, v109, v17
	v_mul_f32_e32 v16, 0xbfb8aa3b, v16
	v_add_f32_e32 v21, 1.0, v21
	v_exp_f32_e32 v32, v16
	v_rcp_f32_e32 v21, v21
	ds_read2st64_b32 v[16:17], v142 offset0:109 offset1:110
	ds_read2st64_b32 v[26:27], v142 offset0:111 offset1:112
	ds_read2st64_b32 v[28:29], v142 offset0:79 offset1:80
	v_add_f32_e32 v18, v109, v18
	v_mul_f32_e32 v18, 0xbfb8aa3b, v18
	s_waitcnt lgkmcnt(3)
	v_mul_f32_e32 v24, v24, v31
	v_add_f32_e32 v31, 1.0, v32
	s_waitcnt lgkmcnt(2)
	v_xor_b32_e32 v32, 0x80000000, v16
	v_mul_f32_e32 v16, v16, v20
	v_add_f32_e32 v20, -1.0, v21
	v_exp_f32_e32 v18, v18
	v_fma_f32 v20, v111, v20, 1.0
	v_mul_f32_e32 v20, v25, v20
	ds_write2st64_b32 v142, v24, v20 offset0:77 offset1:78
	v_xor_b32_e32 v20, 0x80000000, v17
	v_mul_f32_e32 v17, v21, v17
	ds_write2st64_b32 v142, v16, v17 offset0:125 offset1:126
	v_add_f32_e32 v16, 1.0, v18
	v_add_f32_e32 v18, v109, v19
	v_mul_f32_e32 v18, 0xbfb8aa3b, v18
	v_exp_f32_e32 v18, v18
	ds_write2st64_b32 v142, v32, v20 offset0:109 offset1:110
	v_add_f32_e32 v17, v110, v22
	v_add_f32_e32 v20, v110, v23
	v_add_f32_e32 v18, 1.0, v18
	v_rcp_f32_e32 v16, v16
	v_mul_f32_e32 v17, 0xbfb8aa3b, v17
	v_rcp_f32_e32 v18, v18
	v_mul_f32_e32 v20, 0xbfb8aa3b, v20
	v_exp_f32_e32 v17, v17
	v_exp_f32_e32 v20, v20
	v_mul_f32_e32 v16, 0xbf1b4598, v16
	v_mul_f32_e32 v18, 0xbf1b4598, v18
	v_rcp_f32_e32 v31, v31
	v_mul_f32_e32 v16, 0x3fb8aa3b, v16
	v_add_f32_e32 v17, 1.0, v17
	v_mul_f32_e32 v18, 0x3fb8aa3b, v18
	v_add_f32_e32 v20, 1.0, v20
	v_exp_f32_e32 v16, v16
	v_rcp_f32_e32 v17, v17
	v_exp_f32_e32 v18, v18
	v_rcp_f32_e32 v20, v20
	v_mul_f32_e32 v31, 0xbf1b4598, v31
	v_mul_f32_e32 v31, 0x3fb8aa3b, v31
	v_add_f32_e32 v19, -1.0, v17
	ds_write2st64_b32 v142, v16, v18 offset0:63 offset1:64
	v_add_f32_e32 v16, -1.0, v20
	v_exp_f32_e32 v31, v31
	v_fma_f32 v19, v111, v19, 1.0
	v_fma_f32 v16, v111, v16, 1.0
	s_waitcnt lgkmcnt(4)
	v_mul_f32_e32 v19, v19, v28
	v_mul_f32_e32 v16, v16, v29
	v_xor_b32_e32 v21, 0x80000000, v26
	ds_write2st64_b32 v142, v19, v16 offset0:79 offset1:80
	v_xor_b32_e32 v16, 0x80000000, v27
	v_mul_f32_e32 v17, v17, v26
	ds_write2st64_b32 v142, v21, v16 offset0:111 offset1:112
	v_mul_f32_e32 v16, v20, v27
	ds_write2st64_b32 v142, v30, v31 offset0:61 offset1:62
	ds_write2st64_b32 v142, v17, v16 offset0:127 offset1:128
	s_waitcnt lgkmcnt(0)
	s_barrier
; DI float wave_sum(float v) { return fq_sum(row_sum16(v)); }
; DI void item_scan(const Params& p, int l, int L, int b, int h, int dir, const bf16_t* __restrict__ z, bf16_t* __restrict__ yout, float* __restrict__ bon, unsigned char* smem) {
;     ...
;     float pc[4];
; #pragma unroll
;     for (int i = 0; i < 4; ++i) { const int tt = w * 4 + i; pc[i] = VR[tt * 64 + cA] * VK[tt * 64 + cA] * rkc; }
; #pragma unroll
;     for (int i = 0; i < 4; ++i) {
;       const int tt = w * 4 + i;
;       const float s = wave_sum(pc[i]);
;       if (lane == 0) BO[tt] = s;
;     }
;     ...
;       const int dstep = dir ? -64 : 64;
;       int off = (dir ? 15 * 64 : 0) + kq * 8, voff = (dir ? 15 * 64 : 0) + v0;
;       VA_ X, Y;
;       loada(X, off, voff);
; #pragma unroll 1
;       for (int it2 = 0; it2 < 8; ++it2) {
;         stepf(X, Y, off, voff, off + dstep, voff + dstep, true);
;         stepf(Y, X, off + dstep, voff + dstep, off + 2 * dstep, voff + 2 * dstep, it2 < 7);
;         off += 2 * dstep; voff += 2 * dstep;
;       }
	ds_read2st64_b32 v[20:21], v143 offset0:45 offset1:46
	ds_read2st64_b32 v[22:23], v143 offset0:77 offset1:78
	ds_read2st64_b32 v[16:17], v143 offset0:79 offset1:80
	ds_read2st64_b32 v[18:19], v143 offset0:47 offset1:48
	s_waitcnt lgkmcnt(2)
	v_mul_f32_e32 v20, v20, v22
	v_mul_f32_e32 v22, v83, v20
	s_nop 1
	v_mov_b32_dpp v22, v22 quad_perm:[1,0,3,2] row_mask:0xf bank_mask:0xf bound_ctrl:1
	v_fmac_f32_e32 v22, v83, v20
	s_nop 1
	v_add_f32_dpp v20, v22, v22 quad_perm:[2,3,0,1] row_mask:0xf bank_mask:0xf bound_ctrl:1
	s_nop 1
	v_add_f32_dpp v20, v20, v20 row_half_mirror row_mask:0xf bank_mask:0xf bound_ctrl:1
	s_nop 1
	v_add_f32_dpp v20, v20, v20 row_mirror row_mask:0xf bank_mask:0xf bound_ctrl:1
	v_mov_b32_e32 v22, v20
	s_nop 1
	v_permlane16_swap_b32_e32 v20, v22
	v_add_f32_e32 v22, v20, v22
	v_mov_b32_e32 v24, v22
	s_nop 1
	v_permlane32_swap_b32_e32 v22, v24
	v_add_u32_e32 v20, s17, v108
	s_and_saveexec_b64 s[12:13], s[46:47]
	v_add_f32_e32 v22, v22, v24
	ds_write_b32 v20, v22 offset:40192
	s_or_b64 exec, exec, s[12:13]
	v_mul_f32_e32 v21, v21, v23
	v_mul_f32_e32 v22, v83, v21
	s_nop 1
	v_mov_b32_dpp v22, v22 quad_perm:[1,0,3,2] row_mask:0xf bank_mask:0xf bound_ctrl:1
	v_fmac_f32_e32 v22, v83, v21
	s_nop 1
	v_add_f32_dpp v21, v22, v22 quad_perm:[2,3,0,1] row_mask:0xf bank_mask:0xf bound_ctrl:1
	s_nop 1
	v_add_f32_dpp v21, v21, v21 row_half_mirror row_mask:0xf bank_mask:0xf bound_ctrl:1
	s_nop 1
	v_add_f32_dpp v21, v21, v21 row_mirror row_mask:0xf bank_mask:0xf bound_ctrl:1
	v_mov_b32_e32 v22, v21
	s_nop 1
	v_permlane16_swap_b32_e32 v21, v22
	v_add_f32_e32 v21, v21, v22
	v_mov_b32_e32 v22, v21
	s_nop 1
	v_permlane32_swap_b32_e32 v21, v22
	s_and_saveexec_b64 s[12:13], s[46:47]
	v_add_f32_e32 v21, v21, v22
	ds_write_b32 v20, v21 offset:40196
	s_or_b64 exec, exec, s[12:13]
	s_waitcnt lgkmcnt(0)
	v_mul_f32_e32 v16, v18, v16
	v_mul_f32_e32 v18, v83, v16
	s_nop 1
	v_mov_b32_dpp v18, v18 quad_perm:[1,0,3,2] row_mask:0xf bank_mask:0xf bound_ctrl:1
	v_fmac_f32_e32 v18, v83, v16
	s_nop 1
	v_add_f32_dpp v16, v18, v18 quad_perm:[2,3,0,1] row_mask:0xf bank_mask:0xf bound_ctrl:1
	s_nop 1
	v_add_f32_dpp v16, v16, v16 row_half_mirror row_mask:0xf bank_mask:0xf bound_ctrl:1
	s_nop 1
	v_add_f32_dpp v16, v16, v16 row_mirror row_mask:0xf bank_mask:0xf bound_ctrl:1
	v_mov_b32_e32 v18, v16
	s_nop 1
	v_permlane16_swap_b32_e32 v16, v18
	v_add_f32_e32 v16, v16, v18
	v_mov_b32_e32 v18, v16
	s_nop 1
	v_permlane32_swap_b32_e32 v16, v18
	s_and_saveexec_b64 s[12:13], s[46:47]
	v_add_f32_e32 v16, v16, v18
	ds_write_b32 v20, v16 offset:40200
	s_or_b64 exec, exec, s[12:13]
	v_mul_f32_e32 v16, v19, v17
	v_mul_f32_e32 v17, v83, v16
	s_nop 1
	v_mov_b32_dpp v17, v17 quad_perm:[1,0,3,2] row_mask:0xf bank_mask:0xf bound_ctrl:1
	v_fmac_f32_e32 v17, v83, v16
	s_nop 1
	v_add_f32_dpp v16, v17, v17 quad_perm:[2,3,0,1] row_mask:0xf bank_mask:0xf bound_ctrl:1
	s_nop 1
	v_add_f32_dpp v16, v16, v16 row_half_mirror row_mask:0xf bank_mask:0xf bound_ctrl:1
	s_nop 1
	v_add_f32_dpp v16, v16, v16 row_mirror row_mask:0xf bank_mask:0xf bound_ctrl:1
	v_mov_b32_e32 v17, v16
	s_nop 1
	v_permlane16_swap_b32_e32 v16, v17
	v_add_f32_e32 v16, v16, v17
	v_mov_b32_e32 v17, v16
	s_nop 1
	v_permlane32_swap_b32_e32 v16, v17
	s_and_saveexec_b64 s[12:13], s[46:47]
	v_add_f32_e32 v16, v16, v17
	ds_write_b32 v20, v16 offset:40204
	s_or_b64 exec, exec, s[12:13]
	ds_read_b128 v[20:23], v138 offset:27904
	ds_read_b128 v[16:19], v138 offset:27920
	ds_read_b64 v[90:91], v139 offset:23808
	s_mov_b32 s12, 8
	s_mov_b32 s13, s17
	s_waitcnt lgkmcnt(0)
	s_branch .LBB0_523
.LBB0_523:
	v_add_u32_e32 v250, s13, v149
	s_waitcnt lgkmcnt(2)
	v_pk_mul_f32 v[248:249], v[56:57], v[22:23]
	ds_read_b128 v[168:171], v250 offset:32000
	ds_read_b128 v[172:175], v250 offset:32016
	v_pk_mul_f32 v[246:247], v[44:45], v[18:19]
	v_pk_mul_f32 v[244:245], v[42:43], v[18:19]
	v_pk_mul_f32 v[242:243], v[54:55], v[22:23]
	ds_read_b128 v[176:179], v250 offset:19712
	ds_read_b128 v[180:183], v250 offset:19728
	v_pk_fma_f32 v[240:241], v[88:89], v[20:21], v[248:249]
	v_pk_fma_f32 v[248:249], v[58:59], v[16:17], v[246:247]
	v_pk_fma_f32 v[246:247], v[40:41], v[16:17], v[244:245]
	v_pk_fma_f32 v[244:245], v[52:53], v[20:21], v[242:243]
	ds_read_b128 v[184:187], v250 offset:15616
	ds_read_b128 v[188:191], v250 offset:15632
	v_pk_add_f32 v[242:243], v[248:249], v[240:241]
	v_pk_add_f32 v[248:249], v[246:247], v[244:245]
	v_add_u32_e32 v246, s13, v148
	v_add_f32_e32 v244, v242, v243
	ds_read_b128 v[192:195], v246 offset:16384
	ds_read_b128 v[196:199], v246 offset:16400
	v_add_f32_e32 v242, v248, v249
	v_add_f32_dpp v248, v244, v244 quad_perm:[1,0,3,2] row_mask:0xf bank_mask:0xf bound_ctrl:1
	s_nop 0
	v_add_f32_dpp v244, v242, v242 quad_perm:[1,0,3,2] row_mask:0xf bank_mask:0xf bound_ctrl:1
	v_add_f32_dpp v242, v248, v248 quad_perm:[2,3,0,1] row_mask:0xf bank_mask:0xf bound_ctrl:1
	s_nop 0
	v_add_f32_dpp v248, v244, v244 quad_perm:[2,3,0,1] row_mask:0xf bank_mask:0xf bound_ctrl:1
	v_add_f32_dpp v244, v242, v242 row_half_mirror row_mask:0xf bank_mask:0xf bound_ctrl:1
	s_nop 0
	v_add_f32_dpp v242, v248, v248 row_half_mirror row_mask:0xf bank_mask:0xf bound_ctrl:1
	s_waitcnt lgkmcnt(7)
	v_pk_mul_f32 v[248:249], v[168:169], v[244:245] op_sel_hi:[1,0]
	v_pk_mul_f32 v[240:241], v[168:169], v[242:243] op_sel_hi:[1,0]
	s_waitcnt lgkmcnt(6)
	v_pk_mul_f32 v[238:239], v[174:175], v[244:245] op_sel_hi:[1,0]
	v_pk_mul_f32 v[236:237], v[174:175], v[242:243] op_sel_hi:[1,0]
	s_waitcnt lgkmcnt(5)
; DI void item_scan(const Params& p, int l, int L, int b, int h, int dir, const bf16_t* __restrict__ z, bf16_t* __restrict__ yout, float* __restrict__ bon, unsigned char* smem) {
;     ...
;       auto stepf = [&](const VA_& c, VA_& nx, int off, int voff, int offn, int voffn, bool has_next) {
;         const f32x4 D0 = *(const f32x4*)(VD + off), D1 = *(const f32x4*)(VD + off + 4);
;         const f32x4 B0 = *(const f32x4*)(VB + off), B1 = *(const f32x4*)(VB + off + 4);
;         const f32x4 K0 = *(const f32x4*)(VK + off), K1 = *(const f32x4*)(VK + off + 4);
;         const f32x4 R0 = *(const f32x4*)(VR + off), R1 = *(const f32x4*)(VR + off + 4);
;         if (has_next) loada(nx, offn, voffn);
;         const f32x2 a[4] = {{c.A0[0], c.A0[1]}, {c.A0[2], c.A0[3]}, {c.A1[0], c.A1[1]}, {c.A1[2], c.A1[3]}};
;         const f32x2 d[4] = {{D0[0], D0[1]}, {D0[2], D0[3]}, {D1[0], D1[1]}, {D1[2], D1[3]}};
;         const f32x2 bb[4] = {{B0[0], B0[1]}, {B0[2], B0[3]}, {B1[0], B1[1]}, {B1[2], B1[3]}};
;         const f32x2 kk[4] = {{K0[0], K0[1]}, {K0[2], K0[3]}, {K1[0], K1[1]}, {K1[2], K1[3]}};
;         const f32x2 rr[4] = {{R0[0], R0[1]}, {R0[2], R0[3]}, {R1[0], R1[1]}, {R1[2], R1[3]}};
;         const f32x2 p0 = (S0[0] * a[0] + S0[1] * a[1]) + (S0[2] * a[2] + S0[3] * a[3]);
;         const f32x2 p1 = (S1[0] * a[0] + S1[1] * a[1]) + (S1[2] * a[2] + S1[3] * a[3]);
;         const float sa0 = oct_sum(p0[0] + p0[1]);
;         const float sa1 = oct_sum(p1[0] + p1[1]);
;         f32x2 y0, y1;
; #pragma unroll
;         for (int i = 0; i < 4; ++i) {
;           const f32x2 n0 = S0[i] * d[i] + (sa0 * bb[i] + c.V[0] * kk[i]);
;           const f32x2 n1 = S1[i] * d[i] + (sa1 * bb[i] + c.V[1] * kk[i]);
;           S0[i] = n0; S1[i] = n1;
;           if (i == 0) { y0 = n0 * rr[0]; y1 = n1 * rr[0]; } else { y0 += n0 * rr[i]; y1 += n1 * rr[i]; }
;         }
	v_pk_fma_f32 v[234:235], v[90:91], v[176:177], v[248:249] op_sel_hi:[0,1,1]
	v_pk_fma_f32 v[248:249], v[90:91], v[176:177], v[240:241] op_sel:[1,0,0]
	v_pk_mul_f32 v[240:241], v[170:171], v[244:245] op_sel_hi:[1,0]
	v_pk_mul_f32 v[232:233], v[170:171], v[242:243] op_sel_hi:[1,0]
	v_pk_mul_f32 v[230:231], v[172:173], v[244:245] op_sel_hi:[1,0]
	v_pk_mul_f32 v[244:245], v[172:173], v[242:243] op_sel_hi:[1,0]
	s_waitcnt lgkmcnt(4)
	v_pk_fma_f32 v[242:243], v[90:91], v[182:183], v[238:239] op_sel_hi:[0,1,1]
	v_pk_fma_f32 v[238:239], v[90:91], v[182:183], v[236:237] op_sel:[1,0,0]
	s_waitcnt lgkmcnt(3)
	v_pk_fma_f32 v[236:237], v[88:89], v[184:185], v[234:235]
	v_pk_fma_f32 v[234:235], v[52:53], v[184:185], v[248:249]
	v_pk_fma_f32 v[248:249], v[90:91], v[178:179], v[240:241] op_sel_hi:[0,1,1]
	v_pk_fma_f32 v[240:241], v[90:91], v[178:179], v[232:233] op_sel:[1,0,0]
	v_pk_fma_f32 v[232:233], v[90:91], v[180:181], v[230:231] op_sel_hi:[0,1,1]
	v_pk_fma_f32 v[230:231], v[90:91], v[180:181], v[244:245] op_sel:[1,0,0]
	s_waitcnt lgkmcnt(2)
	v_pk_fma_f32 v[244:245], v[44:45], v[190:191], v[242:243]
	v_pk_fma_f32 v[242:243], v[42:43], v[190:191], v[238:239]
	ds_read_b128 v[168:171], v246 offset:20480
	v_add_u32_e32 v238, s13, v146
	v_pk_fma_f32 v[228:229], v[56:57], v[186:187], v[248:249]
	v_pk_fma_f32 v[248:249], v[54:55], v[186:187], v[240:241]
	v_pk_fma_f32 v[240:241], v[58:59], v[188:189], v[232:233]
	v_pk_fma_f32 v[232:233], v[40:41], v[188:189], v[230:231]
	s_waitcnt lgkmcnt(2)
	v_pk_mul_f32 v[230:231], v[192:193], v[236:237]
	s_waitcnt lgkmcnt(1)
	v_pk_mul_f32 v[226:227], v[198:199], v[244:245]
	v_pk_mul_f32 v[210:211], v[192:193], v[234:235]
	v_pk_mul_f32 v[208:209], v[198:199], v[242:243]
	ds_read_b64 v[206:207], v238 offset:23808
	ds_read_b128 v[172:175], v246 offset:8192
	v_pk_fma_f32 v[204:205], v[194:195], v[228:229], v[230:231]
	v_pk_fma_f32 v[230:231], v[196:197], v[240:241], v[226:227]
	v_pk_fma_f32 v[226:227], v[194:195], v[248:249], v[210:211]
	v_pk_fma_f32 v[210:211], v[196:197], v[232:233], v[208:209]
	ds_read_b128 v[176:179], v246 offset:4096
	ds_read_b128 v[180:183], v246 offset:20496
	v_pk_add_f32 v[208:209], v[230:231], v[204:205]
	v_pk_add_f32 v[230:231], v[210:211], v[226:227]
	ds_read_b128 v[184:187], v250 offset:11520
	ds_read_b128 v[188:191], v246 offset:8208
	v_add_f32_e32 v226, v208, v209
	v_add_f32_e32 v210, v230, v231
	s_nop 0
	v_add_f32_dpp v230, v226, v226 quad_perm:[1,0,3,2] row_mask:0xf bank_mask:0xf bound_ctrl:1
	v_add_f32_dpp v226, v210, v210 quad_perm:[1,0,3,2] row_mask:0xf bank_mask:0xf bound_ctrl:1
	s_nop 0
	v_add_f32_dpp v210, v230, v230 quad_perm:[2,3,0,1] row_mask:0xf bank_mask:0xf bound_ctrl:1
	v_add_f32_dpp v230, v226, v226 quad_perm:[2,3,0,1] row_mask:0xf bank_mask:0xf bound_ctrl:1
	s_nop 0
	v_add_f32_dpp v226, v210, v210 row_half_mirror row_mask:0xf bank_mask:0xf bound_ctrl:1
	v_add_f32_dpp v210, v230, v230 row_half_mirror row_mask:0xf bank_mask:0xf bound_ctrl:1
	s_waitcnt lgkmcnt(6)
	v_pk_mul_f32 v[230:231], v[170:171], v[226:227] op_sel_hi:[1,0]
	v_pk_mul_f32 v[208:209], v[170:171], v[210:211] op_sel_hi:[1,0]
	v_pk_mul_f32 v[204:205], v[168:169], v[226:227] op_sel_hi:[1,0]
	v_pk_mul_f32 v[202:203], v[168:169], v[210:211] op_sel_hi:[1,0]
	s_waitcnt lgkmcnt(4)
	v_pk_fma_f32 v[200:201], v[206:207], v[174:175], v[230:231] op_sel_hi:[0,1,1]
	v_pk_fma_f32 v[230:231], v[206:207], v[174:175], v[208:209] op_sel:[1,0,0]
	v_pk_fma_f32 v[208:209], v[206:207], v[172:173], v[204:205] op_sel_hi:[0,1,1]
	v_pk_fma_f32 v[204:205], v[206:207], v[172:173], v[202:203] op_sel:[1,0,0]
	s_waitcnt lgkmcnt(3)
	v_pk_fma_f32 v[56:57], v[228:229], v[178:179], v[200:201]
	ds_read_b128 v[168:171], v246
	v_pk_fma_f32 v[54:55], v[248:249], v[178:179], v[230:231]
	s_waitcnt lgkmcnt(3)
; DI void item_scan(const Params& p, int l, int L, int b, int h, int dir, const bf16_t* __restrict__ z, bf16_t* __restrict__ yout, float* __restrict__ bon, unsigned char* smem) {
;     ...
;         const f32x2 p0 = (S0[0] * a[0] + S0[1] * a[1]) + (S0[2] * a[2] + S0[3] * a[3]);
;         const f32x2 p1 = (S1[0] * a[0] + S1[1] * a[1]) + (S1[2] * a[2] + S1[3] * a[3]);
;         const float sa0 = oct_sum(p0[0] + p0[1]);
;         const float sa1 = oct_sum(p1[0] + p1[1]);
;         f32x2 y0, y1;
; #pragma unroll
;         for (int i = 0; i < 4; ++i) {
;           const f32x2 n0 = S0[i] * d[i] + (sa0 * bb[i] + c.V[0] * kk[i]);
;           const f32x2 n1 = S1[i] * d[i] + (sa1 * bb[i] + c.V[1] * kk[i]);
;           S0[i] = n0; S1[i] = n1;
;           if (i == 0) { y0 = n0 * rr[0]; y1 = n1 * rr[0]; } else { y0 += n0 * rr[i]; y1 += n1 * rr[i]; }
;         }
;         float ys0 = y0[0] + y0[1], ys1 = y1[0] + y1[1];
;         asm volatile("" : "+v"(ys0));
;         asm volatile("" : "+v"(ys1));
;         oct_sum_pair(ys0, ys1);
;         *(f32x2*)(YO + voff) = (f32x2){ys0, ys1};
;       };
;       const int dstep = dir ? -64 : 64;
;       int off = (dir ? 15 * 64 : 0) + kq * 8, voff = (dir ? 15 * 64 : 0) + v0;
;       VA_ X, Y;
;       loada(X, off, voff);
; #pragma unroll 1
;       for (int it2 = 0; it2 < 8; ++it2) {
;         stepf(X, Y, off, voff, off + dstep, voff + dstep, true);
;         stepf(Y, X, off + dstep, voff + dstep, off + 2 * dstep, voff + 2 * dstep, it2 < 7);
;         off += 2 * dstep; voff += 2 * dstep;
	v_pk_mul_f32 v[230:231], v[180:181], v[226:227] op_sel_hi:[1,0]
	v_pk_mul_f32 v[202:203], v[180:181], v[210:211] op_sel_hi:[1,0]
	s_waitcnt lgkmcnt(2)
	v_pk_mul_f32 v[200:201], v[186:187], v[228:229]
	v_pk_mul_f32 v[228:229], v[186:187], v[248:249]
	v_pk_fma_f32 v[88:89], v[236:237], v[176:177], v[208:209]
	v_pk_fma_f32 v[52:53], v[234:235], v[176:177], v[204:205]
	ds_read_b128 v[172:175], v246 offset:4112
	v_pk_mul_f32 v[248:249], v[182:183], v[226:227] op_sel_hi:[1,0]
	s_waitcnt lgkmcnt(2)
	v_pk_fma_f32 v[226:227], v[206:207], v[188:189], v[230:231] op_sel_hi:[0,1,1]
	v_pk_mul_f32 v[230:231], v[182:183], v[210:211] op_sel_hi:[1,0]
	ds_read_b128 v[176:179], v250 offset:11536
	ds_read_b128 v[180:183], v246 offset:16
	v_pk_fma_f32 v[250:251], v[206:207], v[188:189], v[202:203] op_sel:[1,0,0]
	v_add_u32_e32 v246, s13, v145
	s_waitcnt lgkmcnt(3)
	v_pk_mul_f32 v[210:211], v[170:171], v[56:57]
	v_pk_mul_f32 v[208:209], v[170:171], v[54:55]
	v_add_u32_e32 v204, s13, v147
	v_pk_fma_f32 v[202:203], v[184:185], v[236:237], v[200:201]
	v_pk_fma_f32 v[236:237], v[184:185], v[234:235], v[228:229]
	v_pk_fma_f32 v[234:235], v[206:207], v[190:191], v[248:249] op_sel_hi:[0,1,1]
	v_pk_fma_f32 v[248:249], v[206:207], v[190:191], v[230:231] op_sel:[1,0,0]
	v_pk_fma_f32 v[230:231], v[168:169], v[88:89], v[210:211]
	s_waitcnt lgkmcnt(2)
	v_pk_fma_f32 v[58:59], v[240:241], v[172:173], v[226:227]
	v_pk_fma_f32 v[40:41], v[232:233], v[172:173], v[250:251]
	v_pk_fma_f32 v[250:251], v[168:169], v[52:53], v[208:209]
	ds_read_b128 v[16:19], v204 offset:16
	ds_read_b128 v[20:23], v204
	ds_read_b64 v[90:91], v246
	s_waitcnt lgkmcnt(4)
	v_pk_fma_f32 v[246:247], v[176:177], v[240:241], v[202:203]
	v_pk_fma_f32 v[240:241], v[176:177], v[232:233], v[236:237]
	v_pk_fma_f32 v[44:45], v[244:245], v[174:175], v[234:235]
	v_pk_fma_f32 v[42:43], v[242:243], v[174:175], v[248:249]
	s_waitcnt lgkmcnt(3)
	v_pk_fma_f32 v[248:249], v[180:181], v[58:59], v[230:231]
	v_pk_fma_f32 v[236:237], v[180:181], v[40:41], v[250:251]
	v_pk_fma_f32 v[250:251], v[178:179], v[244:245], v[246:247]
	v_pk_fma_f32 v[246:247], v[178:179], v[242:243], v[240:241]
	v_pk_fma_f32 v[244:245], v[182:183], v[44:45], v[248:249]
	v_pk_fma_f32 v[248:249], v[182:183], v[42:43], v[236:237]
	v_add_f32_e32 v242, v250, v251
	v_add_f32_e32 v250, v246, v247
	v_add_f32_e32 v246, v244, v245
	v_add_f32_e32 v244, v248, v249
	v_add_f32_dpp v248, v242, v242 quad_perm:[1,0,3,2] row_mask:0xf bank_mask:0xf bound_ctrl:1
	v_add_f32_dpp v242, v250, v250 quad_perm:[1,0,3,2] row_mask:0xf bank_mask:0xf bound_ctrl:1
	v_add_f32_dpp v250, v246, v246 quad_perm:[1,0,3,2] row_mask:0xf bank_mask:0xf bound_ctrl:1
	v_add_f32_dpp v246, v244, v244 quad_perm:[1,0,3,2] row_mask:0xf bank_mask:0xf bound_ctrl:1
	v_add_f32_dpp v244, v248, v248 quad_perm:[2,3,0,1] row_mask:0xf bank_mask:0xf bound_ctrl:1
	v_add_f32_dpp v248, v242, v242 quad_perm:[2,3,0,1] row_mask:0xf bank_mask:0xf bound_ctrl:1
	v_add_f32_dpp v242, v250, v250 quad_perm:[2,3,0,1] row_mask:0xf bank_mask:0xf bound_ctrl:1
	v_add_f32_dpp v250, v246, v246 quad_perm:[2,3,0,1] row_mask:0xf bank_mask:0xf bound_ctrl:1
	v_add_f32_dpp v246, v244, v244 row_half_mirror row_mask:0xf bank_mask:0xf bound_ctrl:1
	v_add_f32_dpp v247, v248, v248 row_half_mirror row_mask:0xf bank_mask:0xf bound_ctrl:1
	v_add_u32_e32 v248, s13, v144
	v_add_f32_dpp v244, v242, v242 row_half_mirror row_mask:0xf bank_mask:0xf bound_ctrl:1
	v_add_f32_dpp v245, v250, v250 row_half_mirror row_mask:0xf bank_mask:0xf bound_ctrl:1
	ds_write_b64 v248, v[246:247] offset:36096
	ds_write_b64 v238, v[244:245] offset:36096
	s_add_i32 s12, s12, -1
	s_add_i32 s13, s13, s68
	s_cmp_lg_u32 s12, 0
	s_cbranch_scc1 .LBB0_523
	s_branch .LBB0_504

; DI void phase_gemm_resid(const bf16_t* __restrict__ A, int K, const bf16_t* __restrict__ Bt, const float* __restrict__ xin, float* __restrict__ xout, float alpha, unsigned char* smem) {
;     ...
; #pragma unroll
;     for (int m = 0; m < 8; ++m) {
;       const size_t row = (size_t)pm * 256 + wr * 128 + m * 16 + fr;
; #pragma unroll
;       for (int n = 0; n < 4; ++n) {
;         const size_t o = row * D + pn * 256 + wc * 64 + n * 16 + fq * 4;
;         const f32x4 x = *(const f32x4*)(xin + o);
;         *(f32x4*)(xout + o) = x + alpha * acc[m][n];
;       }
;     }
.LBB0_759:
	s_lshl_b64 s[4:5], s[4:5], 18
	s_lshl_b32 s2, s6, 8
	v_lshl_add_u64 v[138:139], s[4:5], 0, v[134:135]
	v_readlane_b32 s4, v254, 42
	s_ashr_i32 s6, s2, 31
	v_readlane_b32 s5, v254, 43
	v_mov_b32_e32 v137, s6
	v_or_b32_e32 v136, s2, v132
	v_lshl_add_u64 v[138:139], v[138:139], 2, s[4:5]
	v_lshl_add_u64 v[136:137], v[136:137], 2, v[138:139]
	global_load_dwordx4 v[168:171], v[136:137], off
	global_load_dwordx4 v[172:175], v[136:137], off offset:64
	global_load_dwordx4 v[176:179], v[136:137], off offset:128
	global_load_dwordx4 v[180:183], v[136:137], off offset:192
	s_mov_b64 s[4:5], 0x10000
	v_lshl_add_u64 v[248:249], v[136:137], 0, s[4:5]
	global_load_dwordx4 v[184:187], v[248:249], off
	global_load_dwordx4 v[188:191], v[248:249], off offset:64
	global_load_dwordx4 v[192:195], v[248:249], off offset:128
	global_load_dwordx4 v[196:199], v[248:249], off offset:192
	s_mov_b64 s[4:5], 0x20000
	v_lshl_add_u64 v[248:249], v[136:137], 0, s[4:5]
	global_load_dwordx4 v[200:203], v[248:249], off
	global_load_dwordx4 v[204:207], v[248:249], off offset:64
	global_load_dwordx4 v[208:211], v[248:249], off offset:128
	global_load_dwordx4 v[228:231], v[248:249], off offset:192
	s_mov_b64 s[4:5], 0x30000
	v_lshl_add_u64 v[248:249], v[136:137], 0, s[4:5]
	global_load_dwordx4 v[232:235], v[248:249], off
	global_load_dwordx4 v[236:239], v[248:249], off offset:64
	global_load_dwordx4 v[240:243], v[248:249], off offset:128
	global_load_dwordx4 v[244:247], v[248:249], off offset:192
	s_waitcnt vmcnt(15)
	v_pk_add_f32 v[126:127], v[126:127], v[170:171]
	v_pk_add_f32 v[124:125], v[124:125], v[168:169]
	global_store_dwordx4 v[136:137], v[124:127], off
	s_mov_b64 s[4:5], 0x40000
	v_lshl_add_u64 v[248:249], v[136:137], 0, s[4:5]
	global_load_dwordx4 v[168:171], v[248:249], off
	s_waitcnt vmcnt(16)
	v_pk_add_f32 v[122:123], v[122:123], v[174:175]
	v_pk_add_f32 v[120:121], v[120:121], v[172:173]
	global_store_dwordx4 v[136:137], v[120:123], off offset:64
	global_load_dwordx4 v[172:175], v[248:249], off offset:64
	s_waitcnt vmcnt(17)
	v_pk_add_f32 v[118:119], v[118:119], v[178:179]
	v_pk_add_f32 v[116:117], v[116:117], v[176:177]
	global_store_dwordx4 v[136:137], v[116:119], off offset:128
	global_load_dwordx4 v[176:179], v[248:249], off offset:128
	s_waitcnt vmcnt(18)
	v_pk_add_f32 v[114:115], v[114:115], v[182:183]
	v_pk_add_f32 v[112:113], v[112:113], v[180:181]
	global_store_dwordx4 v[136:137], v[112:115], off offset:192
	global_load_dwordx4 v[180:183], v[248:249], off offset:192
	s_waitcnt vmcnt(19)
	v_pk_add_f32 v[110:111], v[110:111], v[186:187]
	v_pk_add_f32 v[108:109], v[108:109], v[184:185]
	s_mov_b64 s[4:5], 0x10000
	v_lshl_add_u64 v[250:251], v[136:137], 0, s[4:5]
	global_store_dwordx4 v[250:251], v[108:111], off
	s_mov_b64 s[4:5], 0x50000
	v_lshl_add_u64 v[248:249], v[136:137], 0, s[4:5]
	global_load_dwordx4 v[184:187], v[248:249], off
	s_waitcnt vmcnt(20)
	v_pk_add_f32 v[106:107], v[106:107], v[190:191]
	v_pk_add_f32 v[104:105], v[104:105], v[188:189]
	global_store_dwordx4 v[250:251], v[104:107], off offset:64
	global_load_dwordx4 v[188:191], v[248:249], off offset:64
	s_waitcnt vmcnt(21)
	v_pk_add_f32 v[102:103], v[102:103], v[194:195]
	v_pk_add_f32 v[100:101], v[100:101], v[192:193]
	global_store_dwordx4 v[250:251], v[100:103], off offset:128
	global_load_dwordx4 v[192:195], v[248:249], off offset:128
	s_waitcnt vmcnt(22)
	v_pk_add_f32 v[98:99], v[98:99], v[198:199]
	v_pk_add_f32 v[96:97], v[96:97], v[196:197]
	global_store_dwordx4 v[250:251], v[96:99], off offset:192
	global_load_dwordx4 v[196:199], v[248:249], off offset:192
	s_waitcnt vmcnt(23)
	v_pk_add_f32 v[94:95], v[94:95], v[202:203]
	v_pk_add_f32 v[92:93], v[92:93], v[200:201]
	s_mov_b64 s[4:5], 0x20000
	v_lshl_add_u64 v[250:251], v[136:137], 0, s[4:5]
	global_store_dwordx4 v[250:251], v[92:95], off
	s_mov_b64 s[4:5], 0x60000
	v_lshl_add_u64 v[248:249], v[136:137], 0, s[4:5]
	global_load_dwordx4 v[200:203], v[248:249], off
	s_waitcnt vmcnt(24)
	v_pk_add_f32 v[90:91], v[90:91], v[206:207]
	v_pk_add_f32 v[88:89], v[88:89], v[204:205]
	global_store_dwordx4 v[250:251], v[88:91], off offset:64
	global_load_dwordx4 v[204:207], v[248:249], off offset:64
	s_waitcnt vmcnt(25)
	v_pk_add_f32 v[86:87], v[86:87], v[210:211]
	v_pk_add_f32 v[84:85], v[84:85], v[208:209]
	global_store_dwordx4 v[250:251], v[84:87], off offset:128
	global_load_dwordx4 v[208:211], v[248:249], off offset:128
	s_waitcnt vmcnt(26)
; DI void phase_gemm_resid(const bf16_t* __restrict__ A, int K, const bf16_t* __restrict__ Bt, const float* __restrict__ xin, float* __restrict__ xout, float alpha, unsigned char* smem) {
;     ...
; #pragma unroll
;     for (int m = 0; m < 8; ++m) {
;       const size_t row = (size_t)pm * 256 + wr * 128 + m * 16 + fr;
; #pragma unroll
;       for (int n = 0; n < 4; ++n) {
;         const size_t o = row * D + pn * 256 + wc * 64 + n * 16 + fq * 4;
;         const f32x4 x = *(const f32x4*)(xin + o);
;         *(f32x4*)(xout + o) = x + alpha * acc[m][n];
;       }
;     }
	v_pk_add_f32 v[82:83], v[82:83], v[230:231]
	v_pk_add_f32 v[80:81], v[80:81], v[228:229]
	global_store_dwordx4 v[250:251], v[80:83], off offset:192
	global_load_dwordx4 v[228:231], v[248:249], off offset:192
	s_waitcnt vmcnt(27)
	v_pk_add_f32 v[78:79], v[78:79], v[234:235]
	v_pk_add_f32 v[76:77], v[76:77], v[232:233]
	s_mov_b64 s[4:5], 0x30000
	v_lshl_add_u64 v[250:251], v[136:137], 0, s[4:5]
	global_store_dwordx4 v[250:251], v[76:79], off
	s_mov_b64 s[4:5], 0x70000
	v_lshl_add_u64 v[248:249], v[136:137], 0, s[4:5]
	global_load_dwordx4 v[232:235], v[248:249], off
	s_waitcnt vmcnt(28)
	v_pk_add_f32 v[74:75], v[74:75], v[238:239]
	v_pk_add_f32 v[72:73], v[72:73], v[236:237]
	global_store_dwordx4 v[250:251], v[72:75], off offset:64
	global_load_dwordx4 v[236:239], v[248:249], off offset:64
	s_waitcnt vmcnt(29)
	v_pk_add_f32 v[70:71], v[70:71], v[242:243]
	v_pk_add_f32 v[68:69], v[68:69], v[240:241]
	global_store_dwordx4 v[250:251], v[68:71], off offset:128
	global_load_dwordx4 v[240:243], v[248:249], off offset:128
	s_waitcnt vmcnt(30)
	v_pk_add_f32 v[66:67], v[66:67], v[246:247]
	v_pk_add_f32 v[64:65], v[64:65], v[244:245]
	global_store_dwordx4 v[250:251], v[64:67], off offset:192
	global_load_dwordx4 v[244:247], v[248:249], off offset:192
	s_waitcnt vmcnt(30)
	v_pk_add_f32 v[62:63], v[62:63], v[170:171]
	v_pk_add_f32 v[60:61], v[60:61], v[168:169]
	s_mov_b64 s[4:5], 0x40000
	v_lshl_add_u64 v[250:251], v[136:137], 0, s[4:5]
	global_store_dwordx4 v[250:251], v[60:63], off
	s_waitcnt vmcnt(29)
	v_pk_add_f32 v[58:59], v[58:59], v[174:175]
	v_pk_add_f32 v[56:57], v[56:57], v[172:173]
	global_store_dwordx4 v[250:251], v[56:59], off offset:64
	s_waitcnt vmcnt(28)
	v_pk_add_f32 v[54:55], v[54:55], v[178:179]
	v_pk_add_f32 v[52:53], v[52:53], v[176:177]
	global_store_dwordx4 v[250:251], v[52:55], off offset:128
	s_waitcnt vmcnt(27)
	v_pk_add_f32 v[50:51], v[50:51], v[182:183]
	v_pk_add_f32 v[48:49], v[48:49], v[180:181]
	global_store_dwordx4 v[250:251], v[48:51], off offset:192
	s_waitcnt vmcnt(26)
	v_pk_add_f32 v[46:47], v[46:47], v[186:187]
	v_pk_add_f32 v[44:45], v[44:45], v[184:185]
	s_mov_b64 s[4:5], 0x50000
	v_lshl_add_u64 v[250:251], v[136:137], 0, s[4:5]
	global_store_dwordx4 v[250:251], v[44:47], off
	s_waitcnt vmcnt(25)
	v_pk_add_f32 v[42:43], v[42:43], v[190:191]
	v_pk_add_f32 v[40:41], v[40:41], v[188:189]
	global_store_dwordx4 v[250:251], v[40:43], off offset:64
	s_waitcnt vmcnt(24)
	v_pk_add_f32 v[38:39], v[38:39], v[194:195]
	v_pk_add_f32 v[36:37], v[36:37], v[192:193]
	global_store_dwordx4 v[250:251], v[36:39], off offset:128
	s_waitcnt vmcnt(23)
	v_pk_add_f32 v[34:35], v[34:35], v[198:199]
	v_pk_add_f32 v[32:33], v[32:33], v[196:197]
	global_store_dwordx4 v[250:251], v[32:35], off offset:192
	s_waitcnt vmcnt(22)
	v_pk_add_f32 v[30:31], v[30:31], v[202:203]
	v_pk_add_f32 v[28:29], v[28:29], v[200:201]
	s_mov_b64 s[4:5], 0x60000
	v_lshl_add_u64 v[250:251], v[136:137], 0, s[4:5]
	global_store_dwordx4 v[250:251], v[28:31], off
	s_waitcnt vmcnt(21)
	v_pk_add_f32 v[26:27], v[26:27], v[206:207]
	v_pk_add_f32 v[24:25], v[24:25], v[204:205]
	global_store_dwordx4 v[250:251], v[24:27], off offset:64
	s_waitcnt vmcnt(20)
	v_pk_add_f32 v[22:23], v[22:23], v[210:211]
	v_pk_add_f32 v[20:21], v[20:21], v[208:209]
	global_store_dwordx4 v[250:251], v[20:23], off offset:128
	s_waitcnt vmcnt(19)
	v_pk_add_f32 v[18:19], v[18:19], v[230:231]
	v_pk_add_f32 v[16:17], v[16:17], v[228:229]
	global_store_dwordx4 v[250:251], v[16:19], off offset:192
	s_waitcnt vmcnt(18)
	v_pk_add_f32 v[14:15], v[14:15], v[234:235]
	v_pk_add_f32 v[12:13], v[12:13], v[232:233]
	s_mov_b64 s[4:5], 0x70000
	v_lshl_add_u64 v[250:251], v[136:137], 0, s[4:5]
	global_store_dwordx4 v[250:251], v[12:15], off
	s_waitcnt vmcnt(17)
	v_pk_add_f32 v[10:11], v[10:11], v[238:239]
	v_pk_add_f32 v[8:9], v[8:9], v[236:237]
	global_store_dwordx4 v[250:251], v[8:11], off offset:64
	s_waitcnt vmcnt(16)
	v_pk_add_f32 v[6:7], v[6:7], v[242:243]
	v_pk_add_f32 v[4:5], v[4:5], v[240:241]
	global_store_dwordx4 v[250:251], v[4:7], off offset:128
	s_waitcnt vmcnt(15)
	v_pk_add_f32 v[2:3], v[2:3], v[246:247]
	v_pk_add_f32 v[0:1], v[0:1], v[244:245]
	global_store_dwordx4 v[250:251], v[0:3], off offset:192
	s_mov_b64 s[4:5], 0x70000
	s_andn2_b64 vcc, exec, s[0:1]
	s_mov_b32 s2, s21
	s_cbranch_vccz .LBB0_772

; #define MFMA16(a, b, c) __builtin_amdgcn_mfma_f32_16x16x32_bf16((a), (b), (c), 0, 0, 0)
; DI void glds16(const void* g, unsigned char* l) { __builtin_amdgcn_global_load_lds((const unsigned*)g, (lds_u32*)l, 16, 0, 0); }
; template <int N> DI void wait_vm() { asm volatile("s_waitcnt vmcnt(%0)" :: "n"(N) : "memory"); }
;     ...
;   for (int kt = 0; kt < nk; ++kt) {
;     wait_vm<0>();
;     __builtin_amdgcn_s_barrier();
;     if (kt + 1 < nk) {
;       unsigned char* sn = smem + ((kt + 1) & 1) * STG;
;       const int ko = (kt + 1) * 64;
; #pragma unroll
;       for (int i = 0; i < NA; ++i) glds16(Ab + ((size_t)i * 128 * lda + ko * 2) + voA, sn + (i * 512 + tid) * 16);
; #pragma unroll
;       for (int i = 0; i < NB; ++i) glds16(Bb + ((size_t)i * 128 * ldb + ko * 2) + voB, sn + AB + (i * 512 + tid) * 16);
;     } else if (nA) {
;       const unsigned nvoA = (unsigned)(srow * nlda + kch * 8) * 2u, nvoB = (unsigned)(srow * nldb + kch * 8) * 2u;
; #pragma unroll
;       for (int i = 0; i < NA; ++i) glds16((const char*)nA + (size_t)i * 128 * nlda + nvoA, smem + (i * 512 + tid) * 16);
; #pragma unroll
;       for (int i = 0; i < NB; ++i) glds16((const char*)nB + (size_t)i * 128 * nldb + nvoB, smem + AB + (i * 512 + tid) * 16);
;     }
;     const unsigned stb = lds_base + (kt & 1) * STG;
; #pragma unroll
;     for (int ks = 0; ks < 2; ++ks) {
;       const unsigned co = ((ks * 4 + fq) ^ sw) * 16;
;       const unsigned sa = stb + a_row + co, sb = stb + b_row + co;
;       bf16x8 af[4], bfr[NT];
; #pragma unroll
;       for (int n = 0; n < NT; ++n) asm volatile("ds_read_b128 %0, %1 offset:%2" : "=v"(bfr[n]) : "v"(sb), "n"(n * 2048) : "memory");
; #pragma unroll
;       for (int mg = 0; mg < MT / 4; ++mg) {
; #pragma unroll
;         for (int m = 0; m < 4; ++m) asm volatile("ds_read_b128 %0, %1 offset:%2" : "=v"(af[m]) : "v"(sa), "n"((mg * 4 + m) * 2048) : "memory");
;         if (mg == 0) {
; #pragma unroll
;           for (int n = 0; n < NT; ++n) asm volatile("s_waitcnt lgkmcnt(%1)" : "+v"(bfr[n]) : "n"(4 + NT - 1 - n) : "memory");
;         }
; #pragma unroll
;         for (int m = 0; m < 4; ++m) {
;           asm volatile("s_waitcnt lgkmcnt(%1)" : "+v"(af[m]) : "n"(3 - m) : "memory");
; #pragma unroll
;           for (int n = 0; n < NT; ++n) acc[mg * 4 + m][n] = MFMA16(bfr[n], af[m], acc[mg * 4 + m][n]);
;         }
;       }
;     }
.LBB0_767:
	s_add_i32 s2, s7, 0x10000
	s_and_b32 s14, s2, 0x10000
	v_add_u32_e32 v143, s14, v133
	v_lshl_add_u64 v[144:145], v[136:137], 0, s[42:43]
	v_readfirstlane_b32 s14, v143
	v_lshl_add_u64 v[146:147], v[144:145], 0, s[96:97]
	s_mov_b32 m0, s14
	s_mov_b64 s[14:15], 0xe368080
	v_add_u32_e32 v148, 0x2000, v143
	s_waitcnt vmcnt(0)
	s_waitcnt lgkmcnt(0)
	s_barrier
	s_and_b32 s7, s7, 0x10000
	v_add_u32_e32 v240, s7, v142
	v_add_u32_e32 v236, v240, v140
	v_add_u32_e32 v237, v240, v131
	v_add_u32_e32 v240, s7, v141
	v_add_u32_e32 v238, v240, v140
	v_add_u32_e32 v239, v240, v131
	v_mfma_f32_16x16x32_bf16 v[60:63], v[188:191], v[204:207], v[60:63]
	ds_read_b128 v[152:155], v236 offset:0
	ds_read_b128 v[156:159], v236 offset:2048
	v_mfma_f32_16x16x32_bf16 v[56:59], v[192:195], v[204:207], v[56:59]
	ds_read_b128 v[160:163], v236 offset:4096
	ds_read_b128 v[164:167], v236 offset:6144
	global_load_lds_dwordx4 v[146:147], off
	v_mfma_f32_16x16x32_bf16 v[52:55], v[196:199], v[204:207], v[52:55]
	ds_read_b128 v[168:171], v238 offset:0
	ds_read_b128 v[172:175], v238 offset:2048
	v_mfma_f32_16x16x32_bf16 v[48:51], v[200:203], v[204:207], v[48:51]
	ds_read_b128 v[180:183], v238 offset:4096
	ds_read_b128 v[184:187], v238 offset:6144
	v_mfma_f32_16x16x32_bf16 v[44:47], v[188:191], v[208:211], v[44:47]
	v_mfma_f32_16x16x32_bf16 v[40:43], v[192:195], v[208:211], v[40:43]
	v_mfma_f32_16x16x32_bf16 v[36:39], v[196:199], v[208:211], v[36:39]
	v_lshl_add_u64 v[146:147], v[144:145], 0, s[14:15]
	v_readfirstlane_b32 s14, v148
	s_mov_b32 m0, s14
	s_mov_b64 s[14:15], 0xe388080
	v_add_u32_e32 v148, 0x4000, v143
	global_load_lds_dwordx4 v[146:147], off
	v_mfma_f32_16x16x32_bf16 v[32:35], v[200:203], v[208:211], v[32:35]
	v_mfma_f32_16x16x32_bf16 v[28:31], v[188:191], v[228:231], v[28:31]
	v_mfma_f32_16x16x32_bf16 v[24:27], v[192:195], v[228:231], v[24:27]
	v_mfma_f32_16x16x32_bf16 v[20:23], v[196:199], v[228:231], v[20:23]
	v_mfma_f32_16x16x32_bf16 v[16:19], v[200:203], v[228:231], v[16:19]
	v_lshl_add_u64 v[146:147], v[144:145], 0, s[14:15]
	v_readfirstlane_b32 s14, v148
	s_mov_b32 m0, s14
	s_mov_b64 s[14:15], 0xe3a8080
	global_load_lds_dwordx4 v[146:147], off
	v_mfma_f32_16x16x32_bf16 v[12:15], v[188:191], v[232:235], v[12:15]
	v_mfma_f32_16x16x32_bf16 v[8:11], v[192:195], v[232:235], v[8:11]
	v_mfma_f32_16x16x32_bf16 v[4:7], v[196:199], v[232:235], v[4:7]
	v_mfma_f32_16x16x32_bf16 v[0:3], v[200:203], v[232:235], v[0:3]
	s_waitcnt lgkmcnt(3)
	v_mfma_f32_16x16x32_bf16 v[124:127], v[152:155], v[168:171], v[124:127]
	v_add_u32_e32 v146, 0x6000, v143
	v_lshl_add_u64 v[144:145], v[144:145], 0, s[14:15]
	v_readfirstlane_b32 s14, v146
	s_mov_b32 m0, s14
	v_add_u32_e32 v148, 0x8000, v143
	global_load_lds_dwordx4 v[144:145], off
	v_mfma_f32_16x16x32_bf16 v[120:123], v[156:159], v[168:171], v[120:123]
	ds_read_b128 v[204:207], v238 offset:8192
	v_mfma_f32_16x16x32_bf16 v[116:119], v[160:163], v[168:171], v[116:119]
	v_mfma_f32_16x16x32_bf16 v[112:115], v[164:167], v[168:171], v[112:115]
	ds_read_b128 v[208:211], v238 offset:10240
	s_waitcnt lgkmcnt(4)
	v_mfma_f32_16x16x32_bf16 v[108:111], v[152:155], v[172:175], v[108:111]
	v_mfma_f32_16x16x32_bf16 v[104:107], v[156:159], v[172:175], v[104:107]
	ds_read_b128 v[228:231], v238 offset:12288
	v_lshl_add_u64 v[144:145], v[138:139], 0, s[42:43]
	s_mov_b64 s[14:15], 0x2f88080
	v_lshl_add_u64 v[146:147], v[144:145], 0, s[14:15]
	v_readfirstlane_b32 s14, v148
	s_mov_b32 m0, s14
	s_mov_b64 s[14:15], 0x2fa8080
	v_add_u32_e32 v148, 0xa000, v143
	global_load_lds_dwordx4 v[146:147], off
	v_mfma_f32_16x16x32_bf16 v[100:103], v[160:163], v[172:175], v[100:103]
	v_mfma_f32_16x16x32_bf16 v[96:99], v[164:167], v[172:175], v[96:99]
	ds_read_b128 v[232:235], v238 offset:14336
	s_waitcnt lgkmcnt(5)
	v_mfma_f32_16x16x32_bf16 v[92:95], v[152:155], v[180:183], v[92:95]
	v_mfma_f32_16x16x32_bf16 v[88:91], v[156:159], v[180:183], v[88:91]
	ds_read_b128 v[188:191], v237 offset:0
	v_mfma_f32_16x16x32_bf16 v[84:87], v[160:163], v[180:183], v[84:87]
	v_lshl_add_u64 v[146:147], v[144:145], 0, s[14:15]
	v_readfirstlane_b32 s14, v148
	s_mov_b32 m0, s14
	s_mov_b64 s[14:15], 0x2fc8080
	v_add_u32_e32 v148, 0xc000, v143
	global_load_lds_dwordx4 v[146:147], off
	v_mfma_f32_16x16x32_bf16 v[80:83], v[164:167], v[180:183], v[80:83]
	ds_read_b128 v[192:195], v237 offset:2048
	s_waitcnt lgkmcnt(6)
	v_mfma_f32_16x16x32_bf16 v[76:79], v[152:155], v[184:187], v[76:79]
	v_mfma_f32_16x16x32_bf16 v[72:75], v[156:159], v[184:187], v[72:75]
	ds_read_b128 v[196:199], v237 offset:4096
	v_mfma_f32_16x16x32_bf16 v[68:71], v[160:163], v[184:187], v[68:71]
	v_mfma_f32_16x16x32_bf16 v[64:67], v[164:167], v[184:187], v[64:67]
	ds_read_b128 v[200:203], v237 offset:6144
	v_lshl_add_u64 v[146:147], v[144:145], 0, s[14:15]
	v_readfirstlane_b32 s14, v148
	s_mov_b32 m0, s14
	s_mov_b64 s[14:15], 0x2fe8080
	v_add_u32_e32 v143, 0xe000, v143
	v_lshl_add_u64 v[144:145], v[144:145], 0, s[14:15]
	v_readfirstlane_b32 s14, v143
	global_load_lds_dwordx4 v[146:147], off
	s_waitcnt lgkmcnt(7)
	v_mfma_f32_16x16x32_bf16 v[60:63], v[152:155], v[204:207], v[60:63]
	v_mfma_f32_16x16x32_bf16 v[56:59], v[156:159], v[204:207], v[56:59]
	ds_read_b128 v[168:171], v239 offset:0
	v_mfma_f32_16x16x32_bf16 v[52:55], v[160:163], v[204:207], v[52:55]
	v_mfma_f32_16x16x32_bf16 v[48:51], v[164:167], v[204:207], v[48:51]
	ds_read_b128 v[172:175], v239 offset:2048
	s_waitcnt lgkmcnt(8)
; #define MFMA16(a, b, c) __builtin_amdgcn_mfma_f32_16x16x32_bf16((a), (b), (c), 0, 0, 0)
; DI void glds16(const void* g, unsigned char* l) { __builtin_amdgcn_global_load_lds((const unsigned*)g, (lds_u32*)l, 16, 0, 0); }
; template <int N> DI void wait_vm() { asm volatile("s_waitcnt vmcnt(%0)" :: "n"(N) : "memory"); }
;     ...
;   for (int kt = 0; kt < nk; ++kt) {
;     wait_vm<0>();
;     __builtin_amdgcn_s_barrier();
;     if (kt + 1 < nk) {
;       unsigned char* sn = smem + ((kt + 1) & 1) * STG;
;       const int ko = (kt + 1) * 64;
; #pragma unroll
;       for (int i = 0; i < NA; ++i) glds16(Ab + ((size_t)i * 128 * lda + ko * 2) + voA, sn + (i * 512 + tid) * 16);
; #pragma unroll
;       for (int i = 0; i < NB; ++i) glds16(Bb + ((size_t)i * 128 * ldb + ko * 2) + voB, sn + AB + (i * 512 + tid) * 16);
;     } else if (nA) {
;       const unsigned nvoA = (unsigned)(srow * nlda + kch * 8) * 2u, nvoB = (unsigned)(srow * nldb + kch * 8) * 2u;
; #pragma unroll
;       for (int i = 0; i < NA; ++i) glds16((const char*)nA + (size_t)i * 128 * nlda + nvoA, smem + (i * 512 + tid) * 16);
; #pragma unroll
;       for (int i = 0; i < NB; ++i) glds16((const char*)nB + (size_t)i * 128 * nldb + nvoB, smem + AB + (i * 512 + tid) * 16);
;     }
;     const unsigned stb = lds_base + (kt & 1) * STG;
; #pragma unroll
;     for (int ks = 0; ks < 2; ++ks) {
;       const unsigned co = ((ks * 4 + fq) ^ sw) * 16;
;       const unsigned sa = stb + a_row + co, sb = stb + b_row + co;
;       bf16x8 af[4], bfr[NT];
; #pragma unroll
;       for (int n = 0; n < NT; ++n) asm volatile("ds_read_b128 %0, %1 offset:%2" : "=v"(bfr[n]) : "v"(sb), "n"(n * 2048) : "memory");
; #pragma unroll
;       for (int mg = 0; mg < MT / 4; ++mg) {
; #pragma unroll
;         for (int m = 0; m < 4; ++m) asm volatile("ds_read_b128 %0, %1 offset:%2" : "=v"(af[m]) : "v"(sa), "n"((mg * 4 + m) * 2048) : "memory");
;         if (mg == 0) {
; #pragma unroll
;           for (int n = 0; n < NT; ++n) asm volatile("s_waitcnt lgkmcnt(%1)" : "+v"(bfr[n]) : "n"(4 + NT - 1 - n) : "memory");
;         }
; #pragma unroll
;         for (int m = 0; m < 4; ++m) {
;           asm volatile("s_waitcnt lgkmcnt(%1)" : "+v"(af[m]) : "n"(3 - m) : "memory");
; #pragma unroll
;           for (int n = 0; n < NT; ++n) acc[mg * 4 + m][n] = MFMA16(bfr[n], af[m], acc[mg * 4 + m][n]);
;         }
;       }
;     }
	v_mfma_f32_16x16x32_bf16 v[44:47], v[152:155], v[208:211], v[44:47]
	s_mov_b32 m0, s14
	s_nop 0
	global_load_lds_dwordx4 v[144:145], off
	v_mfma_f32_16x16x32_bf16 v[40:43], v[156:159], v[208:211], v[40:43]
	ds_read_b128 v[180:183], v239 offset:4096
	v_mfma_f32_16x16x32_bf16 v[36:39], v[160:163], v[208:211], v[36:39]
	v_mfma_f32_16x16x32_bf16 v[32:35], v[164:167], v[208:211], v[32:35]
	ds_read_b128 v[184:187], v239 offset:6144
	s_waitcnt lgkmcnt(9)
	v_mfma_f32_16x16x32_bf16 v[28:31], v[152:155], v[228:231], v[28:31]
	v_mfma_f32_16x16x32_bf16 v[24:27], v[156:159], v[228:231], v[24:27]
	v_mfma_f32_16x16x32_bf16 v[20:23], v[160:163], v[228:231], v[20:23]
	v_mfma_f32_16x16x32_bf16 v[16:19], v[164:167], v[228:231], v[16:19]
	s_waitcnt lgkmcnt(8)
	v_mfma_f32_16x16x32_bf16 v[12:15], v[152:155], v[232:235], v[12:15]
	v_mfma_f32_16x16x32_bf16 v[8:11], v[156:159], v[232:235], v[8:11]
	v_mfma_f32_16x16x32_bf16 v[4:7], v[160:163], v[232:235], v[4:7]
	v_mfma_f32_16x16x32_bf16 v[0:3], v[164:167], v[232:235], v[0:3]
	s_waitcnt lgkmcnt(3)
	v_mfma_f32_16x16x32_bf16 v[124:127], v[188:191], v[168:171], v[124:127]
	v_mfma_f32_16x16x32_bf16 v[120:123], v[192:195], v[168:171], v[120:123]
	ds_read_b128 v[204:207], v239 offset:8192
	v_mfma_f32_16x16x32_bf16 v[116:119], v[196:199], v[168:171], v[116:119]
	v_mfma_f32_16x16x32_bf16 v[112:115], v[200:203], v[168:171], v[112:115]
	ds_read_b128 v[208:211], v239 offset:10240
	s_waitcnt lgkmcnt(4)
	v_mfma_f32_16x16x32_bf16 v[108:111], v[188:191], v[172:175], v[108:111]
	v_mfma_f32_16x16x32_bf16 v[104:107], v[192:195], v[172:175], v[104:107]
	ds_read_b128 v[228:231], v239 offset:12288
	v_mfma_f32_16x16x32_bf16 v[100:103], v[196:199], v[172:175], v[100:103]
	v_mfma_f32_16x16x32_bf16 v[96:99], v[200:203], v[172:175], v[96:99]
	ds_read_b128 v[232:235], v239 offset:14336
	s_waitcnt lgkmcnt(5)
	v_mfma_f32_16x16x32_bf16 v[92:95], v[188:191], v[180:183], v[92:95]
	v_mfma_f32_16x16x32_bf16 v[88:91], v[192:195], v[180:183], v[88:91]
	v_mfma_f32_16x16x32_bf16 v[84:87], v[196:199], v[180:183], v[84:87]
	v_mfma_f32_16x16x32_bf16 v[80:83], v[200:203], v[180:183], v[80:83]
	s_waitcnt lgkmcnt(4)
	v_mfma_f32_16x16x32_bf16 v[76:79], v[188:191], v[184:187], v[76:79]
	v_mfma_f32_16x16x32_bf16 v[72:75], v[192:195], v[184:187], v[72:75]
	v_mfma_f32_16x16x32_bf16 v[68:71], v[196:199], v[184:187], v[68:71]
	v_mfma_f32_16x16x32_bf16 v[64:67], v[200:203], v[184:187], v[64:67]
	s_add_u32 s42, s42, 0x80
	s_addc_u32 s43, s43, 0
	s_cmpk_eq_i32 s42, 0x780
	s_mov_b32 s7, s2
	s_cbranch_scc0 .LBB0_767
	s_waitcnt lgkmcnt(0)
	v_mfma_f32_16x16x32_bf16 v[60:63], v[188:191], v[204:207], v[60:63]
	v_mfma_f32_16x16x32_bf16 v[56:59], v[192:195], v[204:207], v[56:59]
	v_mfma_f32_16x16x32_bf16 v[52:55], v[196:199], v[204:207], v[52:55]
	v_mfma_f32_16x16x32_bf16 v[48:51], v[200:203], v[204:207], v[48:51]
	v_mfma_f32_16x16x32_bf16 v[44:47], v[188:191], v[208:211], v[44:47]
	v_mfma_f32_16x16x32_bf16 v[40:43], v[192:195], v[208:211], v[40:43]
	v_mfma_f32_16x16x32_bf16 v[36:39], v[196:199], v[208:211], v[36:39]
	v_mfma_f32_16x16x32_bf16 v[32:35], v[200:203], v[208:211], v[32:35]
	v_mfma_f32_16x16x32_bf16 v[28:31], v[188:191], v[228:231], v[28:31]
	v_mfma_f32_16x16x32_bf16 v[24:27], v[192:195], v[228:231], v[24:27]
	v_mfma_f32_16x16x32_bf16 v[20:23], v[196:199], v[228:231], v[20:23]
	v_mfma_f32_16x16x32_bf16 v[16:19], v[200:203], v[228:231], v[16:19]
	v_mfma_f32_16x16x32_bf16 v[12:15], v[188:191], v[232:235], v[12:15]
	v_mfma_f32_16x16x32_bf16 v[8:11], v[192:195], v[232:235], v[8:11]
	v_mfma_f32_16x16x32_bf16 v[4:7], v[196:199], v[232:235], v[4:7]
	v_mfma_f32_16x16x32_bf16 v[0:3], v[200:203], v[232:235], v[0:3]
	s_waitcnt vmcnt(0)
	s_andn2_b64 vcc, exec, s[12:13]
	s_barrier
	v_readlane_b32 s41, v254, 60
	s_cbranch_vccnz .LBB0_770
	s_lshl_b64 s[10:11], s[10:11], 1
	s_add_u32 s2, s52, s10
	s_addc_u32 s7, s53, s11
	s_and_b64 s[10:11], exec, s[0:1]
	s_cselect_b32 s11, 0, s7
	s_cselect_b32 s10, 0, s2
	v_readfirstlane_b32 s2, v133
	v_lshl_add_u64 v[136:137], s[10:11], 0, v[128:129]
	s_mov_b32 m0, s2
	v_lshl_add_u64 v[144:145], v[136:137], 0, s[80:81]
	v_lshl_add_u64 v[152:153], v[136:137], 0, s[82:83]
	v_lshl_add_u64 v[154:155], v[136:137], 0, s[70:71]
	global_load_lds_dwordx4 v[136:137], off
	v_add_u32_e32 v136, 0x2000, v133
	v_add_u32_e32 v143, 0x4000, v133
	v_readfirstlane_b32 s2, v136
	s_lshl_b64 s[12:13], s[38:39], 1
	s_mov_b32 m0, s2
	v_readfirstlane_b32 s2, v143
	v_add_u32_e32 v136, 0x6000, v133
	s_add_u32 s12, s8, s12
	global_load_lds_dwordx4 v[154:155], off
	s_mov_b32 m0, s2
	v_readfirstlane_b32 s2, v136
	v_add_u32_e32 v136, 0x8000, v133
	s_addc_u32 s13, s18, s13
	global_load_lds_dwordx4 v[144:145], off
	s_mov_b32 m0, s2
	v_readfirstlane_b32 s2, v136
	v_add_u32_e32 v136, 0xa000, v133
	v_lshl_add_u64 v[138:139], s[12:13], 0, v[128:129]
	v_add_u32_e32 v128, 0xc000, v133
	global_load_lds_dwordx4 v[152:153], off
	s_mov_b32 m0, s2
	v_readfirstlane_b32 s2, v136
	v_lshl_add_u64 v[150:151], v[138:139], 0, s[70:71]
	global_load_lds_dwordx4 v[138:139], off
	s_mov_b32 m0, s2
	v_readfirstlane_b32 s2, v128
	v_add_u32_e32 v128, 0xe000, v133
	v_lshl_add_u64 v[146:147], v[138:139], 0, s[80:81]
	global_load_lds_dwordx4 v[150:151], off
	s_mov_b32 m0, s2
	v_readfirstlane_b32 s2, v128
	v_lshl_add_u64 v[148:149], v[138:139], 0, s[82:83]
	global_load_lds_dwordx4 v[146:147], off
	s_mov_b32 m0, s2
	s_nop 0
	global_load_lds_dwordx4 v[148:149], off

; #define MFMA16(a, b, c) __builtin_amdgcn_mfma_f32_16x16x32_bf16((a), (b), (c), 0, 0, 0)
; DI void glds16(const void* g, unsigned char* l) { __builtin_amdgcn_global_load_lds((const unsigned*)g, (lds_u32*)l, 16, 0, 0); }
; template <int N> DI void wait_vm() { asm volatile("s_waitcnt vmcnt(%0)" :: "n"(N) : "memory"); }
;     ...
;   for (int kt = 0; kt < nk; ++kt) {
;     wait_vm<0>();
;     __builtin_amdgcn_s_barrier();
;     if (kt + 1 < nk) {
;       unsigned char* sn = smem + ((kt + 1) & 1) * STG;
;       const int ko = (kt + 1) * 64;
; #pragma unroll
;       for (int i = 0; i < NA; ++i) glds16(Ab + ((size_t)i * 128 * lda + ko * 2) + voA, sn + (i * 512 + tid) * 16);
; #pragma unroll
;       for (int i = 0; i < NB; ++i) glds16(Bb + ((size_t)i * 128 * ldb + ko * 2) + voB, sn + AB + (i * 512 + tid) * 16);
;     } else if (nA) {
;       const unsigned nvoA = (unsigned)(srow * nlda + kch * 8) * 2u, nvoB = (unsigned)(srow * nldb + kch * 8) * 2u;
; #pragma unroll
;       for (int i = 0; i < NA; ++i) glds16((const char*)nA + (size_t)i * 128 * nlda + nvoA, smem + (i * 512 + tid) * 16);
; #pragma unroll
;       for (int i = 0; i < NB; ++i) glds16((const char*)nB + (size_t)i * 128 * nldb + nvoB, smem + AB + (i * 512 + tid) * 16);
;     }
;     const unsigned stb = lds_base + (kt & 1) * STG;
; #pragma unroll
;     for (int ks = 0; ks < 2; ++ks) {
;       const unsigned co = ((ks * 4 + fq) ^ sw) * 16;
;       const unsigned sa = stb + a_row + co, sb = stb + b_row + co;
;       bf16x8 af[4], bfr[NT];
; #pragma unroll
;       for (int n = 0; n < NT; ++n) asm volatile("ds_read_b128 %0, %1 offset:%2" : "=v"(bfr[n]) : "v"(sb), "n"(n * 2048) : "memory");
; #pragma unroll
;       for (int mg = 0; mg < MT / 4; ++mg) {
; #pragma unroll
;         for (int m = 0; m < 4; ++m) asm volatile("ds_read_b128 %0, %1 offset:%2" : "=v"(af[m]) : "v"(sa), "n"((mg * 4 + m) * 2048) : "memory");
;         if (mg == 0) {
; #pragma unroll
;           for (int n = 0; n < NT; ++n) asm volatile("s_waitcnt lgkmcnt(%1)" : "+v"(bfr[n]) : "n"(4 + NT - 1 - n) : "memory");
;         }
; #pragma unroll
;         for (int m = 0; m < 4; ++m) {
;           asm volatile("s_waitcnt lgkmcnt(%1)" : "+v"(af[m]) : "n"(3 - m) : "memory");
; #pragma unroll
;           for (int n = 0; n < NT; ++n) acc[mg * 4 + m][n] = MFMA16(bfr[n], af[m], acc[mg * 4 + m][n]);
;         }
;       }
;     }
.LBB0_899:
	s_add_i32 s2, s7, 0x10000
	s_and_b32 s14, s2, 0x10000
	v_add_u32_e32 v143, s14, v139
	v_lshl_add_u64 v[144:145], v[134:135], 0, s[42:43]
	v_readfirstlane_b32 s14, v143
	v_add_u32_e32 v148, 0x2000, v143
	v_lshl_add_u64 v[146:147], v[144:145], 0, s[58:59]
	s_mov_b32 m0, s14
	v_readfirstlane_b32 s14, v148
	v_add_u32_e32 v148, 0x4000, v143
	s_waitcnt vmcnt(0)
	s_waitcnt lgkmcnt(0)
	s_barrier
	s_and_b32 s7, s7, 0x10000
	v_add_u32_e32 v240, s7, v142
	v_add_u32_e32 v236, v240, v140
	v_add_u32_e32 v237, v240, v138
	v_add_u32_e32 v240, s7, v141
	v_add_u32_e32 v238, v240, v140
	v_add_u32_e32 v239, v240, v138
	v_mfma_f32_16x16x32_bf16 v[60:63], v[188:191], v[204:207], v[60:63]
	ds_read_b128 v[152:155], v236 offset:0
	ds_read_b128 v[156:159], v236 offset:2048
	v_mfma_f32_16x16x32_bf16 v[56:59], v[192:195], v[204:207], v[56:59]
	ds_read_b128 v[160:163], v236 offset:4096
	ds_read_b128 v[164:167], v236 offset:6144
	global_load_lds_dwordx4 v[146:147], off
	v_mfma_f32_16x16x32_bf16 v[52:55], v[196:199], v[204:207], v[52:55]
	ds_read_b128 v[168:171], v238 offset:0
	ds_read_b128 v[172:175], v238 offset:2048
	v_mfma_f32_16x16x32_bf16 v[48:51], v[200:203], v[204:207], v[48:51]
	ds_read_b128 v[180:183], v238 offset:4096
	ds_read_b128 v[184:187], v238 offset:6144
	v_mfma_f32_16x16x32_bf16 v[44:47], v[188:191], v[208:211], v[44:47]
	v_mfma_f32_16x16x32_bf16 v[40:43], v[192:195], v[208:211], v[40:43]
	v_mfma_f32_16x16x32_bf16 v[36:39], v[196:199], v[208:211], v[36:39]
	v_lshl_add_u64 v[146:147], v[144:145], 0, s[60:61]
	s_mov_b32 m0, s14
	v_readfirstlane_b32 s14, v148
	global_load_lds_dwordx4 v[146:147], off
	v_mfma_f32_16x16x32_bf16 v[32:35], v[200:203], v[208:211], v[32:35]
	v_mfma_f32_16x16x32_bf16 v[28:31], v[188:191], v[228:231], v[28:31]
	v_mfma_f32_16x16x32_bf16 v[24:27], v[192:195], v[228:231], v[24:27]
	v_mfma_f32_16x16x32_bf16 v[20:23], v[196:199], v[228:231], v[20:23]
	v_mfma_f32_16x16x32_bf16 v[16:19], v[200:203], v[228:231], v[16:19]
	v_lshl_add_u64 v[146:147], v[144:145], 0, s[62:63]
	s_mov_b32 m0, s14
	v_lshl_add_u64 v[144:145], v[144:145], 0, s[64:65]
	global_load_lds_dwordx4 v[146:147], off
	v_mfma_f32_16x16x32_bf16 v[12:15], v[188:191], v[232:235], v[12:15]
	v_mfma_f32_16x16x32_bf16 v[8:11], v[192:195], v[232:235], v[8:11]
	v_mfma_f32_16x16x32_bf16 v[4:7], v[196:199], v[232:235], v[4:7]
	v_mfma_f32_16x16x32_bf16 v[0:3], v[200:203], v[232:235], v[0:3]
	s_waitcnt lgkmcnt(3)
	v_mfma_f32_16x16x32_bf16 v[124:127], v[152:155], v[168:171], v[124:127]
	v_add_u32_e32 v146, 0x6000, v143
	v_add_u32_e32 v148, 0x8000, v143
	v_readfirstlane_b32 s14, v146
	s_mov_b32 m0, s14
	s_mov_b64 s[14:15], 0x1088080
	global_load_lds_dwordx4 v[144:145], off
	v_mfma_f32_16x16x32_bf16 v[120:123], v[156:159], v[168:171], v[120:123]
	ds_read_b128 v[204:207], v238 offset:8192
	v_mfma_f32_16x16x32_bf16 v[116:119], v[160:163], v[168:171], v[116:119]
	v_mfma_f32_16x16x32_bf16 v[112:115], v[164:167], v[168:171], v[112:115]
	ds_read_b128 v[208:211], v238 offset:10240
	s_waitcnt lgkmcnt(4)
	v_mfma_f32_16x16x32_bf16 v[108:111], v[152:155], v[172:175], v[108:111]
	v_mfma_f32_16x16x32_bf16 v[104:107], v[156:159], v[172:175], v[104:107]
	ds_read_b128 v[228:231], v238 offset:12288
	v_lshl_add_u64 v[144:145], v[136:137], 0, s[42:43]
	v_lshl_add_u64 v[146:147], v[144:145], 0, s[14:15]
	v_readfirstlane_b32 s14, v148
	s_mov_b32 m0, s14
	s_mov_b64 s[14:15], 0x10a8080
	v_add_u32_e32 v148, 0xa000, v143
	global_load_lds_dwordx4 v[146:147], off
	v_mfma_f32_16x16x32_bf16 v[100:103], v[160:163], v[172:175], v[100:103]
	v_mfma_f32_16x16x32_bf16 v[96:99], v[164:167], v[172:175], v[96:99]
	ds_read_b128 v[232:235], v238 offset:14336
	s_waitcnt lgkmcnt(5)
	v_mfma_f32_16x16x32_bf16 v[92:95], v[152:155], v[180:183], v[92:95]
	v_mfma_f32_16x16x32_bf16 v[88:91], v[156:159], v[180:183], v[88:91]
	ds_read_b128 v[188:191], v237 offset:0
	v_mfma_f32_16x16x32_bf16 v[84:87], v[160:163], v[180:183], v[84:87]
	v_lshl_add_u64 v[146:147], v[144:145], 0, s[14:15]
	v_readfirstlane_b32 s14, v148
	s_mov_b32 m0, s14
	s_mov_b64 s[14:15], 0x10c8080
	v_add_u32_e32 v148, 0xc000, v143
	global_load_lds_dwordx4 v[146:147], off
	v_mfma_f32_16x16x32_bf16 v[80:83], v[164:167], v[180:183], v[80:83]
	ds_read_b128 v[192:195], v237 offset:2048
	s_waitcnt lgkmcnt(6)
	v_mfma_f32_16x16x32_bf16 v[76:79], v[152:155], v[184:187], v[76:79]
	v_mfma_f32_16x16x32_bf16 v[72:75], v[156:159], v[184:187], v[72:75]
	ds_read_b128 v[196:199], v237 offset:4096
	v_mfma_f32_16x16x32_bf16 v[68:71], v[160:163], v[184:187], v[68:71]
	v_mfma_f32_16x16x32_bf16 v[64:67], v[164:167], v[184:187], v[64:67]
	ds_read_b128 v[200:203], v237 offset:6144
	v_lshl_add_u64 v[146:147], v[144:145], 0, s[14:15]
	v_readfirstlane_b32 s14, v148
	s_mov_b32 m0, s14
	s_mov_b64 s[14:15], 0x10e8080
	v_add_u32_e32 v143, 0xe000, v143
	v_lshl_add_u64 v[144:145], v[144:145], 0, s[14:15]
	v_readfirstlane_b32 s14, v143
	global_load_lds_dwordx4 v[146:147], off
	s_waitcnt lgkmcnt(7)
	v_mfma_f32_16x16x32_bf16 v[60:63], v[152:155], v[204:207], v[60:63]
	v_mfma_f32_16x16x32_bf16 v[56:59], v[156:159], v[204:207], v[56:59]
	ds_read_b128 v[168:171], v239 offset:0
	v_mfma_f32_16x16x32_bf16 v[52:55], v[160:163], v[204:207], v[52:55]
	v_mfma_f32_16x16x32_bf16 v[48:51], v[164:167], v[204:207], v[48:51]
	ds_read_b128 v[172:175], v239 offset:2048
	s_waitcnt lgkmcnt(8)
; #define MFMA16(a, b, c) __builtin_amdgcn_mfma_f32_16x16x32_bf16((a), (b), (c), 0, 0, 0)
; DI void glds16(const void* g, unsigned char* l) { __builtin_amdgcn_global_load_lds((const unsigned*)g, (lds_u32*)l, 16, 0, 0); }
; template <int N> DI void wait_vm() { asm volatile("s_waitcnt vmcnt(%0)" :: "n"(N) : "memory"); }
;     ...
;   for (int kt = 0; kt < nk; ++kt) {
;     wait_vm<0>();
;     __builtin_amdgcn_s_barrier();
;     if (kt + 1 < nk) {
;       unsigned char* sn = smem + ((kt + 1) & 1) * STG;
;       const int ko = (kt + 1) * 64;
; #pragma unroll
;       for (int i = 0; i < NA; ++i) glds16(Ab + ((size_t)i * 128 * lda + ko * 2) + voA, sn + (i * 512 + tid) * 16);
; #pragma unroll
;       for (int i = 0; i < NB; ++i) glds16(Bb + ((size_t)i * 128 * ldb + ko * 2) + voB, sn + AB + (i * 512 + tid) * 16);
;     } else if (nA) {
;       const unsigned nvoA = (unsigned)(srow * nlda + kch * 8) * 2u, nvoB = (unsigned)(srow * nldb + kch * 8) * 2u;
; #pragma unroll
;       for (int i = 0; i < NA; ++i) glds16((const char*)nA + (size_t)i * 128 * nlda + nvoA, smem + (i * 512 + tid) * 16);
; #pragma unroll
;       for (int i = 0; i < NB; ++i) glds16((const char*)nB + (size_t)i * 128 * nldb + nvoB, smem + AB + (i * 512 + tid) * 16);
;     }
;     const unsigned stb = lds_base + (kt & 1) * STG;
; #pragma unroll
;     for (int ks = 0; ks < 2; ++ks) {
;       const unsigned co = ((ks * 4 + fq) ^ sw) * 16;
;       const unsigned sa = stb + a_row + co, sb = stb + b_row + co;
;       bf16x8 af[4], bfr[NT];
; #pragma unroll
;       for (int n = 0; n < NT; ++n) asm volatile("ds_read_b128 %0, %1 offset:%2" : "=v"(bfr[n]) : "v"(sb), "n"(n * 2048) : "memory");
; #pragma unroll
;       for (int mg = 0; mg < MT / 4; ++mg) {
; #pragma unroll
;         for (int m = 0; m < 4; ++m) asm volatile("ds_read_b128 %0, %1 offset:%2" : "=v"(af[m]) : "v"(sa), "n"((mg * 4 + m) * 2048) : "memory");
;         if (mg == 0) {
; #pragma unroll
;           for (int n = 0; n < NT; ++n) asm volatile("s_waitcnt lgkmcnt(%1)" : "+v"(bfr[n]) : "n"(4 + NT - 1 - n) : "memory");
;         }
; #pragma unroll
;         for (int m = 0; m < 4; ++m) {
;           asm volatile("s_waitcnt lgkmcnt(%1)" : "+v"(af[m]) : "n"(3 - m) : "memory");
; #pragma unroll
;           for (int n = 0; n < NT; ++n) acc[mg * 4 + m][n] = MFMA16(bfr[n], af[m], acc[mg * 4 + m][n]);
;         }
;       }
;     }
	v_mfma_f32_16x16x32_bf16 v[44:47], v[152:155], v[208:211], v[44:47]
	s_mov_b32 m0, s14
	s_nop 0
	global_load_lds_dwordx4 v[144:145], off
	v_mfma_f32_16x16x32_bf16 v[40:43], v[156:159], v[208:211], v[40:43]
	ds_read_b128 v[180:183], v239 offset:4096
	v_mfma_f32_16x16x32_bf16 v[36:39], v[160:163], v[208:211], v[36:39]
	v_mfma_f32_16x16x32_bf16 v[32:35], v[164:167], v[208:211], v[32:35]
	ds_read_b128 v[184:187], v239 offset:6144
	s_waitcnt lgkmcnt(9)
	v_mfma_f32_16x16x32_bf16 v[28:31], v[152:155], v[228:231], v[28:31]
	v_mfma_f32_16x16x32_bf16 v[24:27], v[156:159], v[228:231], v[24:27]
	v_mfma_f32_16x16x32_bf16 v[20:23], v[160:163], v[228:231], v[20:23]
	v_mfma_f32_16x16x32_bf16 v[16:19], v[164:167], v[228:231], v[16:19]
	s_waitcnt lgkmcnt(8)
	v_mfma_f32_16x16x32_bf16 v[12:15], v[152:155], v[232:235], v[12:15]
	v_mfma_f32_16x16x32_bf16 v[8:11], v[156:159], v[232:235], v[8:11]
	v_mfma_f32_16x16x32_bf16 v[4:7], v[160:163], v[232:235], v[4:7]
	v_mfma_f32_16x16x32_bf16 v[0:3], v[164:167], v[232:235], v[0:3]
	s_waitcnt lgkmcnt(3)
	v_mfma_f32_16x16x32_bf16 v[124:127], v[188:191], v[168:171], v[124:127]
	v_mfma_f32_16x16x32_bf16 v[120:123], v[192:195], v[168:171], v[120:123]
	ds_read_b128 v[204:207], v239 offset:8192
	v_mfma_f32_16x16x32_bf16 v[116:119], v[196:199], v[168:171], v[116:119]
	v_mfma_f32_16x16x32_bf16 v[112:115], v[200:203], v[168:171], v[112:115]
	ds_read_b128 v[208:211], v239 offset:10240
	s_waitcnt lgkmcnt(4)
	v_mfma_f32_16x16x32_bf16 v[108:111], v[188:191], v[172:175], v[108:111]
	v_mfma_f32_16x16x32_bf16 v[104:107], v[192:195], v[172:175], v[104:107]
	ds_read_b128 v[228:231], v239 offset:12288
	v_mfma_f32_16x16x32_bf16 v[100:103], v[196:199], v[172:175], v[100:103]
	v_mfma_f32_16x16x32_bf16 v[96:99], v[200:203], v[172:175], v[96:99]
	ds_read_b128 v[232:235], v239 offset:14336
	s_waitcnt lgkmcnt(5)
	v_mfma_f32_16x16x32_bf16 v[92:95], v[188:191], v[180:183], v[92:95]
	v_mfma_f32_16x16x32_bf16 v[88:91], v[192:195], v[180:183], v[88:91]
	v_mfma_f32_16x16x32_bf16 v[84:87], v[196:199], v[180:183], v[84:87]
	v_mfma_f32_16x16x32_bf16 v[80:83], v[200:203], v[180:183], v[80:83]
	s_waitcnt lgkmcnt(4)
	v_mfma_f32_16x16x32_bf16 v[76:79], v[188:191], v[184:187], v[76:79]
	v_mfma_f32_16x16x32_bf16 v[72:75], v[192:195], v[184:187], v[72:75]
	v_mfma_f32_16x16x32_bf16 v[68:71], v[196:199], v[184:187], v[68:71]
	v_mfma_f32_16x16x32_bf16 v[64:67], v[200:203], v[184:187], v[64:67]
	s_add_u32 s42, s42, 0x80
	s_addc_u32 s43, s43, 0
	s_cmpk_eq_i32 s42, 0x780
	s_mov_b32 s7, s2
	s_cbranch_scc0 .LBB0_899
	s_waitcnt lgkmcnt(0)
	v_mfma_f32_16x16x32_bf16 v[60:63], v[188:191], v[204:207], v[60:63]
	v_mfma_f32_16x16x32_bf16 v[56:59], v[192:195], v[204:207], v[56:59]
	v_mfma_f32_16x16x32_bf16 v[52:55], v[196:199], v[204:207], v[52:55]
	v_mfma_f32_16x16x32_bf16 v[48:51], v[200:203], v[204:207], v[48:51]
	v_mfma_f32_16x16x32_bf16 v[44:47], v[188:191], v[208:211], v[44:47]
	v_mfma_f32_16x16x32_bf16 v[40:43], v[192:195], v[208:211], v[40:43]
	v_mfma_f32_16x16x32_bf16 v[36:39], v[196:199], v[208:211], v[36:39]
	v_mfma_f32_16x16x32_bf16 v[32:35], v[200:203], v[208:211], v[32:35]
	v_mfma_f32_16x16x32_bf16 v[28:31], v[188:191], v[228:231], v[28:31]
	v_mfma_f32_16x16x32_bf16 v[24:27], v[192:195], v[228:231], v[24:27]
	v_mfma_f32_16x16x32_bf16 v[20:23], v[196:199], v[228:231], v[20:23]
	v_mfma_f32_16x16x32_bf16 v[16:19], v[200:203], v[228:231], v[16:19]
	v_mfma_f32_16x16x32_bf16 v[12:15], v[188:191], v[232:235], v[12:15]
	v_mfma_f32_16x16x32_bf16 v[8:11], v[192:195], v[232:235], v[8:11]
	v_mfma_f32_16x16x32_bf16 v[4:7], v[196:199], v[232:235], v[4:7]
	v_mfma_f32_16x16x32_bf16 v[0:3], v[200:203], v[232:235], v[0:3]
	s_waitcnt vmcnt(0)
	s_andn2_b64 vcc, exec, s[12:13]
	s_barrier
	v_readlane_b32 s41, v254, 60
	s_cbranch_vccnz .LBB0_902
	s_add_u32 s2, s54, s10
	s_addc_u32 s7, s55, s11
	s_and_b64 s[10:11], exec, s[0:1]
	s_cselect_b32 s11, 0, s7
	s_cselect_b32 s10, 0, s2
	v_readfirstlane_b32 s2, v139
	v_lshl_add_u64 v[134:135], s[10:11], 0, v[128:129]
	s_mov_b32 m0, s2
	v_lshl_add_u64 v[144:145], v[134:135], 0, s[80:81]
	v_lshl_add_u64 v[152:153], v[134:135], 0, s[82:83]
	v_lshl_add_u64 v[154:155], v[134:135], 0, s[70:71]
	global_load_lds_dwordx4 v[134:135], off
	v_add_u32_e32 v134, 0x2000, v139
	v_add_u32_e32 v143, 0x4000, v139
	v_readfirstlane_b32 s2, v134
	s_mov_b32 m0, s2
	v_readfirstlane_b32 s2, v143
	v_add_u32_e32 v134, 0x6000, v139
	s_add_u32 s12, s8, s38
	global_load_lds_dwordx4 v[154:155], off
	s_mov_b32 m0, s2
	v_readfirstlane_b32 s2, v134
	v_add_u32_e32 v134, 0x8000, v139
	s_addc_u32 s13, s18, s39
	global_load_lds_dwordx4 v[144:145], off
	s_mov_b32 m0, s2
	v_readfirstlane_b32 s2, v134
	v_add_u32_e32 v134, 0xa000, v139
	v_lshl_add_u64 v[136:137], s[12:13], 0, v[128:129]
	v_add_u32_e32 v128, 0xc000, v139
	global_load_lds_dwordx4 v[152:153], off
	s_mov_b32 m0, s2
	v_readfirstlane_b32 s2, v134
	v_lshl_add_u64 v[150:151], v[136:137], 0, s[70:71]
	global_load_lds_dwordx4 v[136:137], off
	s_mov_b32 m0, s2
	v_readfirstlane_b32 s2, v128
	v_add_u32_e32 v128, 0xe000, v139
	v_lshl_add_u64 v[146:147], v[136:137], 0, s[80:81]
	global_load_lds_dwordx4 v[150:151], off
	s_mov_b32 m0, s2
	v_readfirstlane_b32 s2, v128
	v_lshl_add_u64 v[148:149], v[136:137], 0, s[82:83]
	global_load_lds_dwordx4 v[146:147], off
	s_mov_b32 m0, s2
	s_nop 0
	global_load_lds_dwordx4 v[148:149], off

; DI void phase_gemm_resid(const bf16_t* __restrict__ A, int K, const bf16_t* __restrict__ Bt, const float* __restrict__ xin, float* __restrict__ xout, float alpha, unsigned char* smem) {
;     ...
; #pragma unroll
;     for (int m = 0; m < 8; ++m) {
;       const size_t row = (size_t)pm * 256 + wr * 128 + m * 16 + fr;
; #pragma unroll
;       for (int n = 0; n < 4; ++n) {
;         const size_t o = row * D + pn * 256 + wc * 64 + n * 16 + fq * 4;
;         const f32x4 x = *(const f32x4*)(xin + o);
;         *(f32x4*)(xout + o) = x + alpha * acc[m][n];
;       }
;     }
.LBB0_959:
	s_lshl_b64 s[4:5], s[4:5], 18
	s_lshl_b32 s2, s2, 8
	v_lshl_add_u64 v[138:139], s[4:5], 0, v[134:135]
	v_readlane_b32 s4, v254, 42
	s_ashr_i32 s6, s2, 31
	v_readlane_b32 s5, v254, 43
	v_mov_b32_e32 v137, s6
	v_or_b32_e32 v136, s2, v132
	v_lshl_add_u64 v[138:139], v[138:139], 2, s[4:5]
	v_lshl_add_u64 v[136:137], v[136:137], 2, v[138:139]
	global_load_dwordx4 v[168:171], v[136:137], off
	global_load_dwordx4 v[172:175], v[136:137], off offset:64
	global_load_dwordx4 v[176:179], v[136:137], off offset:128
	global_load_dwordx4 v[180:183], v[136:137], off offset:192
	s_mov_b64 s[4:5], 0x10000
	v_lshl_add_u64 v[248:249], v[136:137], 0, s[4:5]
	global_load_dwordx4 v[184:187], v[248:249], off
	global_load_dwordx4 v[188:191], v[248:249], off offset:64
	global_load_dwordx4 v[192:195], v[248:249], off offset:128
	global_load_dwordx4 v[196:199], v[248:249], off offset:192
	s_mov_b64 s[4:5], 0x20000
	v_lshl_add_u64 v[248:249], v[136:137], 0, s[4:5]
	global_load_dwordx4 v[200:203], v[248:249], off
	global_load_dwordx4 v[204:207], v[248:249], off offset:64
	global_load_dwordx4 v[208:211], v[248:249], off offset:128
	global_load_dwordx4 v[228:231], v[248:249], off offset:192
	s_mov_b64 s[4:5], 0x30000
	v_lshl_add_u64 v[248:249], v[136:137], 0, s[4:5]
	global_load_dwordx4 v[232:235], v[248:249], off
	global_load_dwordx4 v[236:239], v[248:249], off offset:64
	global_load_dwordx4 v[240:243], v[248:249], off offset:128
	global_load_dwordx4 v[244:247], v[248:249], off offset:192
	s_waitcnt vmcnt(15)
	v_pk_fma_f32 v[126:127], v[126:127], 0.5, v[170:171] op_sel_hi:[1,0,1]
	v_pk_fma_f32 v[124:125], v[124:125], 0.5, v[168:169] op_sel_hi:[1,0,1]
	global_store_dwordx4 v[136:137], v[124:127], off
	s_mov_b64 s[4:5], 0x40000
	v_lshl_add_u64 v[248:249], v[136:137], 0, s[4:5]
	global_load_dwordx4 v[168:171], v[248:249], off
	s_waitcnt vmcnt(16)
	v_pk_fma_f32 v[122:123], v[122:123], 0.5, v[174:175] op_sel_hi:[1,0,1]
	v_pk_fma_f32 v[120:121], v[120:121], 0.5, v[172:173] op_sel_hi:[1,0,1]
	global_store_dwordx4 v[136:137], v[120:123], off offset:64
	global_load_dwordx4 v[172:175], v[248:249], off offset:64
	s_waitcnt vmcnt(17)
	v_pk_fma_f32 v[118:119], v[118:119], 0.5, v[178:179] op_sel_hi:[1,0,1]
	v_pk_fma_f32 v[116:117], v[116:117], 0.5, v[176:177] op_sel_hi:[1,0,1]
	global_store_dwordx4 v[136:137], v[116:119], off offset:128
	global_load_dwordx4 v[176:179], v[248:249], off offset:128
	s_waitcnt vmcnt(18)
	v_pk_fma_f32 v[114:115], v[114:115], 0.5, v[182:183] op_sel_hi:[1,0,1]
	v_pk_fma_f32 v[112:113], v[112:113], 0.5, v[180:181] op_sel_hi:[1,0,1]
	global_store_dwordx4 v[136:137], v[112:115], off offset:192
	global_load_dwordx4 v[180:183], v[248:249], off offset:192
	s_waitcnt vmcnt(19)
	v_pk_fma_f32 v[110:111], v[110:111], 0.5, v[186:187] op_sel_hi:[1,0,1]
	v_pk_fma_f32 v[108:109], v[108:109], 0.5, v[184:185] op_sel_hi:[1,0,1]
	s_mov_b64 s[4:5], 0x10000
	v_lshl_add_u64 v[250:251], v[136:137], 0, s[4:5]
	global_store_dwordx4 v[250:251], v[108:111], off
	s_mov_b64 s[4:5], 0x50000
	v_lshl_add_u64 v[248:249], v[136:137], 0, s[4:5]
	global_load_dwordx4 v[184:187], v[248:249], off
	s_waitcnt vmcnt(20)
	v_pk_fma_f32 v[106:107], v[106:107], 0.5, v[190:191] op_sel_hi:[1,0,1]
	v_pk_fma_f32 v[104:105], v[104:105], 0.5, v[188:189] op_sel_hi:[1,0,1]
	global_store_dwordx4 v[250:251], v[104:107], off offset:64
	global_load_dwordx4 v[188:191], v[248:249], off offset:64
	s_waitcnt vmcnt(21)
	v_pk_fma_f32 v[102:103], v[102:103], 0.5, v[194:195] op_sel_hi:[1,0,1]
	v_pk_fma_f32 v[100:101], v[100:101], 0.5, v[192:193] op_sel_hi:[1,0,1]
	global_store_dwordx4 v[250:251], v[100:103], off offset:128
	global_load_dwordx4 v[192:195], v[248:249], off offset:128
	s_waitcnt vmcnt(22)
	v_pk_fma_f32 v[98:99], v[98:99], 0.5, v[198:199] op_sel_hi:[1,0,1]
	v_pk_fma_f32 v[96:97], v[96:97], 0.5, v[196:197] op_sel_hi:[1,0,1]
	global_store_dwordx4 v[250:251], v[96:99], off offset:192
	global_load_dwordx4 v[196:199], v[248:249], off offset:192
	s_waitcnt vmcnt(23)
	v_pk_fma_f32 v[94:95], v[94:95], 0.5, v[202:203] op_sel_hi:[1,0,1]
	v_pk_fma_f32 v[92:93], v[92:93], 0.5, v[200:201] op_sel_hi:[1,0,1]
	s_mov_b64 s[4:5], 0x20000
	v_lshl_add_u64 v[250:251], v[136:137], 0, s[4:5]
	global_store_dwordx4 v[250:251], v[92:95], off
	s_mov_b64 s[4:5], 0x60000
	v_lshl_add_u64 v[248:249], v[136:137], 0, s[4:5]
	global_load_dwordx4 v[200:203], v[248:249], off
	s_waitcnt vmcnt(24)
	v_pk_fma_f32 v[90:91], v[90:91], 0.5, v[206:207] op_sel_hi:[1,0,1]
	v_pk_fma_f32 v[88:89], v[88:89], 0.5, v[204:205] op_sel_hi:[1,0,1]
	global_store_dwordx4 v[250:251], v[88:91], off offset:64
	global_load_dwordx4 v[204:207], v[248:249], off offset:64
	s_waitcnt vmcnt(25)
	v_pk_fma_f32 v[86:87], v[86:87], 0.5, v[210:211] op_sel_hi:[1,0,1]
	v_pk_fma_f32 v[84:85], v[84:85], 0.5, v[208:209] op_sel_hi:[1,0,1]
	global_store_dwordx4 v[250:251], v[84:87], off offset:128
	global_load_dwordx4 v[208:211], v[248:249], off offset:128
	s_waitcnt vmcnt(26)
	v_pk_fma_f32 v[82:83], v[82:83], 0.5, v[230:231] op_sel_hi:[1,0,1]
	v_pk_fma_f32 v[80:81], v[80:81], 0.5, v[228:229] op_sel_hi:[1,0,1]
	global_store_dwordx4 v[250:251], v[80:83], off offset:192
	global_load_dwordx4 v[228:231], v[248:249], off offset:192
	s_waitcnt vmcnt(27)
; DI void phase_gemm_resid(const bf16_t* __restrict__ A, int K, const bf16_t* __restrict__ Bt, const float* __restrict__ xin, float* __restrict__ xout, float alpha, unsigned char* smem) {
;     ...
; #pragma unroll
;     for (int m = 0; m < 8; ++m) {
;       const size_t row = (size_t)pm * 256 + wr * 128 + m * 16 + fr;
; #pragma unroll
;       for (int n = 0; n < 4; ++n) {
;         const size_t o = row * D + pn * 256 + wc * 64 + n * 16 + fq * 4;
;         const f32x4 x = *(const f32x4*)(xin + o);
;         *(f32x4*)(xout + o) = x + alpha * acc[m][n];
;       }
;     }
	v_pk_fma_f32 v[78:79], v[78:79], 0.5, v[234:235] op_sel_hi:[1,0,1]
	v_pk_fma_f32 v[76:77], v[76:77], 0.5, v[232:233] op_sel_hi:[1,0,1]
	s_mov_b64 s[4:5], 0x30000
	v_lshl_add_u64 v[250:251], v[136:137], 0, s[4:5]
	global_store_dwordx4 v[250:251], v[76:79], off
	s_mov_b64 s[4:5], 0x70000
	v_lshl_add_u64 v[248:249], v[136:137], 0, s[4:5]
	global_load_dwordx4 v[232:235], v[248:249], off
	s_waitcnt vmcnt(28)
	v_pk_fma_f32 v[74:75], v[74:75], 0.5, v[238:239] op_sel_hi:[1,0,1]
	v_pk_fma_f32 v[72:73], v[72:73], 0.5, v[236:237] op_sel_hi:[1,0,1]
	global_store_dwordx4 v[250:251], v[72:75], off offset:64
	global_load_dwordx4 v[236:239], v[248:249], off offset:64
	s_waitcnt vmcnt(29)
	v_pk_fma_f32 v[70:71], v[70:71], 0.5, v[242:243] op_sel_hi:[1,0,1]
	v_pk_fma_f32 v[68:69], v[68:69], 0.5, v[240:241] op_sel_hi:[1,0,1]
	global_store_dwordx4 v[250:251], v[68:71], off offset:128
	global_load_dwordx4 v[240:243], v[248:249], off offset:128
	s_waitcnt vmcnt(30)
	v_pk_fma_f32 v[66:67], v[66:67], 0.5, v[246:247] op_sel_hi:[1,0,1]
	v_pk_fma_f32 v[64:65], v[64:65], 0.5, v[244:245] op_sel_hi:[1,0,1]
	global_store_dwordx4 v[250:251], v[64:67], off offset:192
	global_load_dwordx4 v[244:247], v[248:249], off offset:192
	s_waitcnt vmcnt(30)
	v_pk_fma_f32 v[62:63], v[62:63], 0.5, v[170:171] op_sel_hi:[1,0,1]
	v_pk_fma_f32 v[60:61], v[60:61], 0.5, v[168:169] op_sel_hi:[1,0,1]
	s_mov_b64 s[4:5], 0x40000
	v_lshl_add_u64 v[250:251], v[136:137], 0, s[4:5]
	global_store_dwordx4 v[250:251], v[60:63], off
	s_waitcnt vmcnt(29)
	v_pk_fma_f32 v[58:59], v[58:59], 0.5, v[174:175] op_sel_hi:[1,0,1]
	v_pk_fma_f32 v[56:57], v[56:57], 0.5, v[172:173] op_sel_hi:[1,0,1]
	global_store_dwordx4 v[250:251], v[56:59], off offset:64
	s_waitcnt vmcnt(28)
	v_pk_fma_f32 v[54:55], v[54:55], 0.5, v[178:179] op_sel_hi:[1,0,1]
	v_pk_fma_f32 v[52:53], v[52:53], 0.5, v[176:177] op_sel_hi:[1,0,1]
	global_store_dwordx4 v[250:251], v[52:55], off offset:128
	s_waitcnt vmcnt(27)
	v_pk_fma_f32 v[50:51], v[50:51], 0.5, v[182:183] op_sel_hi:[1,0,1]
	v_pk_fma_f32 v[48:49], v[48:49], 0.5, v[180:181] op_sel_hi:[1,0,1]
	global_store_dwordx4 v[250:251], v[48:51], off offset:192
	s_waitcnt vmcnt(26)
	v_pk_fma_f32 v[46:47], v[46:47], 0.5, v[186:187] op_sel_hi:[1,0,1]
	v_pk_fma_f32 v[44:45], v[44:45], 0.5, v[184:185] op_sel_hi:[1,0,1]
	s_mov_b64 s[4:5], 0x50000
	v_lshl_add_u64 v[250:251], v[136:137], 0, s[4:5]
	global_store_dwordx4 v[250:251], v[44:47], off
	s_waitcnt vmcnt(25)
	v_pk_fma_f32 v[42:43], v[42:43], 0.5, v[190:191] op_sel_hi:[1,0,1]
	v_pk_fma_f32 v[40:41], v[40:41], 0.5, v[188:189] op_sel_hi:[1,0,1]
	global_store_dwordx4 v[250:251], v[40:43], off offset:64
	s_waitcnt vmcnt(24)
	v_pk_fma_f32 v[38:39], v[38:39], 0.5, v[194:195] op_sel_hi:[1,0,1]
	v_pk_fma_f32 v[36:37], v[36:37], 0.5, v[192:193] op_sel_hi:[1,0,1]
	global_store_dwordx4 v[250:251], v[36:39], off offset:128
	s_waitcnt vmcnt(23)
	v_pk_fma_f32 v[34:35], v[34:35], 0.5, v[198:199] op_sel_hi:[1,0,1]
	v_pk_fma_f32 v[32:33], v[32:33], 0.5, v[196:197] op_sel_hi:[1,0,1]
	global_store_dwordx4 v[250:251], v[32:35], off offset:192
	s_waitcnt vmcnt(22)
	v_pk_fma_f32 v[30:31], v[30:31], 0.5, v[202:203] op_sel_hi:[1,0,1]
	v_pk_fma_f32 v[28:29], v[28:29], 0.5, v[200:201] op_sel_hi:[1,0,1]
	s_mov_b64 s[4:5], 0x60000
	v_lshl_add_u64 v[250:251], v[136:137], 0, s[4:5]
	global_store_dwordx4 v[250:251], v[28:31], off
	s_waitcnt vmcnt(21)
	v_pk_fma_f32 v[26:27], v[26:27], 0.5, v[206:207] op_sel_hi:[1,0,1]
	v_pk_fma_f32 v[24:25], v[24:25], 0.5, v[204:205] op_sel_hi:[1,0,1]
	global_store_dwordx4 v[250:251], v[24:27], off offset:64
	s_waitcnt vmcnt(20)
	v_pk_fma_f32 v[22:23], v[22:23], 0.5, v[210:211] op_sel_hi:[1,0,1]
	v_pk_fma_f32 v[20:21], v[20:21], 0.5, v[208:209] op_sel_hi:[1,0,1]
	global_store_dwordx4 v[250:251], v[20:23], off offset:128
	s_waitcnt vmcnt(19)
	v_pk_fma_f32 v[18:19], v[18:19], 0.5, v[230:231] op_sel_hi:[1,0,1]
	v_pk_fma_f32 v[16:17], v[16:17], 0.5, v[228:229] op_sel_hi:[1,0,1]
	global_store_dwordx4 v[250:251], v[16:19], off offset:192
	s_waitcnt vmcnt(18)
	v_pk_fma_f32 v[14:15], v[14:15], 0.5, v[234:235] op_sel_hi:[1,0,1]
	v_pk_fma_f32 v[12:13], v[12:13], 0.5, v[232:233] op_sel_hi:[1,0,1]
	s_mov_b64 s[4:5], 0x70000
	v_lshl_add_u64 v[250:251], v[136:137], 0, s[4:5]
	global_store_dwordx4 v[250:251], v[12:15], off
	s_waitcnt vmcnt(17)
	v_pk_fma_f32 v[10:11], v[10:11], 0.5, v[238:239] op_sel_hi:[1,0,1]
	v_pk_fma_f32 v[8:9], v[8:9], 0.5, v[236:237] op_sel_hi:[1,0,1]
	global_store_dwordx4 v[250:251], v[8:11], off offset:64
	s_waitcnt vmcnt(16)
	v_pk_fma_f32 v[6:7], v[6:7], 0.5, v[242:243] op_sel_hi:[1,0,1]
	v_pk_fma_f32 v[4:5], v[4:5], 0.5, v[240:241] op_sel_hi:[1,0,1]
	global_store_dwordx4 v[250:251], v[4:7], off offset:128
	s_waitcnt vmcnt(15)
	v_pk_fma_f32 v[2:3], v[2:3], 0.5, v[246:247] op_sel_hi:[1,0,1]
	v_pk_fma_f32 v[0:1], v[0:1], 0.5, v[244:245] op_sel_hi:[1,0,1]
	global_store_dwordx4 v[250:251], v[0:3], off offset:192
	s_mov_b64 s[4:5], 0x70000
	s_andn2_b64 vcc, exec, s[0:1]
	s_mov_b32 s2, s21
	s_cbranch_vccz .LBB0_972

; #define MFMA16(a, b, c) __builtin_amdgcn_mfma_f32_16x16x32_bf16((a), (b), (c), 0, 0, 0)
; DI void glds16(const void* g, unsigned char* l) { __builtin_amdgcn_global_load_lds((const unsigned*)g, (lds_u32*)l, 16, 0, 0); }
; template <int N> DI void wait_vm() { asm volatile("s_waitcnt vmcnt(%0)" :: "n"(N) : "memory"); }
;     ...
;   for (int kt = 0; kt < nk; ++kt) {
;     wait_vm<0>();
;     __builtin_amdgcn_s_barrier();
;     if (kt + 1 < nk) {
;       unsigned char* sn = smem + ((kt + 1) & 1) * STG;
;       const int ko = (kt + 1) * 64;
; #pragma unroll
;       for (int i = 0; i < NA; ++i) glds16(Ab + ((size_t)i * 128 * lda + ko * 2) + voA, sn + (i * 512 + tid) * 16);
; #pragma unroll
;       for (int i = 0; i < NB; ++i) glds16(Bb + ((size_t)i * 128 * ldb + ko * 2) + voB, sn + AB + (i * 512 + tid) * 16);
;     } else if (nA) {
;       const unsigned nvoA = (unsigned)(srow * nlda + kch * 8) * 2u, nvoB = (unsigned)(srow * nldb + kch * 8) * 2u;
; #pragma unroll
;       for (int i = 0; i < NA; ++i) glds16((const char*)nA + (size_t)i * 128 * nlda + nvoA, smem + (i * 512 + tid) * 16);
; #pragma unroll
;       for (int i = 0; i < NB; ++i) glds16((const char*)nB + (size_t)i * 128 * nldb + nvoB, smem + AB + (i * 512 + tid) * 16);
;     }
;     const unsigned stb = lds_base + (kt & 1) * STG;
; #pragma unroll
;     for (int ks = 0; ks < 2; ++ks) {
;       const unsigned co = ((ks * 4 + fq) ^ sw) * 16;
;       const unsigned sa = stb + a_row + co, sb = stb + b_row + co;
;       bf16x8 af[4], bfr[NT];
; #pragma unroll
;       for (int n = 0; n < NT; ++n) asm volatile("ds_read_b128 %0, %1 offset:%2" : "=v"(bfr[n]) : "v"(sb), "n"(n * 2048) : "memory");
; #pragma unroll
;       for (int mg = 0; mg < MT / 4; ++mg) {
; #pragma unroll
;         for (int m = 0; m < 4; ++m) asm volatile("ds_read_b128 %0, %1 offset:%2" : "=v"(af[m]) : "v"(sa), "n"((mg * 4 + m) * 2048) : "memory");
;         if (mg == 0) {
; #pragma unroll
;           for (int n = 0; n < NT; ++n) asm volatile("s_waitcnt lgkmcnt(%1)" : "+v"(bfr[n]) : "n"(4 + NT - 1 - n) : "memory");
;         }
; #pragma unroll
;         for (int m = 0; m < 4; ++m) {
;           asm volatile("s_waitcnt lgkmcnt(%1)" : "+v"(af[m]) : "n"(3 - m) : "memory");
; #pragma unroll
;           for (int n = 0; n < NT; ++n) acc[mg * 4 + m][n] = MFMA16(bfr[n], af[m], acc[mg * 4 + m][n]);
;         }
;       }
;     }
.LBB0_967:
	s_add_i32 s14, s15, 0x10000
	s_and_b32 s16, s14, 0x10000
	v_add_u32_e32 v143, s16, v133
	v_lshl_add_u64 v[144:145], v[136:137], 0, s[38:39]
	v_readfirstlane_b32 s16, v143
	v_add_u32_e32 v148, 0x2000, v143
	v_lshl_add_u64 v[146:147], v[144:145], 0, s[96:97]
	s_mov_b32 m0, s16
	v_readfirstlane_b32 s16, v148
	v_add_u32_e32 v148, 0x4000, v143
	s_waitcnt vmcnt(0)
	s_waitcnt lgkmcnt(0)
	s_barrier
	s_and_b32 s15, s15, 0x10000
	v_add_u32_e32 v240, s15, v142
	v_add_u32_e32 v236, v240, v140
	v_add_u32_e32 v237, v240, v131
	v_add_u32_e32 v240, s15, v141
	v_add_u32_e32 v238, v240, v140
	v_add_u32_e32 v239, v240, v131
	v_mfma_f32_16x16x32_bf16 v[60:63], v[188:191], v[204:207], v[60:63]
	ds_read_b128 v[152:155], v236 offset:0
	ds_read_b128 v[156:159], v236 offset:2048
	v_mfma_f32_16x16x32_bf16 v[56:59], v[192:195], v[204:207], v[56:59]
	ds_read_b128 v[160:163], v236 offset:4096
	ds_read_b128 v[164:167], v236 offset:6144
	global_load_lds_dwordx4 v[146:147], off
	v_mfma_f32_16x16x32_bf16 v[52:55], v[196:199], v[204:207], v[52:55]
	ds_read_b128 v[168:171], v238 offset:0
	ds_read_b128 v[172:175], v238 offset:2048
	v_mfma_f32_16x16x32_bf16 v[48:51], v[200:203], v[204:207], v[48:51]
	ds_read_b128 v[180:183], v238 offset:4096
	ds_read_b128 v[184:187], v238 offset:6144
	v_mfma_f32_16x16x32_bf16 v[44:47], v[188:191], v[208:211], v[44:47]
	v_mfma_f32_16x16x32_bf16 v[40:43], v[192:195], v[208:211], v[40:43]
	v_mfma_f32_16x16x32_bf16 v[36:39], v[196:199], v[208:211], v[36:39]
	v_lshl_add_u64 v[146:147], v[144:145], 0, s[78:79]
	s_mov_b32 m0, s16
	v_readfirstlane_b32 s16, v148
	global_load_lds_dwordx4 v[146:147], off
	v_mfma_f32_16x16x32_bf16 v[32:35], v[200:203], v[208:211], v[32:35]
	v_mfma_f32_16x16x32_bf16 v[28:31], v[188:191], v[228:231], v[28:31]
	v_mfma_f32_16x16x32_bf16 v[24:27], v[192:195], v[228:231], v[24:27]
	v_mfma_f32_16x16x32_bf16 v[20:23], v[196:199], v[228:231], v[20:23]
	v_mfma_f32_16x16x32_bf16 v[16:19], v[200:203], v[228:231], v[16:19]
	v_lshl_add_u64 v[146:147], v[144:145], 0, s[50:51]
	s_mov_b32 m0, s16
	v_lshl_add_u64 v[144:145], v[144:145], 0, s[22:23]
	global_load_lds_dwordx4 v[146:147], off
	v_mfma_f32_16x16x32_bf16 v[12:15], v[188:191], v[232:235], v[12:15]
	v_mfma_f32_16x16x32_bf16 v[8:11], v[192:195], v[232:235], v[8:11]
	v_mfma_f32_16x16x32_bf16 v[4:7], v[196:199], v[232:235], v[4:7]
	v_mfma_f32_16x16x32_bf16 v[0:3], v[200:203], v[232:235], v[0:3]
	s_waitcnt lgkmcnt(3)
	v_mfma_f32_16x16x32_bf16 v[124:127], v[152:155], v[168:171], v[124:127]
	v_add_u32_e32 v146, 0x6000, v143
	v_add_u32_e32 v148, 0x8000, v143
	v_readfirstlane_b32 s16, v146
	s_mov_b32 m0, s16
	s_mov_b64 s[16:17], 0x1b88080
	global_load_lds_dwordx4 v[144:145], off
	v_mfma_f32_16x16x32_bf16 v[120:123], v[156:159], v[168:171], v[120:123]
	ds_read_b128 v[204:207], v238 offset:8192
	v_mfma_f32_16x16x32_bf16 v[116:119], v[160:163], v[168:171], v[116:119]
	v_mfma_f32_16x16x32_bf16 v[112:115], v[164:167], v[168:171], v[112:115]
	ds_read_b128 v[208:211], v238 offset:10240
	s_waitcnt lgkmcnt(4)
	v_mfma_f32_16x16x32_bf16 v[108:111], v[152:155], v[172:175], v[108:111]
	v_mfma_f32_16x16x32_bf16 v[104:107], v[156:159], v[172:175], v[104:107]
	ds_read_b128 v[228:231], v238 offset:12288
	v_lshl_add_u64 v[144:145], v[138:139], 0, s[38:39]
	v_lshl_add_u64 v[146:147], v[144:145], 0, s[16:17]
	v_readfirstlane_b32 s16, v148
	s_mov_b32 m0, s16
	s_mov_b64 s[16:17], 0x1be0080
	v_add_u32_e32 v148, 0xa000, v143
	global_load_lds_dwordx4 v[146:147], off
	v_mfma_f32_16x16x32_bf16 v[100:103], v[160:163], v[172:175], v[100:103]
	v_mfma_f32_16x16x32_bf16 v[96:99], v[164:167], v[172:175], v[96:99]
	ds_read_b128 v[232:235], v238 offset:14336
	s_waitcnt lgkmcnt(5)
	v_mfma_f32_16x16x32_bf16 v[92:95], v[152:155], v[180:183], v[92:95]
	v_mfma_f32_16x16x32_bf16 v[88:91], v[156:159], v[180:183], v[88:91]
	ds_read_b128 v[188:191], v237 offset:0
	v_mfma_f32_16x16x32_bf16 v[84:87], v[160:163], v[180:183], v[84:87]
	v_lshl_add_u64 v[146:147], v[144:145], 0, s[16:17]
	v_readfirstlane_b32 s16, v148
	s_mov_b32 m0, s16
	s_mov_b64 s[16:17], 0x1c38080
	v_add_u32_e32 v148, 0xc000, v143
	global_load_lds_dwordx4 v[146:147], off
	v_mfma_f32_16x16x32_bf16 v[80:83], v[164:167], v[180:183], v[80:83]
	ds_read_b128 v[192:195], v237 offset:2048
	s_waitcnt lgkmcnt(6)
	v_mfma_f32_16x16x32_bf16 v[76:79], v[152:155], v[184:187], v[76:79]
	v_mfma_f32_16x16x32_bf16 v[72:75], v[156:159], v[184:187], v[72:75]
	ds_read_b128 v[196:199], v237 offset:4096
	v_mfma_f32_16x16x32_bf16 v[68:71], v[160:163], v[184:187], v[68:71]
	v_mfma_f32_16x16x32_bf16 v[64:67], v[164:167], v[184:187], v[64:67]
	ds_read_b128 v[200:203], v237 offset:6144
	v_lshl_add_u64 v[146:147], v[144:145], 0, s[16:17]
	v_readfirstlane_b32 s16, v148
	s_mov_b32 m0, s16
	s_mov_b64 s[16:17], 0x1c90080
	v_add_u32_e32 v143, 0xe000, v143
	v_lshl_add_u64 v[144:145], v[144:145], 0, s[16:17]
	v_readfirstlane_b32 s16, v143
	global_load_lds_dwordx4 v[146:147], off
	s_waitcnt lgkmcnt(7)
	v_mfma_f32_16x16x32_bf16 v[60:63], v[152:155], v[204:207], v[60:63]
	v_mfma_f32_16x16x32_bf16 v[56:59], v[156:159], v[204:207], v[56:59]
	ds_read_b128 v[168:171], v239 offset:0
	v_mfma_f32_16x16x32_bf16 v[52:55], v[160:163], v[204:207], v[52:55]
	v_mfma_f32_16x16x32_bf16 v[48:51], v[164:167], v[204:207], v[48:51]
	ds_read_b128 v[172:175], v239 offset:2048
	s_waitcnt lgkmcnt(8)
; #define MFMA16(a, b, c) __builtin_amdgcn_mfma_f32_16x16x32_bf16((a), (b), (c), 0, 0, 0)
; DI void glds16(const void* g, unsigned char* l) { __builtin_amdgcn_global_load_lds((const unsigned*)g, (lds_u32*)l, 16, 0, 0); }
; template <int N> DI void wait_vm() { asm volatile("s_waitcnt vmcnt(%0)" :: "n"(N) : "memory"); }
;     ...
;   for (int kt = 0; kt < nk; ++kt) {
;     wait_vm<0>();
;     __builtin_amdgcn_s_barrier();
;     if (kt + 1 < nk) {
;       unsigned char* sn = smem + ((kt + 1) & 1) * STG;
;       const int ko = (kt + 1) * 64;
; #pragma unroll
;       for (int i = 0; i < NA; ++i) glds16(Ab + ((size_t)i * 128 * lda + ko * 2) + voA, sn + (i * 512 + tid) * 16);
; #pragma unroll
;       for (int i = 0; i < NB; ++i) glds16(Bb + ((size_t)i * 128 * ldb + ko * 2) + voB, sn + AB + (i * 512 + tid) * 16);
;     } else if (nA) {
;       const unsigned nvoA = (unsigned)(srow * nlda + kch * 8) * 2u, nvoB = (unsigned)(srow * nldb + kch * 8) * 2u;
; #pragma unroll
;       for (int i = 0; i < NA; ++i) glds16((const char*)nA + (size_t)i * 128 * nlda + nvoA, smem + (i * 512 + tid) * 16);
; #pragma unroll
;       for (int i = 0; i < NB; ++i) glds16((const char*)nB + (size_t)i * 128 * nldb + nvoB, smem + AB + (i * 512 + tid) * 16);
;     }
;     const unsigned stb = lds_base + (kt & 1) * STG;
; #pragma unroll
;     for (int ks = 0; ks < 2; ++ks) {
;       const unsigned co = ((ks * 4 + fq) ^ sw) * 16;
;       const unsigned sa = stb + a_row + co, sb = stb + b_row + co;
;       bf16x8 af[4], bfr[NT];
; #pragma unroll
;       for (int n = 0; n < NT; ++n) asm volatile("ds_read_b128 %0, %1 offset:%2" : "=v"(bfr[n]) : "v"(sb), "n"(n * 2048) : "memory");
; #pragma unroll
;       for (int mg = 0; mg < MT / 4; ++mg) {
; #pragma unroll
;         for (int m = 0; m < 4; ++m) asm volatile("ds_read_b128 %0, %1 offset:%2" : "=v"(af[m]) : "v"(sa), "n"((mg * 4 + m) * 2048) : "memory");
;         if (mg == 0) {
; #pragma unroll
;           for (int n = 0; n < NT; ++n) asm volatile("s_waitcnt lgkmcnt(%1)" : "+v"(bfr[n]) : "n"(4 + NT - 1 - n) : "memory");
;         }
; #pragma unroll
;         for (int m = 0; m < 4; ++m) {
;           asm volatile("s_waitcnt lgkmcnt(%1)" : "+v"(af[m]) : "n"(3 - m) : "memory");
; #pragma unroll
;           for (int n = 0; n < NT; ++n) acc[mg * 4 + m][n] = MFMA16(bfr[n], af[m], acc[mg * 4 + m][n]);
;         }
;       }
;     }
	v_mfma_f32_16x16x32_bf16 v[44:47], v[152:155], v[208:211], v[44:47]
	s_mov_b32 m0, s16
	s_nop 0
	global_load_lds_dwordx4 v[144:145], off
	v_mfma_f32_16x16x32_bf16 v[40:43], v[156:159], v[208:211], v[40:43]
	ds_read_b128 v[180:183], v239 offset:4096
	v_mfma_f32_16x16x32_bf16 v[36:39], v[160:163], v[208:211], v[36:39]
	v_mfma_f32_16x16x32_bf16 v[32:35], v[164:167], v[208:211], v[32:35]
	ds_read_b128 v[184:187], v239 offset:6144
	s_waitcnt lgkmcnt(9)
	v_mfma_f32_16x16x32_bf16 v[28:31], v[152:155], v[228:231], v[28:31]
	v_mfma_f32_16x16x32_bf16 v[24:27], v[156:159], v[228:231], v[24:27]
	v_mfma_f32_16x16x32_bf16 v[20:23], v[160:163], v[228:231], v[20:23]
	v_mfma_f32_16x16x32_bf16 v[16:19], v[164:167], v[228:231], v[16:19]
	s_waitcnt lgkmcnt(8)
	v_mfma_f32_16x16x32_bf16 v[12:15], v[152:155], v[232:235], v[12:15]
	v_mfma_f32_16x16x32_bf16 v[8:11], v[156:159], v[232:235], v[8:11]
	v_mfma_f32_16x16x32_bf16 v[4:7], v[160:163], v[232:235], v[4:7]
	v_mfma_f32_16x16x32_bf16 v[0:3], v[164:167], v[232:235], v[0:3]
	s_waitcnt lgkmcnt(3)
	v_mfma_f32_16x16x32_bf16 v[124:127], v[188:191], v[168:171], v[124:127]
	v_mfma_f32_16x16x32_bf16 v[120:123], v[192:195], v[168:171], v[120:123]
	ds_read_b128 v[204:207], v239 offset:8192
	v_mfma_f32_16x16x32_bf16 v[116:119], v[196:199], v[168:171], v[116:119]
	v_mfma_f32_16x16x32_bf16 v[112:115], v[200:203], v[168:171], v[112:115]
	ds_read_b128 v[208:211], v239 offset:10240
	s_waitcnt lgkmcnt(4)
	v_mfma_f32_16x16x32_bf16 v[108:111], v[188:191], v[172:175], v[108:111]
	v_mfma_f32_16x16x32_bf16 v[104:107], v[192:195], v[172:175], v[104:107]
	ds_read_b128 v[228:231], v239 offset:12288
	v_mfma_f32_16x16x32_bf16 v[100:103], v[196:199], v[172:175], v[100:103]
	v_mfma_f32_16x16x32_bf16 v[96:99], v[200:203], v[172:175], v[96:99]
	ds_read_b128 v[232:235], v239 offset:14336
	s_waitcnt lgkmcnt(5)
	v_mfma_f32_16x16x32_bf16 v[92:95], v[188:191], v[180:183], v[92:95]
	v_mfma_f32_16x16x32_bf16 v[88:91], v[192:195], v[180:183], v[88:91]
	v_mfma_f32_16x16x32_bf16 v[84:87], v[196:199], v[180:183], v[84:87]
	v_mfma_f32_16x16x32_bf16 v[80:83], v[200:203], v[180:183], v[80:83]
	s_waitcnt lgkmcnt(4)
	v_mfma_f32_16x16x32_bf16 v[76:79], v[188:191], v[184:187], v[76:79]
	v_mfma_f32_16x16x32_bf16 v[72:75], v[192:195], v[184:187], v[72:75]
	v_mfma_f32_16x16x32_bf16 v[68:71], v[196:199], v[184:187], v[68:71]
	v_mfma_f32_16x16x32_bf16 v[64:67], v[200:203], v[184:187], v[64:67]
	s_add_u32 s38, s38, 0x80
	s_addc_u32 s39, s39, 0
	s_cmpk_eq_i32 s38, 0x1580
	s_mov_b32 s15, s14
	s_cbranch_scc0 .LBB0_967
	s_waitcnt lgkmcnt(0)
	v_mfma_f32_16x16x32_bf16 v[60:63], v[188:191], v[204:207], v[60:63]
	v_mfma_f32_16x16x32_bf16 v[56:59], v[192:195], v[204:207], v[56:59]
	v_mfma_f32_16x16x32_bf16 v[52:55], v[196:199], v[204:207], v[52:55]
	v_mfma_f32_16x16x32_bf16 v[48:51], v[200:203], v[204:207], v[48:51]
	v_mfma_f32_16x16x32_bf16 v[44:47], v[188:191], v[208:211], v[44:47]
	v_mfma_f32_16x16x32_bf16 v[40:43], v[192:195], v[208:211], v[40:43]
	v_mfma_f32_16x16x32_bf16 v[36:39], v[196:199], v[208:211], v[36:39]
	v_mfma_f32_16x16x32_bf16 v[32:35], v[200:203], v[208:211], v[32:35]
	v_mfma_f32_16x16x32_bf16 v[28:31], v[188:191], v[228:231], v[28:31]
	v_mfma_f32_16x16x32_bf16 v[24:27], v[192:195], v[228:231], v[24:27]
	v_mfma_f32_16x16x32_bf16 v[20:23], v[196:199], v[228:231], v[20:23]
	v_mfma_f32_16x16x32_bf16 v[16:19], v[200:203], v[228:231], v[16:19]
	v_mfma_f32_16x16x32_bf16 v[12:15], v[188:191], v[232:235], v[12:15]
	v_mfma_f32_16x16x32_bf16 v[8:11], v[192:195], v[232:235], v[8:11]
	v_mfma_f32_16x16x32_bf16 v[4:7], v[196:199], v[232:235], v[4:7]
	v_mfma_f32_16x16x32_bf16 v[0:3], v[200:203], v[232:235], v[0:3]
	s_waitcnt vmcnt(0)
	s_andn2_b64 vcc, exec, s[6:7]
	s_mov_b32 s23, 0x10000
	s_barrier
	s_cbranch_vccnz .LBB0_970
	s_lshl_b64 s[6:7], s[12:13], 1
	s_add_u32 s12, s52, s6
	s_addc_u32 s13, s53, s7
	s_and_b64 s[6:7], exec, s[0:1]
	s_cselect_b32 s7, 0, s13
	s_cselect_b32 s6, 0, s12
	s_lshl_b64 s[10:11], s[10:11], 1
	s_add_u32 s10, s8, s10
	s_addc_u32 s11, s18, s11
	v_lshl_add_u64 v[136:137], s[6:7], 0, v[128:129]
	v_lshl_add_u64 v[138:139], s[10:11], 0, v[128:129]
	s_mov_b64 s[6:7], 0xb0000
	v_lshl_add_u64 v[144:145], v[136:137], 0, s[6:7]
	v_lshl_add_u64 v[146:147], v[138:139], 0, s[6:7]
	s_mov_b64 s[6:7], 0x58000
	v_lshl_add_u64 v[150:151], v[138:139], 0, s[6:7]
	v_lshl_add_u64 v[154:155], v[136:137], 0, s[6:7]
	v_readfirstlane_b32 s6, v133
	s_mov_b64 s[10:11], 0x108000
	s_mov_b32 m0, s6
	v_lshl_add_u64 v[152:153], v[136:137], 0, s[10:11]
	global_load_lds_dwordx4 v[136:137], off
	v_add_u32_e32 v136, 0x2000, v133
	v_add_u32_e32 v143, 0x4000, v133
	v_readfirstlane_b32 s6, v136
	s_mov_b32 m0, s6
	v_readfirstlane_b32 s6, v143
	v_add_u32_e32 v136, 0x6000, v133
	global_load_lds_dwordx4 v[154:155], off
	s_mov_b32 m0, s6
	v_readfirstlane_b32 s6, v136
	v_add_u32_e32 v136, 0x8000, v133
	global_load_lds_dwordx4 v[144:145], off
	s_mov_b32 m0, s6
	v_readfirstlane_b32 s6, v136
	v_add_u32_e32 v136, 0xa000, v133
	v_add_u32_e32 v128, 0xc000, v133
	global_load_lds_dwordx4 v[152:153], off
	s_mov_b32 m0, s6
	v_readfirstlane_b32 s6, v136
	global_load_lds_dwordx4 v[138:139], off
	s_mov_b32 m0, s6
	v_readfirstlane_b32 s6, v128
	v_add_u32_e32 v128, 0xe000, v133
	global_load_lds_dwordx4 v[150:151], off
	s_mov_b32 m0, s6
	v_readfirstlane_b32 s6, v128
	v_lshl_add_u64 v[148:149], v[138:139], 0, s[10:11]
	global_load_lds_dwordx4 v[146:147], off
	s_mov_b32 m0, s6
	s_nop 0
	global_load_lds_dwordx4 v[148:149], off
